# strategy 7.5 continued: all 448 packed f32 mul/add/fma of the P1/P2 GEMM epilogues (EpiIn rope/scale, EpiPlain, EpiUq, EpiUkv, side product) split into single ops, hi half first where it reads the low
# speedup vs baseline: 1.0115x; 1.0036x over previous
; __device__ __forceinline__ unsigned cvt_pk_bf16(float lo, float hi) { unsigned r; asm volatile("v_cvt_pk_bf16_f32 %0, %1, %2" : "=v"(r) : "v"(lo), "v"(hi)); return r; }
; __device__ __forceinline__ void rope8(float (&v)[8], const tab_t* tp) {
;     const f32x4 t0 = *(const f32x4*)tp, t1 = *(const f32x4*)(tp + 2);
;     const float c[4] = {t0[0], t0[2], t1[0], t1[2]}, s[4] = {t0[1], t0[3], t1[1], t1[3]};
; #pragma unroll
;     for (int j = 0; j < 4; ++j) { const float a = v[2 * j], b = v[2 * j + 1]; v[2 * j] = a * c[j] - b * s[j]; v[2 * j + 1] = b * c[j] + a * s[j]; }
; }
; __device__ __forceinline__ void store8(bf16_t* p, const float (&v)[8]) {
;     u32x4 w; w.x = cvt_pk_bf16(v[0], v[1]); w.y = cvt_pk_bf16(v[2], v[3]); w.z = cvt_pk_bf16(v[4], v[5]); w.w = cvt_pk_bf16(v[6], v[7]);
;     *(u32x4*)p = w;
; }
; template <int N4> __device__ __forceinline__ float sum_parts(const float* p) {
;     f32x4 a = *(const f32x4*)p;
; #pragma unroll
;     for (int i = 1; i < N4; ++i) a += *(const f32x4*)(p + 4 * i);
;     return (a[0] + a[1]) + (a[2] + a[3]);
;     __device__ __forceinline__ void operator()(const f32x4 (&acc)[2][2][4][2], const Unit& u, int wr, int wc, int fr, int fq) const {
;     ...
;         for (int ai = 0; ai < 2; ++ai)
; #pragma unroll
;             for (int m = 0; m < 4; ++m) {
;                 const int row = row0 + ai * HALF + m * 16;
;                 const float r = __builtin_amdgcn_rsqf(sum_parts<8>(ssq_h + (size_t)row * 32) * (1.0f / 2048.0f) + 1e-6f);
; #pragma unroll
;                 for (int bj = 0; bj < 2; ++bj) {
;                     float v[8];
; #pragma unroll
;                     for (int e = 0; e < 4; ++e) { v[e] = acc[ai][bj][m][0][e] * r; v[4 + e] = acc[ai][bj][m][1][e] * r; }
;                     if (tab[bj] >= 0) rope8(v, TAB + (size_t)row * NTAB + tab[bj]);
.LBB0_343:
	s_ashr_i32 s1, s1, 2
	s_andn2_b32 s1, s1, 63
	v_lshrrev_b32_e32 v198, 4, v146
	v_and_or_b32 v146, v146, 15, s1
	v_lshl_add_u32 v146, s87, 8, v146
	v_ashrrev_i32_e32 v147, 31, v146
	v_lshlrev_b32_e32 v198, 5, v198
	v_mov_b32_e32 v199, 0
	v_lshlrev_b64 v[190:191], 7, v[146:147]
	v_lshl_add_u64 v[190:191], s[22:23], 0, v[190:191]
	v_lshl_add_u64 v[190:191], v[190:191], 0, v[198:199]
	v_mov_b32_e32 v160, 0x1000
	v_mov_b32_e32 v161, 0
	v_lshl_add_u64 v[192:193], v[160:161], 0, v[190:191]
	v_lshl_add_u64 v[194:195], v[160:161], 2, v[190:191]
	v_lshl_add_u64 v[196:197], v[160:161], 0, v[194:195]
	global_load_dwordx4 v[218:221], v[190:191], off
	global_load_dwordx4 v[222:225], v[190:191], off offset:16
	global_load_dwordx4 v[226:229], v[190:191], off offset:2048
	global_load_dwordx4 v[230:233], v[190:191], off offset:2064
	global_load_dwordx4 v[234:237], v[192:193], off
	global_load_dwordx4 v[238:241], v[192:193], off offset:16
	global_load_dwordx4 v[178:181], v[192:193], off offset:2048
	global_load_dwordx4 v[182:185], v[192:193], off offset:2064
	global_load_dwordx4 v[186:189], v[194:195], off
	global_load_dwordx4 v[154:157], v[194:195], off offset:16
	global_load_dwordx4 v[160:163], v[194:195], off offset:2048
	global_load_dwordx4 v[164:167], v[194:195], off offset:2064
	global_load_dwordx4 v[242:245], v[196:197], off
	global_load_dwordx4 v[246:249], v[196:197], off offset:16
	global_load_dwordx4 v[250:253], v[196:197], off offset:2048
	global_load_dwordx4 v[206:209], v[196:197], off offset:2064
	s_waitcnt vmcnt(0)
	v_add_f32_e32 v218, v218, v220
	v_add_f32_e32 v219, v219, v221
	v_add_f32_e32 v222, v222, v224
	v_add_f32_e32 v223, v223, v225
	v_add_f32_e32 v218, v218, v222
	v_add_f32_e32 v219, v219, v223
	v_add_f32_e32 v168, v218, v219
	v_add_f32_e32 v226, v226, v228
	v_add_f32_e32 v227, v227, v229
	v_add_f32_e32 v230, v230, v232
	v_add_f32_e32 v231, v231, v233
	v_add_f32_e32 v226, v226, v230
	v_add_f32_e32 v227, v227, v231
	v_add_f32_e32 v169, v226, v227
	v_add_f32_e32 v234, v234, v236
	v_add_f32_e32 v235, v235, v237
	v_add_f32_e32 v238, v238, v240
	v_add_f32_e32 v239, v239, v241
	v_add_f32_e32 v234, v234, v238
	v_add_f32_e32 v235, v235, v239
	v_add_f32_e32 v170, v234, v235
	v_add_f32_e32 v178, v178, v180
	v_add_f32_e32 v179, v179, v181
	v_add_f32_e32 v182, v182, v184
	v_add_f32_e32 v183, v183, v185
	v_add_f32_e32 v178, v178, v182
	v_add_f32_e32 v179, v179, v183
	v_add_f32_e32 v171, v178, v179
	v_add_f32_e32 v186, v186, v188
	v_add_f32_e32 v187, v187, v189
	v_add_f32_e32 v154, v154, v156
	v_add_f32_e32 v155, v155, v157
	v_add_f32_e32 v186, v186, v154
	v_add_f32_e32 v187, v187, v155
	v_add_f32_e32 v172, v186, v187
	v_add_f32_e32 v160, v160, v162
	v_add_f32_e32 v161, v161, v163
	v_add_f32_e32 v164, v164, v166
	v_add_f32_e32 v165, v165, v167
	v_add_f32_e32 v160, v160, v164
	v_add_f32_e32 v161, v161, v165
	v_add_f32_e32 v173, v160, v161
	v_add_f32_e32 v242, v242, v244
	v_add_f32_e32 v243, v243, v245
	v_add_f32_e32 v246, v246, v248
	v_add_f32_e32 v247, v247, v249
	v_add_f32_e32 v242, v242, v246
	v_add_f32_e32 v243, v243, v247
	v_add_f32_e32 v174, v242, v243
	v_add_f32_e32 v250, v250, v252
	v_add_f32_e32 v251, v251, v253
	v_add_f32_e32 v206, v206, v208
	v_add_f32_e32 v207, v207, v209
	v_add_f32_e32 v250, v250, v206
	v_add_f32_e32 v251, v251, v207
	v_add_f32_e32 v175, v250, v251
	v_mov_b32_e32 v234, v168
	v_mov_b32_e32 v235, v169
	v_mov_b32_e32 v236, v170
	v_mov_b32_e32 v237, v171
	v_mov_b32_e32 v238, v172
	v_mov_b32_e32 v239, v173
	v_mov_b32_e32 v240, v174
	v_mov_b32_e32 v241, v175
	v_permlane32_swap_b32_e32 v168, v234
	v_permlane32_swap_b32_e32 v169, v235
	v_permlane32_swap_b32_e32 v170, v236
	v_permlane32_swap_b32_e32 v171, v237
	v_permlane32_swap_b32_e32 v172, v238
	v_permlane32_swap_b32_e32 v173, v239
	v_permlane32_swap_b32_e32 v174, v240
	v_permlane32_swap_b32_e32 v175, v241
	v_add_f32_e32 v168, v168, v234
	v_add_f32_e32 v169, v169, v235
	v_add_f32_e32 v170, v170, v236
	v_add_f32_e32 v171, v171, v237
	v_add_f32_e32 v172, v172, v238
	v_add_f32_e32 v173, v173, v239
	v_add_f32_e32 v174, v174, v240
	v_add_f32_e32 v175, v175, v241
	v_mov_b32_e32 v234, v168
	v_mov_b32_e32 v235, v169
	v_mov_b32_e32 v236, v170
	v_mov_b32_e32 v237, v171
	v_mov_b32_e32 v238, v172
	v_mov_b32_e32 v239, v173
	v_mov_b32_e32 v240, v174
	v_mov_b32_e32 v241, v175
	v_permlane16_swap_b32_e32 v168, v234
	v_permlane16_swap_b32_e32 v169, v235
	v_permlane16_swap_b32_e32 v170, v236
	v_permlane16_swap_b32_e32 v171, v237
	v_permlane16_swap_b32_e32 v172, v238
	v_permlane16_swap_b32_e32 v173, v239
	v_permlane16_swap_b32_e32 v174, v240
	v_permlane16_swap_b32_e32 v175, v241
	v_add_f32_e32 v168, v168, v234
	v_add_f32_e32 v169, v169, v235
	v_add_f32_e32 v170, v170, v236
	v_add_f32_e32 v171, v171, v237
	v_add_f32_e32 v172, v172, v238
	v_add_f32_e32 v173, v173, v239
	v_add_f32_e32 v174, v174, v240
	v_add_f32_e32 v175, v175, v241
	v_fmamk_f32 v168, v168, 0x3a000000, v204
	v_fmamk_f32 v169, v169, 0x3a000000, v204
	v_fmamk_f32 v170, v170, 0x3a000000, v204
	v_fmamk_f32 v171, v171, 0x3a000000, v204
	v_fmamk_f32 v172, v172, 0x3a000000, v204
	v_fmamk_f32 v173, v173, 0x3a000000, v204
	v_fmamk_f32 v174, v174, 0x3a000000, v204
	v_fmamk_f32 v175, v175, 0x3a000000, v204
	v_rsq_f32_e32 v168, v168
	v_rsq_f32_e32 v169, v169
	v_rsq_f32_e32 v170, v170
	v_rsq_f32_e32 v171, v171
	v_rsq_f32_e32 v172, v172
	v_rsq_f32_e32 v173, v173
	v_rsq_f32_e32 v174, v174
	v_rsq_f32_e32 v175, v175
	s_movk_i32 s1, 0x1c0
	v_mad_i64_i32 v[156:157], s[6:7], v146, s1, 0
	v_mov_b32_e32 v154, v168
	v_cmp_lt_i32_e64 s[6:7], -1, v0
	v_lshl_add_u64 v[156:157], s[70:71], 0, v[156:157]
	v_mul_f32_e32 v2, v2, v154
	v_mul_f32_e32 v3, v3, v154
	v_mul_f32_e32 v6, v6, v154
	v_mul_f32_e32 v7, v7, v154
	v_mul_f32_e32 v4, v4, v154
	v_mul_f32_e32 v5, v5, v154
	v_mul_f32_e32 v8, v8, v154
	v_mul_f32_e32 v9, v9, v154
	s_and_saveexec_b64 s[8:9], s[6:7]
	s_cbranch_execz .LBB0_345
	v_lshl_add_u64 v[160:161], v[0:1], 3, v[156:157]
	global_load_dwordx4 v[184:187], v[160:161], off offset:16
	global_load_dwordx4 v[180:183], v[160:161], off
	s_waitcnt vmcnt(0)
	v_mul_f32_e32 v160, v3, v181
	v_mul_f32_e32 v161, v3, v180
	s_nop 0
	v_fma_f32 v178, v2, v180, -v160
	v_fma_f32 v179, v2, v181, -v161
	v_fma_f32 v3, v2, v181, v161
	v_fma_f32 v2, v2, v180, v160
	v_mul_f32_e32 v160, v5, v183
	v_mul_f32_e32 v161, v5, v182
	v_mul_f32_e32 v2, v9, v187
	v_fma_f32 v180, v4, v182, -v160
	v_fma_f32 v181, v4, v183, -v161
	v_fma_f32 v5, v4, v183, v161
	v_fma_f32 v4, v4, v182, v160
	v_mul_f32_e32 v160, v7, v185
	v_mul_f32_e32 v161, v7, v184
	v_mov_b32_e32 v179, v3
	v_fma_f32 v182, v6, v184, -v160
	v_fma_f32 v183, v6, v185, -v161
	v_fma_f32 v7, v6, v185, v161
	v_fma_f32 v6, v6, v184, v160
	v_fma_f32 v184, v8, v186, -v2
	v_fma_f32 v185, v9, v187, -v2
	v_mul_f32_e32 v2, v9, v186
	v_fma_f32 v8, v8, v187, v2
	v_fma_f32 v9, v9, v186, v2
	v_mov_b32_e32 v181, v5
	v_mov_b32_e32 v183, v7
	v_mov_b32_e32 v185, v8
	v_mov_b64_e32 v[2:3], v[178:179]
	v_mov_b64_e32 v[4:5], v[180:181]
	v_mov_b64_e32 v[6:7], v[182:183]
	v_mov_b64_e32 v[8:9], v[184:185]
; __device__ __forceinline__ float silu_f(float x) { return x * __builtin_amdgcn_rcpf(1.0f + __builtin_amdgcn_exp2f(-x * 1.4426950408889634f)); }
;     __device__ __forceinline__ void operator()(const f32x4 (&acc)[2][2][4][2], const Unit& u, int wr, int wc, int fr, int fq) const {
;     ...
;                     if (act[bj]) {
; #pragma unroll
;                         for (int e = 0; e < 8; ++e) v[e] = silu_f(v[e]);
;                     }
.LBB0_345:
	s_or_b64 exec, exec, s[8:9]
	v_cndmask_b32_e64 v149, 0, 1, s[4:5]
	v_cmp_ne_u32_e64 s[8:9], 1, v149
	s_andn2_b64 vcc, exec, s[4:5]
	s_cbranch_vccnz .LBB0_347
	v_mul_f32_e32 v149, 0xbfb8aa3b, v2
	v_exp_f32_e32 v149, v149
	v_mul_f32_e32 v155, 0xbfb8aa3b, v5
	v_mul_f32_e32 v161, 0xbfb8aa3b, v6
	v_exp_f32_e32 v155, v155
	v_add_f32_e32 v149, 1.0, v149
	v_rcp_f32_e32 v160, v149
	v_mul_f32_e32 v149, 0xbfb8aa3b, v4
	v_exp_f32_e32 v149, v149
	v_exp_f32_e32 v161, v161
	v_mul_f32_e32 v151, 0xbfb8aa3b, v3
	v_mul_f32_e32 v163, 0xbfb8aa3b, v9
	v_add_f32_e32 v149, 1.0, v149
	v_rcp_f32_e32 v162, v149
	v_add_f32_e32 v149, 1.0, v155
	v_add_f32_e32 v155, 1.0, v161
	v_mul_f32_e32 v161, 0xbfb8aa3b, v8
	v_rcp_f32_e32 v164, v155
	v_mul_f32_e32 v155, 0xbfb8aa3b, v7
	v_exp_f32_e32 v161, v161
	v_exp_f32_e32 v151, v151
	v_exp_f32_e32 v155, v155
	v_exp_f32_e32 v163, v163
	v_add_f32_e32 v161, 1.0, v161
	v_add_f32_e32 v151, 1.0, v151
	v_add_f32_e32 v155, 1.0, v155
	v_rcp_f32_e32 v166, v161
	v_add_f32_e32 v161, 1.0, v163
	v_rcp_f32_e32 v167, v161
	v_rcp_f32_e32 v165, v155
	v_rcp_f32_e32 v163, v149
	v_rcp_f32_e32 v161, v151
	v_mul_f32_e32 v8, v8, v166
	v_mul_f32_e32 v9, v9, v167
	v_mul_f32_e32 v6, v6, v164
	v_mul_f32_e32 v7, v7, v165
	v_mul_f32_e32 v4, v4, v162
	v_mul_f32_e32 v5, v5, v163
	v_mul_f32_e32 v2, v2, v160
	v_mul_f32_e32 v3, v3, v161

; __device__ __forceinline__ float silu_f(float x) { return x * __builtin_amdgcn_rcpf(1.0f + __builtin_amdgcn_exp2f(-x * 1.4426950408889634f)); }
; __device__ __forceinline__ void rope8(float (&v)[8], const tab_t* tp) {
;     const f32x4 t0 = *(const f32x4*)tp, t1 = *(const f32x4*)(tp + 2);
;     const float c[4] = {t0[0], t0[2], t1[0], t1[2]}, s[4] = {t0[1], t0[3], t1[1], t1[3]};
; #pragma unroll
;     for (int j = 0; j < 4; ++j) { const float a = v[2 * j], b = v[2 * j + 1]; v[2 * j] = a * c[j] - b * s[j]; v[2 * j + 1] = b * c[j] + a * s[j]; }
; }
;     __device__ __forceinline__ void operator()(const f32x4 (&acc)[2][2][4][2], const Unit& u, int wr, int wc, int fr, int fq) const {
;     ...
;                 const int row = row0 + ai * HALF + m * 16;
;                 const float r = __builtin_amdgcn_rsqf(sum_parts<8>(ssq_h + (size_t)row * 32) * (1.0f / 2048.0f) + 1e-6f);
; #pragma unroll
;                 for (int bj = 0; bj < 2; ++bj) {
;                     float v[8];
; #pragma unroll
;                     for (int e = 0; e < 4; ++e) { v[e] = acc[ai][bj][m][0][e] * r; v[4 + e] = acc[ai][bj][m][1][e] * r; }
;                     if (tab[bj] >= 0) rope8(v, TAB + (size_t)row * NTAB + tab[bj]);
;                     if (act[bj]) {
; #pragma unroll
;                         for (int e = 0; e < 8; ++e) v[e] = silu_f(v[e]);
;                     }
; #pragma unroll
;                     for (int e = 0; e < 8; ++e) v[e] *= sc[bj];
;                     if (ssq[bj]) { float s = 0.f;
; #pragma unroll
;                         for (int e = 0; e < 8; ++e) s += v[e] * v[e];
;                         s += __shfl_xor(s, 16); s += __shfl_xor(s, 32);
;                         if (fq == 0) ssq[bj][(size_t)row * sld[bj]] = s; }
;                     store8(dst[bj] + (size_t)row * ld[bj], v);
;                     asm volatile("" ::: "memory");
;                 }
.LBB0_351:
	v_ashrrev_i32_e32 v149, 31, v148
	v_lshl_add_u64 v[148:149], v[148:149], 1, s[10:11]
	v_mul_lo_u32 v7, s91, v146
	v_mul_lo_u32 v160, s90, v147
	s_waitcnt lgkmcnt(0)
	v_mad_u64_u32 v[8:9], s[10:11], s90, v146, 0
	v_add3_u32 v9, v9, v160, v7
	v_lshl_add_u64 v[8:9], v[8:9], 1, v[148:149]
	v_cvt_pk_bf16_f32 v178, v145, v178
	v_cvt_pk_bf16_f32 v179, v4, v151
	v_cvt_pk_bf16_f32 v180, v3, v5
	v_cvt_pk_bf16_f32 v181, v2, v6
	global_store_dwordx4 v[8:9], v[178:181], off
	v_mov_b32_e32 v155, v154
	v_mul_f32_e32 v2, v126, v154
	v_mul_f32_e32 v3, v127, v155
	v_mul_f32_e32 v6, v122, v154
	v_mul_f32_e32 v7, v123, v155
	v_mul_f32_e32 v4, v128, v154
	v_mul_f32_e32 v5, v129, v155
	v_mul_f32_e32 v8, v124, v154
	v_mul_f32_e32 v9, v125, v155
	v_cmp_lt_i32_e64 s[10:11], -1, v144
	s_and_saveexec_b64 s[14:15], s[10:11]
	s_cbranch_execz .LBB0_353
	v_mov_b32_e32 v145, v1
	v_lshl_add_u64 v[122:123], v[144:145], 3, v[156:157]
	global_load_dwordx4 v[154:157], v[122:123], off offset:16
	global_load_dwordx4 v[124:127], v[122:123], off
	s_waitcnt vmcnt(0)
	v_mul_f32_e32 v128, v3, v125
	v_mul_f32_e32 v129, v3, v124
	s_nop 0
	v_fma_f32 v122, v2, v124, -v128
	v_fma_f32 v123, v2, v125, -v129
	v_fma_f32 v3, v2, v125, v129
	v_fma_f32 v2, v2, v124, v128
	v_mul_f32_e32 v128, v5, v127
	v_mul_f32_e32 v129, v5, v126
	v_mul_f32_e32 v2, v9, v157
	v_fma_f32 v124, v4, v126, -v128
	v_fma_f32 v125, v4, v127, -v129
	v_fma_f32 v5, v4, v127, v129
	v_fma_f32 v4, v4, v126, v128
	v_mul_f32_e32 v128, v7, v155
	v_mul_f32_e32 v129, v7, v154
	v_mov_b32_e32 v123, v3
	v_fma_f32 v126, v6, v154, -v128
	v_fma_f32 v127, v6, v155, -v129
	v_fma_f32 v7, v6, v155, v129
	v_fma_f32 v6, v6, v154, v128
	v_fma_f32 v128, v8, v156, -v2
	v_fma_f32 v129, v9, v157, -v2
	v_mul_f32_e32 v2, v9, v156
	v_fma_f32 v8, v8, v157, v2
	v_fma_f32 v9, v9, v156, v2
	v_mov_b32_e32 v125, v5
	v_mov_b32_e32 v127, v7
	v_mov_b32_e32 v129, v8
	v_mov_b64_e32 v[2:3], v[122:123]
	v_mov_b64_e32 v[4:5], v[124:125]
	v_mov_b64_e32 v[6:7], v[126:127]
	v_mov_b64_e32 v[8:9], v[128:129]
.LBB0_353:
	s_or_b64 exec, exec, s[14:15]
	s_xor_b64 s[14:15], s[12:13], -1
	v_cndmask_b32_e64 v122, 0, 1, s[14:15]
	v_cmp_ne_u32_e64 s[12:13], 1, v122
	s_andn2_b64 vcc, exec, s[14:15]
	s_cbranch_vccnz .LBB0_355
	v_mul_f32_e32 v122, 0xbfb8aa3b, v2
	v_mul_f32_e32 v123, 0xbfb8aa3b, v3
	v_mul_f32_e32 v124, 0xbfb8aa3b, v4
	v_mul_f32_e32 v125, 0xbfb8aa3b, v5
	v_mul_f32_e32 v126, 0xbfb8aa3b, v6
	v_mul_f32_e32 v127, 0xbfb8aa3b, v7
	v_mul_f32_e32 v128, 0xbfb8aa3b, v8
	v_mul_f32_e32 v129, 0xbfb8aa3b, v9
	v_exp_f32_e32 v122, v122
	v_exp_f32_e32 v123, v123
	v_exp_f32_e32 v124, v124
	v_exp_f32_e32 v125, v125
	v_exp_f32_e32 v126, v126
	v_exp_f32_e32 v127, v127
	v_exp_f32_e32 v128, v128
	v_exp_f32_e32 v129, v129
	v_add_f32_e32 v122, 1.0, v122
	v_add_f32_e32 v123, 1.0, v123
	v_add_f32_e32 v124, 1.0, v124
	v_add_f32_e32 v125, 1.0, v125
	v_add_f32_e32 v126, 1.0, v126
	v_add_f32_e32 v127, 1.0, v127
	v_add_f32_e32 v128, 1.0, v128
	v_add_f32_e32 v129, 1.0, v129
	v_rcp_f32_e32 v122, v122
	v_rcp_f32_e32 v124, v124
	v_rcp_f32_e32 v126, v126
	v_rcp_f32_e32 v128, v128
	v_rcp_f32_e32 v129, v129
	v_rcp_f32_e32 v127, v127
	v_rcp_f32_e32 v125, v125
	v_rcp_f32_e32 v123, v123
	v_mul_f32_e32 v8, v8, v128
	v_mul_f32_e32 v9, v9, v129
	v_mul_f32_e32 v6, v6, v126
	v_mul_f32_e32 v7, v7, v127
	v_mul_f32_e32 v4, v4, v124
	v_mul_f32_e32 v5, v5, v125
	v_mul_f32_e32 v2, v2, v122
	v_mul_f32_e32 v3, v3, v123

; __device__ __forceinline__ float silu_f(float x) { return x * __builtin_amdgcn_rcpf(1.0f + __builtin_amdgcn_exp2f(-x * 1.4426950408889634f)); }
; __device__ __forceinline__ void rope8(float (&v)[8], const tab_t* tp) {
;     const f32x4 t0 = *(const f32x4*)tp, t1 = *(const f32x4*)(tp + 2);
;     const float c[4] = {t0[0], t0[2], t1[0], t1[2]}, s[4] = {t0[1], t0[3], t1[1], t1[3]};
; #pragma unroll
;     for (int j = 0; j < 4; ++j) { const float a = v[2 * j], b = v[2 * j + 1]; v[2 * j] = a * c[j] - b * s[j]; v[2 * j + 1] = b * c[j] + a * s[j]; }
; }
;     __device__ __forceinline__ void operator()(const f32x4 (&acc)[2][2][4][2], const Unit& u, int wr, int wc, int fr, int fq) const {
;     ...
;                 const int row = row0 + ai * HALF + m * 16;
;                 const float r = __builtin_amdgcn_rsqf(sum_parts<8>(ssq_h + (size_t)row * 32) * (1.0f / 2048.0f) + 1e-6f);
; #pragma unroll
;                 for (int bj = 0; bj < 2; ++bj) {
;                     float v[8];
; #pragma unroll
;                     for (int e = 0; e < 4; ++e) { v[e] = acc[ai][bj][m][0][e] * r; v[4 + e] = acc[ai][bj][m][1][e] * r; }
;                     if (tab[bj] >= 0) rope8(v, TAB + (size_t)row * NTAB + tab[bj]);
;                     if (act[bj]) {
; #pragma unroll
;                         for (int e = 0; e < 8; ++e) v[e] = silu_f(v[e]);
;                     }
; #pragma unroll
;                     for (int e = 0; e < 8; ++e) v[e] *= sc[bj];
;                     if (ssq[bj]) { float s = 0.f;
; #pragma unroll
;                         for (int e = 0; e < 8; ++e) s += v[e] * v[e];
;                         s += __shfl_xor(s, 16); s += __shfl_xor(s, 32);
;                         if (fq == 0) ssq[bj][(size_t)row * sld[bj]] = s; }
;                     store8(dst[bj] + (size_t)row * ld[bj], v);
;                     asm volatile("" ::: "memory");
;                 }
.LBB0_359:
	v_ashrrev_i32_e32 v151, 31, v150
	v_mul_lo_u32 v8, s93, v146
	v_mul_lo_u32 v9, s92, v147
	s_waitcnt lgkmcnt(0)
	v_mad_u64_u32 v[6:7], s[14:15], s92, v146, 0
	v_lshl_add_u64 v[122:123], v[150:151], 1, v[152:153]
	v_add3_u32 v7, v7, v9, v8
	v_lshl_add_u64 v[128:129], v[6:7], 1, v[122:123]
	v_cvt_pk_bf16_f32 v6, v125, v127
	v_cvt_pk_bf16_f32 v7, v124, v126
	v_or_b32_e32 v124, 16, v146
	v_ashrrev_i32_e32 v125, 31, v124
	v_cvt_pk_bf16_f32 v8, v3, v5
	v_cvt_pk_bf16_f32 v9, v2, v4
	global_store_dwordx4 v[128:129], v[6:9], off
	v_mad_i64_i32 v[128:129], s[14:15], v124, s1, 0
	v_mov_b32_e32 v126, v169
	s_nop 0
	v_mul_f32_e32 v2, v118, v126
	v_mul_f32_e32 v3, v119, v126
	v_mul_f32_e32 v6, v114, v126
	v_mul_f32_e32 v7, v115, v126
	v_mul_f32_e32 v4, v120, v126
	v_mul_f32_e32 v5, v121, v126
	v_mul_f32_e32 v8, v116, v126
	v_mul_f32_e32 v9, v117, v126
	v_lshl_add_u64 v[114:115], s[70:71], 0, v[128:129]
	s_and_saveexec_b64 s[14:15], s[6:7]
	s_cbranch_execz .LBB0_361
	v_lshl_add_u64 v[120:121], v[0:1], 3, v[114:115]
	global_load_dwordx4 v[116:119], v[120:121], off offset:16
	global_load_dwordx4 v[152:155], v[120:121], off
	s_waitcnt vmcnt(0)
	v_mul_f32_e32 v120, v3, v153
	v_mul_f32_e32 v121, v3, v152
	s_nop 0
	v_fma_f32 v150, v2, v152, -v120
	v_fma_f32 v151, v2, v153, -v121
	v_fma_f32 v3, v2, v153, v121
	v_fma_f32 v2, v2, v152, v120
	v_mul_f32_e32 v120, v5, v155
	v_mul_f32_e32 v121, v5, v154
	v_mul_f32_e32 v2, v9, v119
	v_fma_f32 v152, v4, v154, -v120
	v_fma_f32 v153, v4, v155, -v121
	v_fma_f32 v5, v4, v155, v121
	v_fma_f32 v4, v4, v154, v120
	v_mul_f32_e32 v120, v7, v117
	v_mul_f32_e32 v121, v7, v116
	v_fma_f32 v156, v8, v118, -v2
	v_fma_f32 v157, v9, v119, -v2
	v_mul_f32_e32 v2, v9, v118
	v_fma_f32 v154, v6, v116, -v120
	v_fma_f32 v155, v6, v117, -v121
	v_fma_f32 v7, v6, v117, v121
	v_fma_f32 v6, v6, v116, v120
	v_fma_f32 v8, v8, v119, v2
	v_fma_f32 v9, v9, v118, v2
	v_mov_b32_e32 v151, v3
	v_mov_b32_e32 v153, v5
	v_mov_b32_e32 v155, v7
	v_mov_b32_e32 v157, v8
	v_mov_b64_e32 v[2:3], v[150:151]
	v_mov_b64_e32 v[4:5], v[152:153]
	v_mov_b64_e32 v[6:7], v[154:155]
	v_mov_b64_e32 v[8:9], v[156:157]
.LBB0_361:
	s_or_b64 exec, exec, s[14:15]
	s_and_b64 vcc, exec, s[8:9]
	s_cbranch_vccnz .LBB0_363
	v_mul_f32_e32 v127, 0xbfb8aa3b, v8
	v_mul_f32_e32 v116, 0xbfb8aa3b, v2
	v_mul_f32_e32 v117, 0xbfb8aa3b, v3
	v_mul_f32_e32 v118, 0xbfb8aa3b, v4
	v_mul_f32_e32 v119, 0xbfb8aa3b, v5
	v_mul_f32_e32 v120, 0xbfb8aa3b, v6
	v_mul_f32_e32 v121, 0xbfb8aa3b, v7
	v_exp_f32_e32 v127, v127
	v_mul_f32_e32 v128, 0xbfb8aa3b, v9
	v_exp_f32_e32 v116, v116
	v_exp_f32_e32 v117, v117
	v_exp_f32_e32 v118, v118
	v_exp_f32_e32 v119, v119
	v_exp_f32_e32 v120, v120
	v_exp_f32_e32 v121, v121
	v_exp_f32_e32 v129, v128
	v_add_f32_e32 v127, 1.0, v127
	v_add_f32_e32 v116, 1.0, v116
	v_add_f32_e32 v117, 1.0, v117
	v_add_f32_e32 v118, 1.0, v118
	v_add_f32_e32 v119, 1.0, v119
	v_add_f32_e32 v120, 1.0, v120
	v_add_f32_e32 v121, 1.0, v121
	v_rcp_f32_e32 v128, v127
	v_add_f32_e32 v127, 1.0, v129
	v_rcp_f32_e32 v116, v116
	v_rcp_f32_e32 v118, v118
	v_rcp_f32_e32 v120, v120
	v_rcp_f32_e32 v129, v127
	v_rcp_f32_e32 v121, v121
	v_rcp_f32_e32 v119, v119
	v_rcp_f32_e32 v117, v117
	v_mul_f32_e32 v8, v8, v128
	v_mul_f32_e32 v9, v9, v129
	v_mul_f32_e32 v6, v6, v120
	v_mul_f32_e32 v7, v7, v121
	v_mul_f32_e32 v4, v4, v118
	v_mul_f32_e32 v5, v5, v119
	v_mul_f32_e32 v2, v2, v116
	v_mul_f32_e32 v3, v3, v117

; __device__ __forceinline__ float silu_f(float x) { return x * __builtin_amdgcn_rcpf(1.0f + __builtin_amdgcn_exp2f(-x * 1.4426950408889634f)); }
; __device__ __forceinline__ void rope8(float (&v)[8], const tab_t* tp) {
;     const f32x4 t0 = *(const f32x4*)tp, t1 = *(const f32x4*)(tp + 2);
;     const float c[4] = {t0[0], t0[2], t1[0], t1[2]}, s[4] = {t0[1], t0[3], t1[1], t1[3]};
; #pragma unroll
;     for (int j = 0; j < 4; ++j) { const float a = v[2 * j], b = v[2 * j + 1]; v[2 * j] = a * c[j] - b * s[j]; v[2 * j + 1] = b * c[j] + a * s[j]; }
; }
;     __device__ __forceinline__ void operator()(const f32x4 (&acc)[2][2][4][2], const Unit& u, int wr, int wc, int fr, int fq) const {
;     ...
;                 const int row = row0 + ai * HALF + m * 16;
;                 const float r = __builtin_amdgcn_rsqf(sum_parts<8>(ssq_h + (size_t)row * 32) * (1.0f / 2048.0f) + 1e-6f);
; #pragma unroll
;                 for (int bj = 0; bj < 2; ++bj) {
;                     float v[8];
; #pragma unroll
;                     for (int e = 0; e < 4; ++e) { v[e] = acc[ai][bj][m][0][e] * r; v[4 + e] = acc[ai][bj][m][1][e] * r; }
;                     if (tab[bj] >= 0) rope8(v, TAB + (size_t)row * NTAB + tab[bj]);
;                     if (act[bj]) {
; #pragma unroll
;                         for (int e = 0; e < 8; ++e) v[e] = silu_f(v[e]);
;                     }
; #pragma unroll
;                     for (int e = 0; e < 8; ++e) v[e] *= sc[bj];
;                     if (ssq[bj]) { float s = 0.f;
; #pragma unroll
;                         for (int e = 0; e < 8; ++e) s += v[e] * v[e];
;                         s += __shfl_xor(s, 16); s += __shfl_xor(s, 32);
;                         if (fq == 0) ssq[bj][(size_t)row * sld[bj]] = s; }
;                     store8(dst[bj] + (size_t)row * ld[bj], v);
;                     asm volatile("" ::: "memory");
;                 }
.LBB0_367:
	v_mul_lo_u32 v7, s91, v124
	v_mul_lo_u32 v119, s90, v125
	s_waitcnt lgkmcnt(0)
	v_mad_u64_u32 v[8:9], s[16:17], s90, v124, 0
	v_add3_u32 v9, v9, v119, v7
	v_lshl_add_u64 v[8:9], v[8:9], 1, v[148:149]
	v_cvt_pk_bf16_f32 v116, v116, v118
	v_cvt_pk_bf16_f32 v117, v4, v117
	v_cvt_pk_bf16_f32 v118, v3, v5
	v_cvt_pk_bf16_f32 v119, v2, v6
	global_store_dwordx4 v[8:9], v[116:119], off
	v_mov_b32_e32 v127, v126
	v_mul_f32_e32 v2, v110, v126
	v_mul_f32_e32 v3, v111, v127
	v_mul_f32_e32 v6, v106, v126
	v_mul_f32_e32 v7, v107, v127
	v_mul_f32_e32 v4, v112, v126
	v_mul_f32_e32 v5, v113, v127
	v_mul_f32_e32 v8, v108, v126
	v_mul_f32_e32 v9, v109, v127
	s_and_saveexec_b64 s[16:17], s[10:11]
	s_cbranch_execz .LBB0_369
	v_mov_b32_e32 v145, v1
	v_lshl_add_u64 v[106:107], v[144:145], 3, v[114:115]
	global_load_dwordx4 v[112:115], v[106:107], off offset:16
	global_load_dwordx4 v[108:111], v[106:107], off
	s_waitcnt vmcnt(0)
	v_mul_f32_e32 v116, v3, v109
	v_mul_f32_e32 v117, v3, v108
	s_nop 0
	v_fma_f32 v106, v2, v108, -v116
	v_fma_f32 v107, v2, v109, -v117
	v_fma_f32 v3, v2, v109, v117
	v_fma_f32 v2, v2, v108, v116
	v_mul_f32_e32 v116, v5, v111
	v_mul_f32_e32 v117, v5, v110
	v_mul_f32_e32 v2, v9, v115
	v_fma_f32 v108, v4, v110, -v116
	v_fma_f32 v109, v4, v111, -v117
	v_fma_f32 v5, v4, v111, v117
	v_fma_f32 v4, v4, v110, v116
	v_mul_f32_e32 v116, v7, v113
	v_mul_f32_e32 v117, v7, v112
	v_mov_b32_e32 v107, v3
	v_fma_f32 v110, v6, v112, -v116
	v_fma_f32 v111, v6, v113, -v117
	v_fma_f32 v7, v6, v113, v117
	v_fma_f32 v6, v6, v112, v116
	v_fma_f32 v112, v8, v114, -v2
	v_fma_f32 v113, v9, v115, -v2
	v_mul_f32_e32 v2, v9, v114
	v_fma_f32 v8, v8, v115, v2
	v_fma_f32 v9, v9, v114, v2
	v_mov_b32_e32 v109, v5
	v_mov_b32_e32 v111, v7
	v_mov_b32_e32 v113, v8
	v_mov_b64_e32 v[2:3], v[106:107]
	v_mov_b64_e32 v[4:5], v[108:109]
	v_mov_b64_e32 v[6:7], v[110:111]
	v_mov_b64_e32 v[8:9], v[112:113]
.LBB0_369:
	s_or_b64 exec, exec, s[16:17]
	s_and_b64 vcc, exec, s[12:13]
	s_cbranch_vccnz .LBB0_371
	v_mul_f32_e32 v106, 0xbfb8aa3b, v2
	v_mul_f32_e32 v107, 0xbfb8aa3b, v3
	v_mul_f32_e32 v108, 0xbfb8aa3b, v4
	v_mul_f32_e32 v109, 0xbfb8aa3b, v5
	v_mul_f32_e32 v110, 0xbfb8aa3b, v6
	v_mul_f32_e32 v111, 0xbfb8aa3b, v7
	v_mul_f32_e32 v112, 0xbfb8aa3b, v8
	v_mul_f32_e32 v113, 0xbfb8aa3b, v9
	v_exp_f32_e32 v106, v106
	v_exp_f32_e32 v107, v107
	v_exp_f32_e32 v108, v108
	v_exp_f32_e32 v109, v109
	v_exp_f32_e32 v110, v110
	v_exp_f32_e32 v111, v111
	v_exp_f32_e32 v112, v112
	v_exp_f32_e32 v113, v113
	v_add_f32_e32 v106, 1.0, v106
	v_add_f32_e32 v107, 1.0, v107
	v_add_f32_e32 v108, 1.0, v108
	v_add_f32_e32 v109, 1.0, v109
	v_add_f32_e32 v110, 1.0, v110
	v_add_f32_e32 v111, 1.0, v111
	v_add_f32_e32 v112, 1.0, v112
	v_add_f32_e32 v113, 1.0, v113
	v_rcp_f32_e32 v106, v106
	v_rcp_f32_e32 v108, v108
	v_rcp_f32_e32 v110, v110
	v_rcp_f32_e32 v112, v112
	v_rcp_f32_e32 v113, v113
	v_rcp_f32_e32 v111, v111
	v_rcp_f32_e32 v109, v109
	v_rcp_f32_e32 v107, v107
	v_mul_f32_e32 v8, v8, v112
	v_mul_f32_e32 v9, v9, v113
	v_mul_f32_e32 v6, v6, v110
	v_mul_f32_e32 v7, v7, v111
	v_mul_f32_e32 v4, v4, v108
	v_mul_f32_e32 v5, v5, v109
	v_mul_f32_e32 v2, v2, v106
	v_mul_f32_e32 v3, v3, v107

; __device__ __forceinline__ float silu_f(float x) { return x * __builtin_amdgcn_rcpf(1.0f + __builtin_amdgcn_exp2f(-x * 1.4426950408889634f)); }
; __device__ __forceinline__ void rope8(float (&v)[8], const tab_t* tp) {
;     const f32x4 t0 = *(const f32x4*)tp, t1 = *(const f32x4*)(tp + 2);
;     const float c[4] = {t0[0], t0[2], t1[0], t1[2]}, s[4] = {t0[1], t0[3], t1[1], t1[3]};
; #pragma unroll
;     for (int j = 0; j < 4; ++j) { const float a = v[2 * j], b = v[2 * j + 1]; v[2 * j] = a * c[j] - b * s[j]; v[2 * j + 1] = b * c[j] + a * s[j]; }
; }
;     __device__ __forceinline__ void operator()(const f32x4 (&acc)[2][2][4][2], const Unit& u, int wr, int wc, int fr, int fq) const {
;     ...
;                 const int row = row0 + ai * HALF + m * 16;
;                 const float r = __builtin_amdgcn_rsqf(sum_parts<8>(ssq_h + (size_t)row * 32) * (1.0f / 2048.0f) + 1e-6f);
; #pragma unroll
;                 for (int bj = 0; bj < 2; ++bj) {
;                     float v[8];
; #pragma unroll
;                     for (int e = 0; e < 4; ++e) { v[e] = acc[ai][bj][m][0][e] * r; v[4 + e] = acc[ai][bj][m][1][e] * r; }
;                     if (tab[bj] >= 0) rope8(v, TAB + (size_t)row * NTAB + tab[bj]);
;                     if (act[bj]) {
; #pragma unroll
;                         for (int e = 0; e < 8; ++e) v[e] = silu_f(v[e]);
;                     }
; #pragma unroll
;                     for (int e = 0; e < 8; ++e) v[e] *= sc[bj];
;                     if (ssq[bj]) { float s = 0.f;
; #pragma unroll
;                         for (int e = 0; e < 8; ++e) s += v[e] * v[e];
;                         s += __shfl_xor(s, 16); s += __shfl_xor(s, 32);
;                         if (fq == 0) ssq[bj][(size_t)row * sld[bj]] = s; }
;                     store8(dst[bj] + (size_t)row * ld[bj], v);
;                     asm volatile("" ::: "memory");
;                 }
.LBB0_375:
	v_mul_lo_u32 v7, s93, v124
	v_mul_lo_u32 v109, s92, v125
	s_waitcnt lgkmcnt(0)
	v_mad_u64_u32 v[8:9], s[18:19], s92, v124, 0
	v_add3_u32 v9, v9, v109, v7
	v_lshl_add_u64 v[8:9], v[8:9], 1, v[122:123]
	v_cvt_pk_bf16_f32 v106, v106, v108
	v_cvt_pk_bf16_f32 v107, v4, v107
	v_cvt_pk_bf16_f32 v108, v3, v5
	v_cvt_pk_bf16_f32 v109, v2, v6
	global_store_dwordx4 v[8:9], v[106:109], off
	s_nop 1
	v_or_b32_e32 v106, 32, v146
	v_ashrrev_i32_e32 v107, 31, v106
	v_mad_i64_i32 v[110:111], s[18:19], v106, s1, 0
	v_mov_b32_e32 v108, v170
	s_nop 0
	v_mul_f32_e32 v2, v102, v108
	v_mul_f32_e32 v3, v103, v108
	v_mul_f32_e32 v6, v98, v108
	v_mul_f32_e32 v7, v99, v108
	v_mul_f32_e32 v4, v104, v108
	v_mul_f32_e32 v5, v105, v108
	v_mul_f32_e32 v8, v100, v108
	v_mul_f32_e32 v9, v101, v108
	v_lshl_add_u64 v[98:99], s[70:71], 0, v[110:111]
	s_and_saveexec_b64 s[18:19], s[6:7]
	s_cbranch_execz .LBB0_377
	v_lshl_add_u64 v[104:105], v[0:1], 3, v[98:99]
	global_load_dwordx4 v[100:103], v[104:105], off offset:16
	global_load_dwordx4 v[112:115], v[104:105], off
	s_waitcnt vmcnt(0)
	v_mul_f32_e32 v104, v3, v113
	v_mul_f32_e32 v105, v3, v112
	s_nop 0
	v_fma_f32 v110, v2, v112, -v104
	v_fma_f32 v111, v2, v113, -v105
	v_fma_f32 v3, v2, v113, v105
	v_fma_f32 v2, v2, v112, v104
	v_mul_f32_e32 v104, v5, v115
	v_mul_f32_e32 v105, v5, v114
	v_mul_f32_e32 v2, v9, v103
	v_fma_f32 v112, v4, v114, -v104
	v_fma_f32 v113, v4, v115, -v105
	v_fma_f32 v5, v4, v115, v105
	v_fma_f32 v4, v4, v114, v104
	v_mul_f32_e32 v104, v7, v101
	v_mul_f32_e32 v105, v7, v100
	v_fma_f32 v116, v8, v102, -v2
	v_fma_f32 v117, v9, v103, -v2
	v_mul_f32_e32 v2, v9, v102
	v_fma_f32 v114, v6, v100, -v104
	v_fma_f32 v115, v6, v101, -v105
	v_fma_f32 v7, v6, v101, v105
	v_fma_f32 v6, v6, v100, v104
	v_fma_f32 v8, v8, v103, v2
	v_fma_f32 v9, v9, v102, v2
	v_mov_b32_e32 v111, v3
	v_mov_b32_e32 v113, v5
	v_mov_b32_e32 v115, v7
	v_mov_b32_e32 v117, v8
	v_mov_b64_e32 v[2:3], v[110:111]
	v_mov_b64_e32 v[4:5], v[112:113]
	v_mov_b64_e32 v[6:7], v[114:115]
	v_mov_b64_e32 v[8:9], v[116:117]
.LBB0_377:
	s_or_b64 exec, exec, s[18:19]
	s_and_b64 vcc, exec, s[8:9]
	s_cbranch_vccnz .LBB0_379
	v_mul_f32_e32 v109, 0xbfb8aa3b, v8
	v_mul_f32_e32 v100, 0xbfb8aa3b, v2
	v_mul_f32_e32 v101, 0xbfb8aa3b, v3
	v_mul_f32_e32 v102, 0xbfb8aa3b, v4
	v_mul_f32_e32 v103, 0xbfb8aa3b, v5
	v_mul_f32_e32 v104, 0xbfb8aa3b, v6
	v_mul_f32_e32 v105, 0xbfb8aa3b, v7
	v_exp_f32_e32 v109, v109
	v_mul_f32_e32 v110, 0xbfb8aa3b, v9
	v_exp_f32_e32 v100, v100
	v_exp_f32_e32 v101, v101
	v_exp_f32_e32 v102, v102
	v_exp_f32_e32 v103, v103
	v_exp_f32_e32 v104, v104
	v_exp_f32_e32 v105, v105
	v_exp_f32_e32 v111, v110
	v_add_f32_e32 v109, 1.0, v109
	v_add_f32_e32 v100, 1.0, v100
	v_add_f32_e32 v101, 1.0, v101
	v_add_f32_e32 v102, 1.0, v102
	v_add_f32_e32 v103, 1.0, v103
	v_add_f32_e32 v104, 1.0, v104
	v_add_f32_e32 v105, 1.0, v105
	v_rcp_f32_e32 v110, v109
	v_add_f32_e32 v109, 1.0, v111
	v_rcp_f32_e32 v100, v100
	v_rcp_f32_e32 v102, v102
	v_rcp_f32_e32 v104, v104
	v_rcp_f32_e32 v111, v109
	v_rcp_f32_e32 v105, v105
	v_rcp_f32_e32 v103, v103
	v_rcp_f32_e32 v101, v101
	v_mul_f32_e32 v8, v8, v110
	v_mul_f32_e32 v9, v9, v111
	v_mul_f32_e32 v6, v6, v104
	v_mul_f32_e32 v7, v7, v105
	v_mul_f32_e32 v4, v4, v102
	v_mul_f32_e32 v5, v5, v103
	v_mul_f32_e32 v2, v2, v100
	v_mul_f32_e32 v3, v3, v101

; __device__ __forceinline__ float silu_f(float x) { return x * __builtin_amdgcn_rcpf(1.0f + __builtin_amdgcn_exp2f(-x * 1.4426950408889634f)); }
; __device__ __forceinline__ void rope8(float (&v)[8], const tab_t* tp) {
;     const f32x4 t0 = *(const f32x4*)tp, t1 = *(const f32x4*)(tp + 2);
;     const float c[4] = {t0[0], t0[2], t1[0], t1[2]}, s[4] = {t0[1], t0[3], t1[1], t1[3]};
; #pragma unroll
;     for (int j = 0; j < 4; ++j) { const float a = v[2 * j], b = v[2 * j + 1]; v[2 * j] = a * c[j] - b * s[j]; v[2 * j + 1] = b * c[j] + a * s[j]; }
; }
;     __device__ __forceinline__ void operator()(const f32x4 (&acc)[2][2][4][2], const Unit& u, int wr, int wc, int fr, int fq) const {
;     ...
;                 const int row = row0 + ai * HALF + m * 16;
;                 const float r = __builtin_amdgcn_rsqf(sum_parts<8>(ssq_h + (size_t)row * 32) * (1.0f / 2048.0f) + 1e-6f);
; #pragma unroll
;                 for (int bj = 0; bj < 2; ++bj) {
;                     float v[8];
; #pragma unroll
;                     for (int e = 0; e < 4; ++e) { v[e] = acc[ai][bj][m][0][e] * r; v[4 + e] = acc[ai][bj][m][1][e] * r; }
;                     if (tab[bj] >= 0) rope8(v, TAB + (size_t)row * NTAB + tab[bj]);
;                     if (act[bj]) {
; #pragma unroll
;                         for (int e = 0; e < 8; ++e) v[e] = silu_f(v[e]);
;                     }
; #pragma unroll
;                     for (int e = 0; e < 8; ++e) v[e] *= sc[bj];
;                     if (ssq[bj]) { float s = 0.f;
; #pragma unroll
;                         for (int e = 0; e < 8; ++e) s += v[e] * v[e];
;                         s += __shfl_xor(s, 16); s += __shfl_xor(s, 32);
;                         if (fq == 0) ssq[bj][(size_t)row * sld[bj]] = s; }
;                     store8(dst[bj] + (size_t)row * ld[bj], v);
;                     asm volatile("" ::: "memory");
;                 }
.LBB0_383:
	v_mul_lo_u32 v7, s91, v106
	v_mul_lo_u32 v103, s90, v107
	s_waitcnt lgkmcnt(0)
	v_mad_u64_u32 v[8:9], s[18:19], s90, v106, 0
	v_add3_u32 v9, v9, v103, v7
	v_lshl_add_u64 v[8:9], v[8:9], 1, v[148:149]
	v_cvt_pk_bf16_f32 v100, v100, v102
	v_cvt_pk_bf16_f32 v101, v4, v101
	v_cvt_pk_bf16_f32 v102, v3, v5
	v_cvt_pk_bf16_f32 v103, v2, v6
	global_store_dwordx4 v[8:9], v[100:103], off
	v_mov_b32_e32 v109, v108
	v_mul_f32_e32 v2, v94, v108
	v_mul_f32_e32 v3, v95, v109
	v_mul_f32_e32 v6, v90, v108
	v_mul_f32_e32 v7, v91, v109
	v_mul_f32_e32 v4, v96, v108
	v_mul_f32_e32 v5, v97, v109
	v_mul_f32_e32 v8, v92, v108
	v_mul_f32_e32 v9, v93, v109
	s_and_saveexec_b64 s[18:19], s[10:11]
	s_cbranch_execz .LBB0_385
	v_mov_b32_e32 v145, v1
	v_lshl_add_u64 v[90:91], v[144:145], 3, v[98:99]
	global_load_dwordx4 v[96:99], v[90:91], off offset:16
	global_load_dwordx4 v[92:95], v[90:91], off
	s_waitcnt vmcnt(0)
	v_mul_f32_e32 v100, v3, v93
	v_mul_f32_e32 v101, v3, v92
	s_nop 0
	v_fma_f32 v90, v2, v92, -v100
	v_fma_f32 v91, v2, v93, -v101
	v_fma_f32 v3, v2, v93, v101
	v_fma_f32 v2, v2, v92, v100
	v_mul_f32_e32 v100, v5, v95
	v_mul_f32_e32 v101, v5, v94
	v_mul_f32_e32 v2, v9, v99
	v_fma_f32 v92, v4, v94, -v100
	v_fma_f32 v93, v4, v95, -v101
	v_fma_f32 v5, v4, v95, v101
	v_fma_f32 v4, v4, v94, v100
	v_mul_f32_e32 v100, v7, v97
	v_mul_f32_e32 v101, v7, v96
	v_mov_b32_e32 v91, v3
	v_fma_f32 v94, v6, v96, -v100
	v_fma_f32 v95, v6, v97, -v101
	v_fma_f32 v7, v6, v97, v101
	v_fma_f32 v6, v6, v96, v100
	v_fma_f32 v96, v8, v98, -v2
	v_fma_f32 v97, v9, v99, -v2
	v_mul_f32_e32 v2, v9, v98
	v_fma_f32 v8, v8, v99, v2
	v_fma_f32 v9, v9, v98, v2
	v_mov_b32_e32 v93, v5
	v_mov_b32_e32 v95, v7
	v_mov_b32_e32 v97, v8
	v_mov_b64_e32 v[2:3], v[90:91]
	v_mov_b64_e32 v[4:5], v[92:93]
	v_mov_b64_e32 v[6:7], v[94:95]
	v_mov_b64_e32 v[8:9], v[96:97]
.LBB0_385:
	s_or_b64 exec, exec, s[18:19]
	s_and_b64 vcc, exec, s[12:13]
	s_cbranch_vccnz .LBB0_387
	v_mul_f32_e32 v90, 0xbfb8aa3b, v2
	v_mul_f32_e32 v91, 0xbfb8aa3b, v3
	v_mul_f32_e32 v92, 0xbfb8aa3b, v4
	v_mul_f32_e32 v93, 0xbfb8aa3b, v5
	v_mul_f32_e32 v94, 0xbfb8aa3b, v6
	v_mul_f32_e32 v95, 0xbfb8aa3b, v7
	v_mul_f32_e32 v96, 0xbfb8aa3b, v8
	v_mul_f32_e32 v97, 0xbfb8aa3b, v9
	v_exp_f32_e32 v90, v90
	v_exp_f32_e32 v91, v91
	v_exp_f32_e32 v92, v92
	v_exp_f32_e32 v93, v93
	v_exp_f32_e32 v94, v94
	v_exp_f32_e32 v95, v95
	v_exp_f32_e32 v96, v96
	v_exp_f32_e32 v97, v97
	v_add_f32_e32 v90, 1.0, v90
	v_add_f32_e32 v91, 1.0, v91
	v_add_f32_e32 v92, 1.0, v92
	v_add_f32_e32 v93, 1.0, v93
	v_add_f32_e32 v94, 1.0, v94
	v_add_f32_e32 v95, 1.0, v95
	v_add_f32_e32 v96, 1.0, v96
	v_add_f32_e32 v97, 1.0, v97
	v_rcp_f32_e32 v90, v90
	v_rcp_f32_e32 v92, v92
	v_rcp_f32_e32 v94, v94
	v_rcp_f32_e32 v96, v96
	v_rcp_f32_e32 v97, v97
	v_rcp_f32_e32 v95, v95
	v_rcp_f32_e32 v93, v93
	v_rcp_f32_e32 v91, v91
	v_mul_f32_e32 v8, v8, v96
	v_mul_f32_e32 v9, v9, v97
	v_mul_f32_e32 v6, v6, v94
	v_mul_f32_e32 v7, v7, v95
	v_mul_f32_e32 v4, v4, v92
	v_mul_f32_e32 v5, v5, v93
	v_mul_f32_e32 v2, v2, v90
	v_mul_f32_e32 v3, v3, v91

; __device__ __forceinline__ float silu_f(float x) { return x * __builtin_amdgcn_rcpf(1.0f + __builtin_amdgcn_exp2f(-x * 1.4426950408889634f)); }
; __device__ __forceinline__ void rope8(float (&v)[8], const tab_t* tp) {
;     const f32x4 t0 = *(const f32x4*)tp, t1 = *(const f32x4*)(tp + 2);
;     const float c[4] = {t0[0], t0[2], t1[0], t1[2]}, s[4] = {t0[1], t0[3], t1[1], t1[3]};
; #pragma unroll
;     for (int j = 0; j < 4; ++j) { const float a = v[2 * j], b = v[2 * j + 1]; v[2 * j] = a * c[j] - b * s[j]; v[2 * j + 1] = b * c[j] + a * s[j]; }
; }
;     __device__ __forceinline__ void operator()(const f32x4 (&acc)[2][2][4][2], const Unit& u, int wr, int wc, int fr, int fq) const {
;     ...
;                 const int row = row0 + ai * HALF + m * 16;
;                 const float r = __builtin_amdgcn_rsqf(sum_parts<8>(ssq_h + (size_t)row * 32) * (1.0f / 2048.0f) + 1e-6f);
; #pragma unroll
;                 for (int bj = 0; bj < 2; ++bj) {
;                     float v[8];
; #pragma unroll
;                     for (int e = 0; e < 4; ++e) { v[e] = acc[ai][bj][m][0][e] * r; v[4 + e] = acc[ai][bj][m][1][e] * r; }
;                     if (tab[bj] >= 0) rope8(v, TAB + (size_t)row * NTAB + tab[bj]);
;                     if (act[bj]) {
; #pragma unroll
;                         for (int e = 0; e < 8; ++e) v[e] = silu_f(v[e]);
;                     }
; #pragma unroll
;                     for (int e = 0; e < 8; ++e) v[e] *= sc[bj];
;                     if (ssq[bj]) { float s = 0.f;
; #pragma unroll
;                         for (int e = 0; e < 8; ++e) s += v[e] * v[e];
;                         s += __shfl_xor(s, 16); s += __shfl_xor(s, 32);
;                         if (fq == 0) ssq[bj][(size_t)row * sld[bj]] = s; }
;                     store8(dst[bj] + (size_t)row * ld[bj], v);
;                     asm volatile("" ::: "memory");
;                 }
.LBB0_391:
	v_mul_lo_u32 v7, s93, v106
	v_mul_lo_u32 v93, s92, v107
	s_waitcnt lgkmcnt(0)
	v_mad_u64_u32 v[8:9], s[18:19], s92, v106, 0
	v_add3_u32 v9, v9, v93, v7
	v_lshl_add_u64 v[8:9], v[8:9], 1, v[122:123]
	v_cvt_pk_bf16_f32 v90, v90, v92
	v_cvt_pk_bf16_f32 v91, v4, v91
	v_cvt_pk_bf16_f32 v92, v3, v5
	v_cvt_pk_bf16_f32 v93, v2, v6
	global_store_dwordx4 v[8:9], v[90:93], off
	s_nop 1
	v_or_b32_e32 v90, 48, v146
	v_ashrrev_i32_e32 v91, 31, v90
	v_mad_i64_i32 v[94:95], s[18:19], v90, s1, 0
	v_mov_b32_e32 v92, v171
	s_nop 0
	v_mul_f32_e32 v2, v86, v92
	v_mul_f32_e32 v3, v87, v92
	v_mul_f32_e32 v6, v82, v92
	v_mul_f32_e32 v7, v83, v92
	v_mul_f32_e32 v4, v88, v92
	v_mul_f32_e32 v5, v89, v92
	v_mul_f32_e32 v8, v84, v92
	v_mul_f32_e32 v9, v85, v92
	v_lshl_add_u64 v[82:83], s[70:71], 0, v[94:95]
	s_and_saveexec_b64 s[18:19], s[6:7]
	s_cbranch_execz .LBB0_393
	v_lshl_add_u64 v[88:89], v[0:1], 3, v[82:83]
	global_load_dwordx4 v[84:87], v[88:89], off offset:16
	global_load_dwordx4 v[96:99], v[88:89], off
	s_waitcnt vmcnt(0)
	v_mul_f32_e32 v88, v3, v97
	v_mul_f32_e32 v89, v3, v96
	s_nop 0
	v_fma_f32 v94, v2, v96, -v88
	v_fma_f32 v95, v2, v97, -v89
	v_fma_f32 v3, v2, v97, v89
	v_fma_f32 v2, v2, v96, v88
	v_mul_f32_e32 v88, v5, v99
	v_mul_f32_e32 v89, v5, v98
	v_mul_f32_e32 v2, v9, v87
	v_fma_f32 v96, v4, v98, -v88
	v_fma_f32 v97, v4, v99, -v89
	v_fma_f32 v5, v4, v99, v89
	v_fma_f32 v4, v4, v98, v88
	v_mul_f32_e32 v88, v7, v85
	v_mul_f32_e32 v89, v7, v84
	v_fma_f32 v100, v8, v86, -v2
	v_fma_f32 v101, v9, v87, -v2
	v_mul_f32_e32 v2, v9, v86
	v_fma_f32 v98, v6, v84, -v88
	v_fma_f32 v99, v6, v85, -v89
	v_fma_f32 v7, v6, v85, v89
	v_fma_f32 v6, v6, v84, v88
	v_fma_f32 v8, v8, v87, v2
	v_fma_f32 v9, v9, v86, v2
	v_mov_b32_e32 v95, v3
	v_mov_b32_e32 v97, v5
	v_mov_b32_e32 v99, v7
	v_mov_b32_e32 v101, v8
	v_mov_b64_e32 v[2:3], v[94:95]
	v_mov_b64_e32 v[4:5], v[96:97]
	v_mov_b64_e32 v[6:7], v[98:99]
	v_mov_b64_e32 v[8:9], v[100:101]
.LBB0_393:
	s_or_b64 exec, exec, s[18:19]
	s_and_b64 vcc, exec, s[8:9]
	s_cbranch_vccnz .LBB0_395
	v_mul_f32_e32 v93, 0xbfb8aa3b, v8
	v_mul_f32_e32 v84, 0xbfb8aa3b, v2
	v_mul_f32_e32 v85, 0xbfb8aa3b, v3
	v_mul_f32_e32 v86, 0xbfb8aa3b, v4
	v_mul_f32_e32 v87, 0xbfb8aa3b, v5
	v_mul_f32_e32 v88, 0xbfb8aa3b, v6
	v_mul_f32_e32 v89, 0xbfb8aa3b, v7
	v_exp_f32_e32 v93, v93
	v_mul_f32_e32 v94, 0xbfb8aa3b, v9
	v_exp_f32_e32 v84, v84
	v_exp_f32_e32 v85, v85
	v_exp_f32_e32 v86, v86
	v_exp_f32_e32 v87, v87
	v_exp_f32_e32 v88, v88
	v_exp_f32_e32 v89, v89
	v_exp_f32_e32 v95, v94
	v_add_f32_e32 v93, 1.0, v93
	v_add_f32_e32 v84, 1.0, v84
	v_add_f32_e32 v85, 1.0, v85
	v_add_f32_e32 v86, 1.0, v86
	v_add_f32_e32 v87, 1.0, v87
	v_add_f32_e32 v88, 1.0, v88
	v_add_f32_e32 v89, 1.0, v89
	v_rcp_f32_e32 v94, v93
	v_add_f32_e32 v93, 1.0, v95
	v_rcp_f32_e32 v84, v84
	v_rcp_f32_e32 v86, v86
	v_rcp_f32_e32 v88, v88
	v_rcp_f32_e32 v95, v93
	v_rcp_f32_e32 v89, v89
	v_rcp_f32_e32 v87, v87
	v_rcp_f32_e32 v85, v85
	v_mul_f32_e32 v8, v8, v94
	v_mul_f32_e32 v9, v9, v95
	v_mul_f32_e32 v6, v6, v88
	v_mul_f32_e32 v7, v7, v89
	v_mul_f32_e32 v4, v4, v86
	v_mul_f32_e32 v5, v5, v87
	v_mul_f32_e32 v2, v2, v84
	v_mul_f32_e32 v3, v3, v85

; __device__ __forceinline__ float silu_f(float x) { return x * __builtin_amdgcn_rcpf(1.0f + __builtin_amdgcn_exp2f(-x * 1.4426950408889634f)); }
; __device__ __forceinline__ void rope8(float (&v)[8], const tab_t* tp) {
;     const f32x4 t0 = *(const f32x4*)tp, t1 = *(const f32x4*)(tp + 2);
;     const float c[4] = {t0[0], t0[2], t1[0], t1[2]}, s[4] = {t0[1], t0[3], t1[1], t1[3]};
; #pragma unroll
;     for (int j = 0; j < 4; ++j) { const float a = v[2 * j], b = v[2 * j + 1]; v[2 * j] = a * c[j] - b * s[j]; v[2 * j + 1] = b * c[j] + a * s[j]; }
; }
;     __device__ __forceinline__ void operator()(const f32x4 (&acc)[2][2][4][2], const Unit& u, int wr, int wc, int fr, int fq) const {
;     ...
;                 const int row = row0 + ai * HALF + m * 16;
;                 const float r = __builtin_amdgcn_rsqf(sum_parts<8>(ssq_h + (size_t)row * 32) * (1.0f / 2048.0f) + 1e-6f);
; #pragma unroll
;                 for (int bj = 0; bj < 2; ++bj) {
;                     float v[8];
; #pragma unroll
;                     for (int e = 0; e < 4; ++e) { v[e] = acc[ai][bj][m][0][e] * r; v[4 + e] = acc[ai][bj][m][1][e] * r; }
;                     if (tab[bj] >= 0) rope8(v, TAB + (size_t)row * NTAB + tab[bj]);
;                     if (act[bj]) {
; #pragma unroll
;                         for (int e = 0; e < 8; ++e) v[e] = silu_f(v[e]);
;                     }
; #pragma unroll
;                     for (int e = 0; e < 8; ++e) v[e] *= sc[bj];
;                     if (ssq[bj]) { float s = 0.f;
; #pragma unroll
;                         for (int e = 0; e < 8; ++e) s += v[e] * v[e];
;                         s += __shfl_xor(s, 16); s += __shfl_xor(s, 32);
;                         if (fq == 0) ssq[bj][(size_t)row * sld[bj]] = s; }
;                     store8(dst[bj] + (size_t)row * ld[bj], v);
;                     asm volatile("" ::: "memory");
;                 }
.LBB0_399:
	v_mul_lo_u32 v7, s91, v90
	v_mul_lo_u32 v87, s90, v91
	s_waitcnt lgkmcnt(0)
	v_mad_u64_u32 v[8:9], s[18:19], s90, v90, 0
	v_add3_u32 v9, v9, v87, v7
	v_lshl_add_u64 v[8:9], v[8:9], 1, v[148:149]
	v_cvt_pk_bf16_f32 v84, v84, v86
	v_cvt_pk_bf16_f32 v85, v4, v85
	v_cvt_pk_bf16_f32 v86, v3, v5
	v_cvt_pk_bf16_f32 v87, v2, v6
	global_store_dwordx4 v[8:9], v[84:87], off
	v_mov_b32_e32 v93, v92
	v_mul_f32_e32 v2, v78, v92
	v_mul_f32_e32 v3, v79, v93
	v_mul_f32_e32 v6, v74, v92
	v_mul_f32_e32 v7, v75, v93
	v_mul_f32_e32 v4, v80, v92
	v_mul_f32_e32 v5, v81, v93
	v_mul_f32_e32 v8, v76, v92
	v_mul_f32_e32 v9, v77, v93
	s_and_saveexec_b64 s[18:19], s[10:11]
	s_cbranch_execz .LBB0_401
	v_mov_b32_e32 v145, v1
	v_lshl_add_u64 v[74:75], v[144:145], 3, v[82:83]
	global_load_dwordx4 v[80:83], v[74:75], off offset:16
	global_load_dwordx4 v[76:79], v[74:75], off
	s_waitcnt vmcnt(0)
	v_mul_f32_e32 v84, v3, v77
	v_mul_f32_e32 v85, v3, v76
	s_nop 0
	v_fma_f32 v74, v2, v76, -v84
	v_fma_f32 v75, v2, v77, -v85
	v_fma_f32 v3, v2, v77, v85
	v_fma_f32 v2, v2, v76, v84
	v_mul_f32_e32 v84, v5, v79
	v_mul_f32_e32 v85, v5, v78
	v_mul_f32_e32 v2, v9, v83
	v_fma_f32 v76, v4, v78, -v84
	v_fma_f32 v77, v4, v79, -v85
	v_fma_f32 v5, v4, v79, v85
	v_fma_f32 v4, v4, v78, v84
	v_mul_f32_e32 v84, v7, v81
	v_mul_f32_e32 v85, v7, v80
	v_mov_b32_e32 v75, v3
	v_fma_f32 v78, v6, v80, -v84
	v_fma_f32 v79, v6, v81, -v85
	v_fma_f32 v7, v6, v81, v85
	v_fma_f32 v6, v6, v80, v84
	v_fma_f32 v80, v8, v82, -v2
	v_fma_f32 v81, v9, v83, -v2
	v_mul_f32_e32 v2, v9, v82
	v_fma_f32 v8, v8, v83, v2
	v_fma_f32 v9, v9, v82, v2
	v_mov_b32_e32 v77, v5
	v_mov_b32_e32 v79, v7
	v_mov_b32_e32 v81, v8
	v_mov_b64_e32 v[2:3], v[74:75]
	v_mov_b64_e32 v[4:5], v[76:77]
	v_mov_b64_e32 v[6:7], v[78:79]
	v_mov_b64_e32 v[8:9], v[80:81]
.LBB0_401:
	s_or_b64 exec, exec, s[18:19]
	s_and_b64 vcc, exec, s[12:13]
	s_cbranch_vccnz .LBB0_403
	v_mul_f32_e32 v74, 0xbfb8aa3b, v2
	v_mul_f32_e32 v75, 0xbfb8aa3b, v3
	v_mul_f32_e32 v76, 0xbfb8aa3b, v4
	v_mul_f32_e32 v77, 0xbfb8aa3b, v5
	v_mul_f32_e32 v78, 0xbfb8aa3b, v6
	v_mul_f32_e32 v79, 0xbfb8aa3b, v7
	v_mul_f32_e32 v80, 0xbfb8aa3b, v8
	v_mul_f32_e32 v81, 0xbfb8aa3b, v9
	v_exp_f32_e32 v74, v74
	v_exp_f32_e32 v75, v75
	v_exp_f32_e32 v76, v76
	v_exp_f32_e32 v77, v77
	v_exp_f32_e32 v78, v78
	v_exp_f32_e32 v79, v79
	v_exp_f32_e32 v80, v80
	v_exp_f32_e32 v81, v81
	v_add_f32_e32 v74, 1.0, v74
	v_add_f32_e32 v75, 1.0, v75
	v_add_f32_e32 v76, 1.0, v76
	v_add_f32_e32 v77, 1.0, v77
	v_add_f32_e32 v78, 1.0, v78
	v_add_f32_e32 v79, 1.0, v79
	v_add_f32_e32 v80, 1.0, v80
	v_add_f32_e32 v81, 1.0, v81
	v_rcp_f32_e32 v74, v74
	v_rcp_f32_e32 v76, v76
	v_rcp_f32_e32 v78, v78
	v_rcp_f32_e32 v80, v80
	v_rcp_f32_e32 v81, v81
	v_rcp_f32_e32 v79, v79
	v_rcp_f32_e32 v77, v77
	v_rcp_f32_e32 v75, v75
	v_mul_f32_e32 v8, v8, v80
	v_mul_f32_e32 v9, v9, v81
	v_mul_f32_e32 v6, v6, v78
	v_mul_f32_e32 v7, v7, v79
	v_mul_f32_e32 v4, v4, v76
	v_mul_f32_e32 v5, v5, v77
	v_mul_f32_e32 v2, v2, v74
	v_mul_f32_e32 v3, v3, v75

; __device__ __forceinline__ float silu_f(float x) { return x * __builtin_amdgcn_rcpf(1.0f + __builtin_amdgcn_exp2f(-x * 1.4426950408889634f)); }
; __device__ __forceinline__ void rope8(float (&v)[8], const tab_t* tp) {
;     const f32x4 t0 = *(const f32x4*)tp, t1 = *(const f32x4*)(tp + 2);
;     const float c[4] = {t0[0], t0[2], t1[0], t1[2]}, s[4] = {t0[1], t0[3], t1[1], t1[3]};
; #pragma unroll
;     for (int j = 0; j < 4; ++j) { const float a = v[2 * j], b = v[2 * j + 1]; v[2 * j] = a * c[j] - b * s[j]; v[2 * j + 1] = b * c[j] + a * s[j]; }
; }
;     __device__ __forceinline__ void operator()(const f32x4 (&acc)[2][2][4][2], const Unit& u, int wr, int wc, int fr, int fq) const {
;     ...
;                 const int row = row0 + ai * HALF + m * 16;
;                 const float r = __builtin_amdgcn_rsqf(sum_parts<8>(ssq_h + (size_t)row * 32) * (1.0f / 2048.0f) + 1e-6f);
; #pragma unroll
;                 for (int bj = 0; bj < 2; ++bj) {
;                     float v[8];
; #pragma unroll
;                     for (int e = 0; e < 4; ++e) { v[e] = acc[ai][bj][m][0][e] * r; v[4 + e] = acc[ai][bj][m][1][e] * r; }
;                     if (tab[bj] >= 0) rope8(v, TAB + (size_t)row * NTAB + tab[bj]);
;                     if (act[bj]) {
; #pragma unroll
;                         for (int e = 0; e < 8; ++e) v[e] = silu_f(v[e]);
;                     }
; #pragma unroll
;                     for (int e = 0; e < 8; ++e) v[e] *= sc[bj];
;                     if (ssq[bj]) { float s = 0.f;
; #pragma unroll
;                         for (int e = 0; e < 8; ++e) s += v[e] * v[e];
;                         s += __shfl_xor(s, 16); s += __shfl_xor(s, 32);
;                         if (fq == 0) ssq[bj][(size_t)row * sld[bj]] = s; }
;                     store8(dst[bj] + (size_t)row * ld[bj], v);
;                     asm volatile("" ::: "memory");
;                 }
.LBB0_407:
	v_mul_lo_u32 v7, s93, v90
	v_mul_lo_u32 v77, s92, v91
	s_waitcnt lgkmcnt(0)
	v_mad_u64_u32 v[8:9], s[18:19], s92, v90, 0
	v_add3_u32 v9, v9, v77, v7
	v_lshl_add_u64 v[8:9], v[8:9], 1, v[122:123]
	v_cvt_pk_bf16_f32 v74, v74, v76
	v_cvt_pk_bf16_f32 v75, v4, v75
	v_cvt_pk_bf16_f32 v76, v3, v5
	v_cvt_pk_bf16_f32 v77, v2, v6
	global_store_dwordx4 v[8:9], v[74:77], off
	s_nop 1
	v_add_u32_e32 v74, 0x80, v146
	v_ashrrev_i32_e32 v75, 31, v74
	v_mad_i64_i32 v[78:79], s[18:19], v74, s1, 0
	v_mov_b32_e32 v76, v172
	s_nop 0
	v_mul_f32_e32 v2, v70, v76
	v_mul_f32_e32 v3, v71, v76
	v_mul_f32_e32 v6, v66, v76
	v_mul_f32_e32 v7, v67, v76
	v_mul_f32_e32 v4, v72, v76
	v_mul_f32_e32 v5, v73, v76
	v_mul_f32_e32 v8, v68, v76
	v_mul_f32_e32 v9, v69, v76
	v_lshl_add_u64 v[66:67], s[70:71], 0, v[78:79]
	s_and_saveexec_b64 s[18:19], s[6:7]
	s_cbranch_execz .LBB0_409
	v_lshl_add_u64 v[72:73], v[0:1], 3, v[66:67]
	global_load_dwordx4 v[68:71], v[72:73], off offset:16
	global_load_dwordx4 v[80:83], v[72:73], off
	s_waitcnt vmcnt(0)
	v_mul_f32_e32 v72, v3, v81
	v_mul_f32_e32 v73, v3, v80
	s_nop 0
	v_fma_f32 v78, v2, v80, -v72
	v_fma_f32 v79, v2, v81, -v73
	v_fma_f32 v3, v2, v81, v73
	v_fma_f32 v2, v2, v80, v72
	v_mul_f32_e32 v72, v5, v83
	v_mul_f32_e32 v73, v5, v82
	v_mul_f32_e32 v2, v9, v71
	v_fma_f32 v80, v4, v82, -v72
	v_fma_f32 v81, v4, v83, -v73
	v_fma_f32 v5, v4, v83, v73
	v_fma_f32 v4, v4, v82, v72
	v_mul_f32_e32 v72, v7, v69
	v_mul_f32_e32 v73, v7, v68
	v_fma_f32 v84, v8, v70, -v2
	v_fma_f32 v85, v9, v71, -v2
	v_mul_f32_e32 v2, v9, v70
	v_fma_f32 v82, v6, v68, -v72
	v_fma_f32 v83, v6, v69, -v73
	v_fma_f32 v7, v6, v69, v73
	v_fma_f32 v6, v6, v68, v72
	v_fma_f32 v8, v8, v71, v2
	v_fma_f32 v9, v9, v70, v2
	v_mov_b32_e32 v79, v3
	v_mov_b32_e32 v81, v5
	v_mov_b32_e32 v83, v7
	v_mov_b32_e32 v85, v8
	v_mov_b64_e32 v[2:3], v[78:79]
	v_mov_b64_e32 v[4:5], v[80:81]
	v_mov_b64_e32 v[6:7], v[82:83]
	v_mov_b64_e32 v[8:9], v[84:85]
.LBB0_409:
	s_or_b64 exec, exec, s[18:19]
	s_and_b64 vcc, exec, s[8:9]
	s_cbranch_vccnz .LBB0_411
	v_mul_f32_e32 v77, 0xbfb8aa3b, v8
	v_mul_f32_e32 v68, 0xbfb8aa3b, v2
	v_mul_f32_e32 v69, 0xbfb8aa3b, v3
	v_mul_f32_e32 v70, 0xbfb8aa3b, v4
	v_mul_f32_e32 v71, 0xbfb8aa3b, v5
	v_mul_f32_e32 v72, 0xbfb8aa3b, v6
	v_mul_f32_e32 v73, 0xbfb8aa3b, v7
	v_exp_f32_e32 v77, v77
	v_mul_f32_e32 v78, 0xbfb8aa3b, v9
	v_exp_f32_e32 v68, v68
	v_exp_f32_e32 v69, v69
	v_exp_f32_e32 v70, v70
	v_exp_f32_e32 v71, v71
	v_exp_f32_e32 v72, v72
	v_exp_f32_e32 v73, v73
	v_exp_f32_e32 v79, v78
	v_add_f32_e32 v77, 1.0, v77
	v_add_f32_e32 v68, 1.0, v68
	v_add_f32_e32 v69, 1.0, v69
	v_add_f32_e32 v70, 1.0, v70
	v_add_f32_e32 v71, 1.0, v71
	v_add_f32_e32 v72, 1.0, v72
	v_add_f32_e32 v73, 1.0, v73
	v_rcp_f32_e32 v78, v77
	v_add_f32_e32 v77, 1.0, v79
	v_rcp_f32_e32 v68, v68
	v_rcp_f32_e32 v70, v70
	v_rcp_f32_e32 v72, v72
	v_rcp_f32_e32 v79, v77
	v_rcp_f32_e32 v73, v73
	v_rcp_f32_e32 v71, v71
	v_rcp_f32_e32 v69, v69
	v_mul_f32_e32 v8, v8, v78
	v_mul_f32_e32 v9, v9, v79
	v_mul_f32_e32 v6, v6, v72
	v_mul_f32_e32 v7, v7, v73
	v_mul_f32_e32 v4, v4, v70
	v_mul_f32_e32 v5, v5, v71
	v_mul_f32_e32 v2, v2, v68
	v_mul_f32_e32 v3, v3, v69

; __device__ __forceinline__ float silu_f(float x) { return x * __builtin_amdgcn_rcpf(1.0f + __builtin_amdgcn_exp2f(-x * 1.4426950408889634f)); }
; __device__ __forceinline__ void rope8(float (&v)[8], const tab_t* tp) {
;     const f32x4 t0 = *(const f32x4*)tp, t1 = *(const f32x4*)(tp + 2);
;     const float c[4] = {t0[0], t0[2], t1[0], t1[2]}, s[4] = {t0[1], t0[3], t1[1], t1[3]};
; #pragma unroll
;     for (int j = 0; j < 4; ++j) { const float a = v[2 * j], b = v[2 * j + 1]; v[2 * j] = a * c[j] - b * s[j]; v[2 * j + 1] = b * c[j] + a * s[j]; }
; }
;     __device__ __forceinline__ void operator()(const f32x4 (&acc)[2][2][4][2], const Unit& u, int wr, int wc, int fr, int fq) const {
;     ...
;                 const int row = row0 + ai * HALF + m * 16;
;                 const float r = __builtin_amdgcn_rsqf(sum_parts<8>(ssq_h + (size_t)row * 32) * (1.0f / 2048.0f) + 1e-6f);
; #pragma unroll
;                 for (int bj = 0; bj < 2; ++bj) {
;                     float v[8];
; #pragma unroll
;                     for (int e = 0; e < 4; ++e) { v[e] = acc[ai][bj][m][0][e] * r; v[4 + e] = acc[ai][bj][m][1][e] * r; }
;                     if (tab[bj] >= 0) rope8(v, TAB + (size_t)row * NTAB + tab[bj]);
;                     if (act[bj]) {
; #pragma unroll
;                         for (int e = 0; e < 8; ++e) v[e] = silu_f(v[e]);
;                     }
; #pragma unroll
;                     for (int e = 0; e < 8; ++e) v[e] *= sc[bj];
;                     if (ssq[bj]) { float s = 0.f;
; #pragma unroll
;                         for (int e = 0; e < 8; ++e) s += v[e] * v[e];
;                         s += __shfl_xor(s, 16); s += __shfl_xor(s, 32);
;                         if (fq == 0) ssq[bj][(size_t)row * sld[bj]] = s; }
;                     store8(dst[bj] + (size_t)row * ld[bj], v);
;                     asm volatile("" ::: "memory");
;                 }
.LBB0_415:
	v_mul_lo_u32 v7, s91, v74
	v_mul_lo_u32 v71, s90, v75
	s_waitcnt lgkmcnt(0)
	v_mad_u64_u32 v[8:9], s[18:19], s90, v74, 0
	v_add3_u32 v9, v9, v71, v7
	v_lshl_add_u64 v[8:9], v[8:9], 1, v[148:149]
	v_cvt_pk_bf16_f32 v68, v68, v70
	v_cvt_pk_bf16_f32 v69, v4, v69
	v_cvt_pk_bf16_f32 v70, v3, v5
	v_cvt_pk_bf16_f32 v71, v2, v6
	global_store_dwordx4 v[8:9], v[68:71], off
	v_mov_b32_e32 v77, v76
	v_mul_f32_e32 v2, v62, v76
	v_mul_f32_e32 v3, v63, v77
	v_mul_f32_e32 v6, v58, v76
	v_mul_f32_e32 v7, v59, v77
	v_mul_f32_e32 v4, v64, v76
	v_mul_f32_e32 v5, v65, v77
	v_mul_f32_e32 v8, v60, v76
	v_mul_f32_e32 v9, v61, v77
	s_and_saveexec_b64 s[18:19], s[10:11]
	s_cbranch_execz .LBB0_417
	v_mov_b32_e32 v145, v1
	v_lshl_add_u64 v[58:59], v[144:145], 3, v[66:67]
	global_load_dwordx4 v[64:67], v[58:59], off offset:16
	global_load_dwordx4 v[60:63], v[58:59], off
	s_waitcnt vmcnt(0)
	v_mul_f32_e32 v68, v3, v61
	v_mul_f32_e32 v69, v3, v60
	s_nop 0
	v_fma_f32 v58, v2, v60, -v68
	v_fma_f32 v59, v2, v61, -v69
	v_fma_f32 v3, v2, v61, v69
	v_fma_f32 v2, v2, v60, v68
	v_mul_f32_e32 v68, v5, v63
	v_mul_f32_e32 v69, v5, v62
	v_mul_f32_e32 v2, v9, v67
	v_fma_f32 v60, v4, v62, -v68
	v_fma_f32 v61, v4, v63, -v69
	v_fma_f32 v5, v4, v63, v69
	v_fma_f32 v4, v4, v62, v68
	v_mul_f32_e32 v68, v7, v65
	v_mul_f32_e32 v69, v7, v64
	v_mov_b32_e32 v59, v3
	v_fma_f32 v62, v6, v64, -v68
	v_fma_f32 v63, v6, v65, -v69
	v_fma_f32 v7, v6, v65, v69
	v_fma_f32 v6, v6, v64, v68
	v_fma_f32 v64, v8, v66, -v2
	v_fma_f32 v65, v9, v67, -v2
	v_mul_f32_e32 v2, v9, v66
	v_fma_f32 v8, v8, v67, v2
	v_fma_f32 v9, v9, v66, v2
	v_mov_b32_e32 v61, v5
	v_mov_b32_e32 v63, v7
	v_mov_b32_e32 v65, v8
	v_mov_b64_e32 v[2:3], v[58:59]
	v_mov_b64_e32 v[4:5], v[60:61]
	v_mov_b64_e32 v[6:7], v[62:63]
	v_mov_b64_e32 v[8:9], v[64:65]
.LBB0_417:
	s_or_b64 exec, exec, s[18:19]
	s_and_b64 vcc, exec, s[12:13]
	s_cbranch_vccnz .LBB0_419
	v_mul_f32_e32 v58, 0xbfb8aa3b, v2
	v_mul_f32_e32 v59, 0xbfb8aa3b, v3
	v_mul_f32_e32 v60, 0xbfb8aa3b, v4
	v_mul_f32_e32 v61, 0xbfb8aa3b, v5
	v_mul_f32_e32 v62, 0xbfb8aa3b, v6
	v_mul_f32_e32 v63, 0xbfb8aa3b, v7
	v_mul_f32_e32 v64, 0xbfb8aa3b, v8
	v_mul_f32_e32 v65, 0xbfb8aa3b, v9
	v_exp_f32_e32 v58, v58
	v_exp_f32_e32 v59, v59
	v_exp_f32_e32 v60, v60
	v_exp_f32_e32 v61, v61
	v_exp_f32_e32 v62, v62
	v_exp_f32_e32 v63, v63
	v_exp_f32_e32 v64, v64
	v_exp_f32_e32 v65, v65
	v_add_f32_e32 v58, 1.0, v58
	v_add_f32_e32 v59, 1.0, v59
	v_add_f32_e32 v60, 1.0, v60
	v_add_f32_e32 v61, 1.0, v61
	v_add_f32_e32 v62, 1.0, v62
	v_add_f32_e32 v63, 1.0, v63
	v_add_f32_e32 v64, 1.0, v64
	v_add_f32_e32 v65, 1.0, v65
	v_rcp_f32_e32 v58, v58
	v_rcp_f32_e32 v60, v60
	v_rcp_f32_e32 v62, v62
	v_rcp_f32_e32 v64, v64
	v_rcp_f32_e32 v65, v65
	v_rcp_f32_e32 v63, v63
	v_rcp_f32_e32 v61, v61
	v_rcp_f32_e32 v59, v59
	v_mul_f32_e32 v8, v8, v64
	v_mul_f32_e32 v9, v9, v65
	v_mul_f32_e32 v6, v6, v62
	v_mul_f32_e32 v7, v7, v63
	v_mul_f32_e32 v4, v4, v60
	v_mul_f32_e32 v5, v5, v61
	v_mul_f32_e32 v2, v2, v58
	v_mul_f32_e32 v3, v3, v59

; __device__ __forceinline__ float silu_f(float x) { return x * __builtin_amdgcn_rcpf(1.0f + __builtin_amdgcn_exp2f(-x * 1.4426950408889634f)); }
; __device__ __forceinline__ void rope8(float (&v)[8], const tab_t* tp) {
;     const f32x4 t0 = *(const f32x4*)tp, t1 = *(const f32x4*)(tp + 2);
;     const float c[4] = {t0[0], t0[2], t1[0], t1[2]}, s[4] = {t0[1], t0[3], t1[1], t1[3]};
; #pragma unroll
;     for (int j = 0; j < 4; ++j) { const float a = v[2 * j], b = v[2 * j + 1]; v[2 * j] = a * c[j] - b * s[j]; v[2 * j + 1] = b * c[j] + a * s[j]; }
; }
;     __device__ __forceinline__ void operator()(const f32x4 (&acc)[2][2][4][2], const Unit& u, int wr, int wc, int fr, int fq) const {
;     ...
;                 const int row = row0 + ai * HALF + m * 16;
;                 const float r = __builtin_amdgcn_rsqf(sum_parts<8>(ssq_h + (size_t)row * 32) * (1.0f / 2048.0f) + 1e-6f);
; #pragma unroll
;                 for (int bj = 0; bj < 2; ++bj) {
;                     float v[8];
; #pragma unroll
;                     for (int e = 0; e < 4; ++e) { v[e] = acc[ai][bj][m][0][e] * r; v[4 + e] = acc[ai][bj][m][1][e] * r; }
;                     if (tab[bj] >= 0) rope8(v, TAB + (size_t)row * NTAB + tab[bj]);
;                     if (act[bj]) {
; #pragma unroll
;                         for (int e = 0; e < 8; ++e) v[e] = silu_f(v[e]);
;                     }
; #pragma unroll
;                     for (int e = 0; e < 8; ++e) v[e] *= sc[bj];
;                     if (ssq[bj]) { float s = 0.f;
; #pragma unroll
;                         for (int e = 0; e < 8; ++e) s += v[e] * v[e];
;                         s += __shfl_xor(s, 16); s += __shfl_xor(s, 32);
;                         if (fq == 0) ssq[bj][(size_t)row * sld[bj]] = s; }
;                     store8(dst[bj] + (size_t)row * ld[bj], v);
;                     asm volatile("" ::: "memory");
;                 }
.LBB0_423:
	v_mul_lo_u32 v7, s93, v74
	v_mul_lo_u32 v61, s92, v75
	s_waitcnt lgkmcnt(0)
	v_mad_u64_u32 v[8:9], s[18:19], s92, v74, 0
	v_add3_u32 v9, v9, v61, v7
	v_lshl_add_u64 v[8:9], v[8:9], 1, v[122:123]
	v_cvt_pk_bf16_f32 v58, v58, v60
	v_cvt_pk_bf16_f32 v59, v4, v59
	v_cvt_pk_bf16_f32 v60, v3, v5
	v_cvt_pk_bf16_f32 v61, v2, v6
	global_store_dwordx4 v[8:9], v[58:61], off
	s_nop 1
	v_add_u32_e32 v58, 0x90, v146
	v_ashrrev_i32_e32 v59, 31, v58
	v_mad_i64_i32 v[62:63], s[18:19], v58, s1, 0
	v_mov_b32_e32 v60, v173
	s_nop 0
	v_mul_f32_e32 v2, v54, v60
	v_mul_f32_e32 v3, v55, v60
	v_mul_f32_e32 v6, v50, v60
	v_mul_f32_e32 v7, v51, v60
	v_mul_f32_e32 v4, v56, v60
	v_mul_f32_e32 v5, v57, v60
	v_mul_f32_e32 v8, v52, v60
	v_mul_f32_e32 v9, v53, v60
	v_lshl_add_u64 v[50:51], s[70:71], 0, v[62:63]
	s_and_saveexec_b64 s[18:19], s[6:7]
	s_cbranch_execz .LBB0_425
	v_lshl_add_u64 v[56:57], v[0:1], 3, v[50:51]
	global_load_dwordx4 v[52:55], v[56:57], off offset:16
	global_load_dwordx4 v[64:67], v[56:57], off
	s_waitcnt vmcnt(0)
	v_mul_f32_e32 v56, v3, v65
	v_mul_f32_e32 v57, v3, v64
	s_nop 0
	v_fma_f32 v62, v2, v64, -v56
	v_fma_f32 v63, v2, v65, -v57
	v_fma_f32 v3, v2, v65, v57
	v_fma_f32 v2, v2, v64, v56
	v_mul_f32_e32 v56, v5, v67
	v_mul_f32_e32 v57, v5, v66
	v_mul_f32_e32 v2, v9, v55
	v_fma_f32 v64, v4, v66, -v56
	v_fma_f32 v65, v4, v67, -v57
	v_fma_f32 v5, v4, v67, v57
	v_fma_f32 v4, v4, v66, v56
	v_mul_f32_e32 v56, v7, v53
	v_mul_f32_e32 v57, v7, v52
	v_fma_f32 v68, v8, v54, -v2
	v_fma_f32 v69, v9, v55, -v2
	v_mul_f32_e32 v2, v9, v54
	v_fma_f32 v66, v6, v52, -v56
	v_fma_f32 v67, v6, v53, -v57
	v_fma_f32 v7, v6, v53, v57
	v_fma_f32 v6, v6, v52, v56
	v_fma_f32 v8, v8, v55, v2
	v_fma_f32 v9, v9, v54, v2
	v_mov_b32_e32 v63, v3
	v_mov_b32_e32 v65, v5
	v_mov_b32_e32 v67, v7
	v_mov_b32_e32 v69, v8
	v_mov_b64_e32 v[2:3], v[62:63]
	v_mov_b64_e32 v[4:5], v[64:65]
	v_mov_b64_e32 v[6:7], v[66:67]
	v_mov_b64_e32 v[8:9], v[68:69]
.LBB0_425:
	s_or_b64 exec, exec, s[18:19]
	s_and_b64 vcc, exec, s[8:9]
	s_cbranch_vccnz .LBB0_427
	v_mul_f32_e32 v61, 0xbfb8aa3b, v8
	v_mul_f32_e32 v52, 0xbfb8aa3b, v2
	v_mul_f32_e32 v53, 0xbfb8aa3b, v3
	v_mul_f32_e32 v54, 0xbfb8aa3b, v4
	v_mul_f32_e32 v55, 0xbfb8aa3b, v5
	v_mul_f32_e32 v56, 0xbfb8aa3b, v6
	v_mul_f32_e32 v57, 0xbfb8aa3b, v7
	v_exp_f32_e32 v61, v61
	v_mul_f32_e32 v62, 0xbfb8aa3b, v9
	v_exp_f32_e32 v52, v52
	v_exp_f32_e32 v53, v53
	v_exp_f32_e32 v54, v54
	v_exp_f32_e32 v55, v55
	v_exp_f32_e32 v56, v56
	v_exp_f32_e32 v57, v57
	v_exp_f32_e32 v63, v62
	v_add_f32_e32 v61, 1.0, v61
	v_add_f32_e32 v52, 1.0, v52
	v_add_f32_e32 v53, 1.0, v53
	v_add_f32_e32 v54, 1.0, v54
	v_add_f32_e32 v55, 1.0, v55
	v_add_f32_e32 v56, 1.0, v56
	v_add_f32_e32 v57, 1.0, v57
	v_rcp_f32_e32 v62, v61
	v_add_f32_e32 v61, 1.0, v63
	v_rcp_f32_e32 v52, v52
	v_rcp_f32_e32 v54, v54
	v_rcp_f32_e32 v56, v56
	v_rcp_f32_e32 v63, v61
	v_rcp_f32_e32 v57, v57
	v_rcp_f32_e32 v55, v55
	v_rcp_f32_e32 v53, v53
	v_mul_f32_e32 v8, v8, v62
	v_mul_f32_e32 v9, v9, v63
	v_mul_f32_e32 v6, v6, v56
	v_mul_f32_e32 v7, v7, v57
	v_mul_f32_e32 v4, v4, v54
	v_mul_f32_e32 v5, v5, v55
	v_mul_f32_e32 v2, v2, v52
	v_mul_f32_e32 v3, v3, v53

; __device__ __forceinline__ float silu_f(float x) { return x * __builtin_amdgcn_rcpf(1.0f + __builtin_amdgcn_exp2f(-x * 1.4426950408889634f)); }
; __device__ __forceinline__ void rope8(float (&v)[8], const tab_t* tp) {
;     const f32x4 t0 = *(const f32x4*)tp, t1 = *(const f32x4*)(tp + 2);
;     const float c[4] = {t0[0], t0[2], t1[0], t1[2]}, s[4] = {t0[1], t0[3], t1[1], t1[3]};
; #pragma unroll
;     for (int j = 0; j < 4; ++j) { const float a = v[2 * j], b = v[2 * j + 1]; v[2 * j] = a * c[j] - b * s[j]; v[2 * j + 1] = b * c[j] + a * s[j]; }
; }
;     __device__ __forceinline__ void operator()(const f32x4 (&acc)[2][2][4][2], const Unit& u, int wr, int wc, int fr, int fq) const {
;     ...
;                 const int row = row0 + ai * HALF + m * 16;
;                 const float r = __builtin_amdgcn_rsqf(sum_parts<8>(ssq_h + (size_t)row * 32) * (1.0f / 2048.0f) + 1e-6f);
; #pragma unroll
;                 for (int bj = 0; bj < 2; ++bj) {
;                     float v[8];
; #pragma unroll
;                     for (int e = 0; e < 4; ++e) { v[e] = acc[ai][bj][m][0][e] * r; v[4 + e] = acc[ai][bj][m][1][e] * r; }
;                     if (tab[bj] >= 0) rope8(v, TAB + (size_t)row * NTAB + tab[bj]);
;                     if (act[bj]) {
; #pragma unroll
;                         for (int e = 0; e < 8; ++e) v[e] = silu_f(v[e]);
;                     }
; #pragma unroll
;                     for (int e = 0; e < 8; ++e) v[e] *= sc[bj];
;                     if (ssq[bj]) { float s = 0.f;
; #pragma unroll
;                         for (int e = 0; e < 8; ++e) s += v[e] * v[e];
;                         s += __shfl_xor(s, 16); s += __shfl_xor(s, 32);
;                         if (fq == 0) ssq[bj][(size_t)row * sld[bj]] = s; }
;                     store8(dst[bj] + (size_t)row * ld[bj], v);
;                     asm volatile("" ::: "memory");
;                 }
.LBB0_431:
	v_mul_lo_u32 v7, s91, v58
	v_mul_lo_u32 v55, s90, v59
	s_waitcnt lgkmcnt(0)
	v_mad_u64_u32 v[8:9], s[18:19], s90, v58, 0
	v_add3_u32 v9, v9, v55, v7
	v_lshl_add_u64 v[8:9], v[8:9], 1, v[148:149]
	v_cvt_pk_bf16_f32 v52, v52, v54
	v_cvt_pk_bf16_f32 v53, v4, v53
	v_cvt_pk_bf16_f32 v54, v3, v5
	v_cvt_pk_bf16_f32 v55, v2, v6
	global_store_dwordx4 v[8:9], v[52:55], off
	v_mov_b32_e32 v61, v60
	v_mul_f32_e32 v2, v46, v60
	v_mul_f32_e32 v3, v47, v61
	v_mul_f32_e32 v6, v42, v60
	v_mul_f32_e32 v7, v43, v61
	v_mul_f32_e32 v4, v48, v60
	v_mul_f32_e32 v5, v49, v61
	v_mul_f32_e32 v8, v44, v60
	v_mul_f32_e32 v9, v45, v61
	s_and_saveexec_b64 s[18:19], s[10:11]
	s_cbranch_execz .LBB0_433
	v_mov_b32_e32 v145, v1
	v_lshl_add_u64 v[42:43], v[144:145], 3, v[50:51]
	global_load_dwordx4 v[48:51], v[42:43], off offset:16
	global_load_dwordx4 v[44:47], v[42:43], off
	s_waitcnt vmcnt(0)
	v_mul_f32_e32 v52, v3, v45
	v_mul_f32_e32 v53, v3, v44
	s_nop 0
	v_fma_f32 v42, v2, v44, -v52
	v_fma_f32 v43, v2, v45, -v53
	v_fma_f32 v3, v2, v45, v53
	v_fma_f32 v2, v2, v44, v52
	v_mul_f32_e32 v52, v5, v47
	v_mul_f32_e32 v53, v5, v46
	v_mul_f32_e32 v2, v9, v51
	v_fma_f32 v44, v4, v46, -v52
	v_fma_f32 v45, v4, v47, -v53
	v_fma_f32 v5, v4, v47, v53
	v_fma_f32 v4, v4, v46, v52
	v_mul_f32_e32 v52, v7, v49
	v_mul_f32_e32 v53, v7, v48
	v_mov_b32_e32 v43, v3
	v_fma_f32 v46, v6, v48, -v52
	v_fma_f32 v47, v6, v49, -v53
	v_fma_f32 v7, v6, v49, v53
	v_fma_f32 v6, v6, v48, v52
	v_fma_f32 v48, v8, v50, -v2
	v_fma_f32 v49, v9, v51, -v2
	v_mul_f32_e32 v2, v9, v50
	v_fma_f32 v8, v8, v51, v2
	v_fma_f32 v9, v9, v50, v2
	v_mov_b32_e32 v45, v5
	v_mov_b32_e32 v47, v7
	v_mov_b32_e32 v49, v8
	v_mov_b64_e32 v[2:3], v[42:43]
	v_mov_b64_e32 v[4:5], v[44:45]
	v_mov_b64_e32 v[6:7], v[46:47]
	v_mov_b64_e32 v[8:9], v[48:49]
.LBB0_433:
	s_or_b64 exec, exec, s[18:19]
	s_and_b64 vcc, exec, s[12:13]
	s_cbranch_vccnz .LBB0_435
	v_mul_f32_e32 v42, 0xbfb8aa3b, v2
	v_mul_f32_e32 v43, 0xbfb8aa3b, v3
	v_mul_f32_e32 v44, 0xbfb8aa3b, v4
	v_mul_f32_e32 v45, 0xbfb8aa3b, v5
	v_mul_f32_e32 v46, 0xbfb8aa3b, v6
	v_mul_f32_e32 v47, 0xbfb8aa3b, v7
	v_mul_f32_e32 v48, 0xbfb8aa3b, v8
	v_mul_f32_e32 v49, 0xbfb8aa3b, v9
	v_exp_f32_e32 v42, v42
	v_exp_f32_e32 v43, v43
	v_exp_f32_e32 v44, v44
	v_exp_f32_e32 v45, v45
	v_exp_f32_e32 v46, v46
	v_exp_f32_e32 v47, v47
	v_exp_f32_e32 v48, v48
	v_exp_f32_e32 v49, v49
	v_add_f32_e32 v42, 1.0, v42
	v_add_f32_e32 v43, 1.0, v43
	v_add_f32_e32 v44, 1.0, v44
	v_add_f32_e32 v45, 1.0, v45
	v_add_f32_e32 v46, 1.0, v46
	v_add_f32_e32 v47, 1.0, v47
	v_add_f32_e32 v48, 1.0, v48
	v_add_f32_e32 v49, 1.0, v49
	v_rcp_f32_e32 v42, v42
	v_rcp_f32_e32 v44, v44
	v_rcp_f32_e32 v46, v46
	v_rcp_f32_e32 v48, v48
	v_rcp_f32_e32 v49, v49
	v_rcp_f32_e32 v47, v47
	v_rcp_f32_e32 v45, v45
	v_rcp_f32_e32 v43, v43
	v_mul_f32_e32 v8, v8, v48
	v_mul_f32_e32 v9, v9, v49
	v_mul_f32_e32 v6, v6, v46
	v_mul_f32_e32 v7, v7, v47
	v_mul_f32_e32 v4, v4, v44
	v_mul_f32_e32 v5, v5, v45
	v_mul_f32_e32 v2, v2, v42
	v_mul_f32_e32 v3, v3, v43

; __device__ __forceinline__ float silu_f(float x) { return x * __builtin_amdgcn_rcpf(1.0f + __builtin_amdgcn_exp2f(-x * 1.4426950408889634f)); }
; __device__ __forceinline__ void rope8(float (&v)[8], const tab_t* tp) {
;     const f32x4 t0 = *(const f32x4*)tp, t1 = *(const f32x4*)(tp + 2);
;     const float c[4] = {t0[0], t0[2], t1[0], t1[2]}, s[4] = {t0[1], t0[3], t1[1], t1[3]};
; #pragma unroll
;     for (int j = 0; j < 4; ++j) { const float a = v[2 * j], b = v[2 * j + 1]; v[2 * j] = a * c[j] - b * s[j]; v[2 * j + 1] = b * c[j] + a * s[j]; }
; }
;     __device__ __forceinline__ void operator()(const f32x4 (&acc)[2][2][4][2], const Unit& u, int wr, int wc, int fr, int fq) const {
;     ...
;                 const int row = row0 + ai * HALF + m * 16;
;                 const float r = __builtin_amdgcn_rsqf(sum_parts<8>(ssq_h + (size_t)row * 32) * (1.0f / 2048.0f) + 1e-6f);
; #pragma unroll
;                 for (int bj = 0; bj < 2; ++bj) {
;                     float v[8];
; #pragma unroll
;                     for (int e = 0; e < 4; ++e) { v[e] = acc[ai][bj][m][0][e] * r; v[4 + e] = acc[ai][bj][m][1][e] * r; }
;                     if (tab[bj] >= 0) rope8(v, TAB + (size_t)row * NTAB + tab[bj]);
;                     if (act[bj]) {
; #pragma unroll
;                         for (int e = 0; e < 8; ++e) v[e] = silu_f(v[e]);
;                     }
; #pragma unroll
;                     for (int e = 0; e < 8; ++e) v[e] *= sc[bj];
;                     if (ssq[bj]) { float s = 0.f;
; #pragma unroll
;                         for (int e = 0; e < 8; ++e) s += v[e] * v[e];
;                         s += __shfl_xor(s, 16); s += __shfl_xor(s, 32);
;                         if (fq == 0) ssq[bj][(size_t)row * sld[bj]] = s; }
;                     store8(dst[bj] + (size_t)row * ld[bj], v);
;                     asm volatile("" ::: "memory");
;                 }
.LBB0_439:
	v_mul_lo_u32 v7, s93, v58
	v_mul_lo_u32 v45, s92, v59
	s_waitcnt lgkmcnt(0)
	v_mad_u64_u32 v[8:9], s[18:19], s92, v58, 0
	v_add3_u32 v9, v9, v45, v7
	v_lshl_add_u64 v[8:9], v[8:9], 1, v[122:123]
	v_cvt_pk_bf16_f32 v42, v42, v44
	v_cvt_pk_bf16_f32 v43, v4, v43
	v_cvt_pk_bf16_f32 v44, v3, v5
	v_cvt_pk_bf16_f32 v45, v2, v6
	global_store_dwordx4 v[8:9], v[42:45], off
	s_nop 1
	v_add_u32_e32 v42, 0xa0, v146
	v_ashrrev_i32_e32 v43, 31, v42
	v_mad_i64_i32 v[46:47], s[18:19], v42, s1, 0
	v_mov_b32_e32 v44, v174
	s_nop 0
	v_mul_f32_e32 v2, v38, v44
	v_mul_f32_e32 v3, v39, v44
	v_mul_f32_e32 v6, v34, v44
	v_mul_f32_e32 v7, v35, v44
	v_mul_f32_e32 v4, v40, v44
	v_mul_f32_e32 v5, v41, v44
	v_mul_f32_e32 v8, v36, v44
	v_mul_f32_e32 v9, v37, v44
	v_lshl_add_u64 v[34:35], s[70:71], 0, v[46:47]
	s_and_saveexec_b64 s[18:19], s[6:7]
	s_cbranch_execz .LBB0_441
	v_lshl_add_u64 v[40:41], v[0:1], 3, v[34:35]
	global_load_dwordx4 v[36:39], v[40:41], off offset:16
	global_load_dwordx4 v[48:51], v[40:41], off
	s_waitcnt vmcnt(0)
	v_mul_f32_e32 v40, v3, v49
	v_mul_f32_e32 v41, v3, v48
	s_nop 0
	v_fma_f32 v46, v2, v48, -v40
	v_fma_f32 v47, v2, v49, -v41
	v_fma_f32 v3, v2, v49, v41
	v_fma_f32 v2, v2, v48, v40
	v_mul_f32_e32 v40, v5, v51
	v_mul_f32_e32 v41, v5, v50
	v_mul_f32_e32 v2, v9, v39
	v_fma_f32 v48, v4, v50, -v40
	v_fma_f32 v49, v4, v51, -v41
	v_fma_f32 v5, v4, v51, v41
	v_fma_f32 v4, v4, v50, v40
	v_mul_f32_e32 v40, v7, v37
	v_mul_f32_e32 v41, v7, v36
	v_fma_f32 v52, v8, v38, -v2
	v_fma_f32 v53, v9, v39, -v2
	v_mul_f32_e32 v2, v9, v38
	v_fma_f32 v50, v6, v36, -v40
	v_fma_f32 v51, v6, v37, -v41
	v_fma_f32 v7, v6, v37, v41
	v_fma_f32 v6, v6, v36, v40
	v_fma_f32 v8, v8, v39, v2
	v_fma_f32 v9, v9, v38, v2
	v_mov_b32_e32 v47, v3
	v_mov_b32_e32 v49, v5
	v_mov_b32_e32 v51, v7
	v_mov_b32_e32 v53, v8
	v_mov_b64_e32 v[2:3], v[46:47]
	v_mov_b64_e32 v[4:5], v[48:49]
	v_mov_b64_e32 v[6:7], v[50:51]
	v_mov_b64_e32 v[8:9], v[52:53]
.LBB0_441:
	s_or_b64 exec, exec, s[18:19]
	s_and_b64 vcc, exec, s[8:9]
	s_cbranch_vccnz .LBB0_443
	v_mul_f32_e32 v45, 0xbfb8aa3b, v8
	v_mul_f32_e32 v36, 0xbfb8aa3b, v2
	v_mul_f32_e32 v37, 0xbfb8aa3b, v3
	v_mul_f32_e32 v38, 0xbfb8aa3b, v4
	v_mul_f32_e32 v39, 0xbfb8aa3b, v5
	v_mul_f32_e32 v40, 0xbfb8aa3b, v6
	v_mul_f32_e32 v41, 0xbfb8aa3b, v7
	v_exp_f32_e32 v45, v45
	v_mul_f32_e32 v46, 0xbfb8aa3b, v9
	v_exp_f32_e32 v36, v36
	v_exp_f32_e32 v37, v37
	v_exp_f32_e32 v38, v38
	v_exp_f32_e32 v39, v39
	v_exp_f32_e32 v40, v40
	v_exp_f32_e32 v41, v41
	v_exp_f32_e32 v47, v46
	v_add_f32_e32 v45, 1.0, v45
	v_add_f32_e32 v36, 1.0, v36
	v_add_f32_e32 v37, 1.0, v37
	v_add_f32_e32 v38, 1.0, v38
	v_add_f32_e32 v39, 1.0, v39
	v_add_f32_e32 v40, 1.0, v40
	v_add_f32_e32 v41, 1.0, v41
	v_rcp_f32_e32 v46, v45
	v_add_f32_e32 v45, 1.0, v47
	v_rcp_f32_e32 v36, v36
	v_rcp_f32_e32 v38, v38
	v_rcp_f32_e32 v40, v40
	v_rcp_f32_e32 v47, v45
	v_rcp_f32_e32 v41, v41
	v_rcp_f32_e32 v39, v39
	v_rcp_f32_e32 v37, v37
	v_mul_f32_e32 v8, v8, v46
	v_mul_f32_e32 v9, v9, v47
	v_mul_f32_e32 v6, v6, v40
	v_mul_f32_e32 v7, v7, v41
	v_mul_f32_e32 v4, v4, v38
	v_mul_f32_e32 v5, v5, v39
	v_mul_f32_e32 v2, v2, v36
	v_mul_f32_e32 v3, v3, v37

; __device__ __forceinline__ float silu_f(float x) { return x * __builtin_amdgcn_rcpf(1.0f + __builtin_amdgcn_exp2f(-x * 1.4426950408889634f)); }
; __device__ __forceinline__ void rope8(float (&v)[8], const tab_t* tp) {
;     const f32x4 t0 = *(const f32x4*)tp, t1 = *(const f32x4*)(tp + 2);
;     const float c[4] = {t0[0], t0[2], t1[0], t1[2]}, s[4] = {t0[1], t0[3], t1[1], t1[3]};
; #pragma unroll
;     for (int j = 0; j < 4; ++j) { const float a = v[2 * j], b = v[2 * j + 1]; v[2 * j] = a * c[j] - b * s[j]; v[2 * j + 1] = b * c[j] + a * s[j]; }
; }
;     __device__ __forceinline__ void operator()(const f32x4 (&acc)[2][2][4][2], const Unit& u, int wr, int wc, int fr, int fq) const {
;     ...
;                 const int row = row0 + ai * HALF + m * 16;
;                 const float r = __builtin_amdgcn_rsqf(sum_parts<8>(ssq_h + (size_t)row * 32) * (1.0f / 2048.0f) + 1e-6f);
; #pragma unroll
;                 for (int bj = 0; bj < 2; ++bj) {
;                     float v[8];
; #pragma unroll
;                     for (int e = 0; e < 4; ++e) { v[e] = acc[ai][bj][m][0][e] * r; v[4 + e] = acc[ai][bj][m][1][e] * r; }
;                     if (tab[bj] >= 0) rope8(v, TAB + (size_t)row * NTAB + tab[bj]);
;                     if (act[bj]) {
; #pragma unroll
;                         for (int e = 0; e < 8; ++e) v[e] = silu_f(v[e]);
;                     }
; #pragma unroll
;                     for (int e = 0; e < 8; ++e) v[e] *= sc[bj];
;                     if (ssq[bj]) { float s = 0.f;
; #pragma unroll
;                         for (int e = 0; e < 8; ++e) s += v[e] * v[e];
;                         s += __shfl_xor(s, 16); s += __shfl_xor(s, 32);
;                         if (fq == 0) ssq[bj][(size_t)row * sld[bj]] = s; }
;                     store8(dst[bj] + (size_t)row * ld[bj], v);
;                     asm volatile("" ::: "memory");
;                 }
.LBB0_447:
	v_mul_lo_u32 v7, s91, v42
	v_mul_lo_u32 v39, s90, v43
	s_waitcnt lgkmcnt(0)
	v_mad_u64_u32 v[8:9], s[18:19], s90, v42, 0
	v_add3_u32 v9, v9, v39, v7
	v_lshl_add_u64 v[8:9], v[8:9], 1, v[148:149]
	v_cvt_pk_bf16_f32 v36, v36, v38
	v_cvt_pk_bf16_f32 v37, v4, v37
	v_cvt_pk_bf16_f32 v38, v3, v5
	v_cvt_pk_bf16_f32 v39, v2, v6
	global_store_dwordx4 v[8:9], v[36:39], off
	v_mov_b32_e32 v45, v44
	v_mul_f32_e32 v2, v30, v44
	v_mul_f32_e32 v3, v31, v45
	v_mul_f32_e32 v6, v26, v44
	v_mul_f32_e32 v7, v27, v45
	v_mul_f32_e32 v4, v32, v44
	v_mul_f32_e32 v5, v33, v45
	v_mul_f32_e32 v8, v28, v44
	v_mul_f32_e32 v9, v29, v45
	s_and_saveexec_b64 s[18:19], s[10:11]
	s_cbranch_execz .LBB0_449
	v_mov_b32_e32 v145, v1
	v_lshl_add_u64 v[26:27], v[144:145], 3, v[34:35]
	global_load_dwordx4 v[32:35], v[26:27], off offset:16
	global_load_dwordx4 v[28:31], v[26:27], off
	s_waitcnt vmcnt(0)
	v_mul_f32_e32 v36, v3, v29
	v_mul_f32_e32 v37, v3, v28
	s_nop 0
	v_fma_f32 v26, v2, v28, -v36
	v_fma_f32 v27, v2, v29, -v37
	v_fma_f32 v3, v2, v29, v37
	v_fma_f32 v2, v2, v28, v36
	v_mul_f32_e32 v36, v5, v31
	v_mul_f32_e32 v37, v5, v30
	v_mul_f32_e32 v2, v9, v35
	v_fma_f32 v28, v4, v30, -v36
	v_fma_f32 v29, v4, v31, -v37
	v_fma_f32 v5, v4, v31, v37
	v_fma_f32 v4, v4, v30, v36
	v_mul_f32_e32 v36, v7, v33
	v_mul_f32_e32 v37, v7, v32
	v_mov_b32_e32 v27, v3
	v_fma_f32 v30, v6, v32, -v36
	v_fma_f32 v31, v6, v33, -v37
	v_fma_f32 v7, v6, v33, v37
	v_fma_f32 v6, v6, v32, v36
	v_fma_f32 v32, v8, v34, -v2
	v_fma_f32 v33, v9, v35, -v2
	v_mul_f32_e32 v2, v9, v34
	v_fma_f32 v8, v8, v35, v2
	v_fma_f32 v9, v9, v34, v2
	v_mov_b32_e32 v29, v5
	v_mov_b32_e32 v31, v7
	v_mov_b32_e32 v33, v8
	v_mov_b64_e32 v[2:3], v[26:27]
	v_mov_b64_e32 v[4:5], v[28:29]
	v_mov_b64_e32 v[6:7], v[30:31]
	v_mov_b64_e32 v[8:9], v[32:33]
.LBB0_449:
	s_or_b64 exec, exec, s[18:19]
	s_and_b64 vcc, exec, s[12:13]
	s_cbranch_vccnz .LBB0_451
	v_mul_f32_e32 v26, 0xbfb8aa3b, v2
	v_mul_f32_e32 v27, 0xbfb8aa3b, v3
	v_mul_f32_e32 v28, 0xbfb8aa3b, v4
	v_mul_f32_e32 v29, 0xbfb8aa3b, v5
	v_mul_f32_e32 v30, 0xbfb8aa3b, v6
	v_mul_f32_e32 v31, 0xbfb8aa3b, v7
	v_mul_f32_e32 v32, 0xbfb8aa3b, v8
	v_mul_f32_e32 v33, 0xbfb8aa3b, v9
	v_exp_f32_e32 v26, v26
	v_exp_f32_e32 v27, v27
	v_exp_f32_e32 v28, v28
	v_exp_f32_e32 v29, v29
	v_exp_f32_e32 v30, v30
	v_exp_f32_e32 v31, v31
	v_exp_f32_e32 v32, v32
	v_exp_f32_e32 v33, v33
	v_add_f32_e32 v26, 1.0, v26
	v_add_f32_e32 v27, 1.0, v27
	v_add_f32_e32 v28, 1.0, v28
	v_add_f32_e32 v29, 1.0, v29
	v_add_f32_e32 v30, 1.0, v30
	v_add_f32_e32 v31, 1.0, v31
	v_add_f32_e32 v32, 1.0, v32
	v_add_f32_e32 v33, 1.0, v33
	v_rcp_f32_e32 v26, v26
	v_rcp_f32_e32 v28, v28
	v_rcp_f32_e32 v30, v30
	v_rcp_f32_e32 v32, v32
	v_rcp_f32_e32 v33, v33
	v_rcp_f32_e32 v31, v31
	v_rcp_f32_e32 v29, v29
	v_rcp_f32_e32 v27, v27
	v_mul_f32_e32 v8, v8, v32
	v_mul_f32_e32 v9, v9, v33
	v_mul_f32_e32 v6, v6, v30
	v_mul_f32_e32 v7, v7, v31
	v_mul_f32_e32 v4, v4, v28
	v_mul_f32_e32 v5, v5, v29
	v_mul_f32_e32 v2, v2, v26
	v_mul_f32_e32 v3, v3, v27

; __device__ __forceinline__ float silu_f(float x) { return x * __builtin_amdgcn_rcpf(1.0f + __builtin_amdgcn_exp2f(-x * 1.4426950408889634f)); }
; __device__ __forceinline__ void rope8(float (&v)[8], const tab_t* tp) {
;     const f32x4 t0 = *(const f32x4*)tp, t1 = *(const f32x4*)(tp + 2);
;     const float c[4] = {t0[0], t0[2], t1[0], t1[2]}, s[4] = {t0[1], t0[3], t1[1], t1[3]};
; #pragma unroll
;     for (int j = 0; j < 4; ++j) { const float a = v[2 * j], b = v[2 * j + 1]; v[2 * j] = a * c[j] - b * s[j]; v[2 * j + 1] = b * c[j] + a * s[j]; }
; }
;     __device__ __forceinline__ void operator()(const f32x4 (&acc)[2][2][4][2], const Unit& u, int wr, int wc, int fr, int fq) const {
;     ...
;                 const int row = row0 + ai * HALF + m * 16;
;                 const float r = __builtin_amdgcn_rsqf(sum_parts<8>(ssq_h + (size_t)row * 32) * (1.0f / 2048.0f) + 1e-6f);
; #pragma unroll
;                 for (int bj = 0; bj < 2; ++bj) {
;                     float v[8];
; #pragma unroll
;                     for (int e = 0; e < 4; ++e) { v[e] = acc[ai][bj][m][0][e] * r; v[4 + e] = acc[ai][bj][m][1][e] * r; }
;                     if (tab[bj] >= 0) rope8(v, TAB + (size_t)row * NTAB + tab[bj]);
;                     if (act[bj]) {
; #pragma unroll
;                         for (int e = 0; e < 8; ++e) v[e] = silu_f(v[e]);
;                     }
; #pragma unroll
;                     for (int e = 0; e < 8; ++e) v[e] *= sc[bj];
;                     if (ssq[bj]) { float s = 0.f;
; #pragma unroll
;                         for (int e = 0; e < 8; ++e) s += v[e] * v[e];
;                         s += __shfl_xor(s, 16); s += __shfl_xor(s, 32);
;                         if (fq == 0) ssq[bj][(size_t)row * sld[bj]] = s; }
;                     store8(dst[bj] + (size_t)row * ld[bj], v);
;                     asm volatile("" ::: "memory");
;                 }
.LBB0_455:
	v_mul_lo_u32 v7, s93, v42
	v_mul_lo_u32 v29, s92, v43
	s_waitcnt lgkmcnt(0)
	v_mad_u64_u32 v[8:9], s[18:19], s92, v42, 0
	v_add3_u32 v9, v9, v29, v7
	v_lshl_add_u64 v[8:9], v[8:9], 1, v[122:123]
	v_cvt_pk_bf16_f32 v26, v26, v28
	v_cvt_pk_bf16_f32 v27, v4, v27
	v_cvt_pk_bf16_f32 v28, v3, v5
	v_cvt_pk_bf16_f32 v29, v2, v6
	global_store_dwordx4 v[8:9], v[26:29], off
	s_nop 1
	v_add_u32_e32 v26, 0xb0, v146
	v_ashrrev_i32_e32 v27, 31, v26
	v_mad_i64_i32 v[30:31], s[18:19], v26, s1, 0
	v_mov_b32_e32 v28, v175
	s_nop 0
	v_mul_f32_e32 v2, v22, v28
	v_mul_f32_e32 v3, v23, v28
	v_mul_f32_e32 v6, v18, v28
	v_mul_f32_e32 v7, v19, v28
	v_mul_f32_e32 v4, v24, v28
	v_mul_f32_e32 v5, v25, v28
	v_mul_f32_e32 v8, v20, v28
	v_mul_f32_e32 v9, v21, v28
	v_lshl_add_u64 v[18:19], s[70:71], 0, v[30:31]
	s_and_saveexec_b64 s[18:19], s[6:7]
	s_cbranch_execz .LBB0_457
	v_lshl_add_u64 v[24:25], v[0:1], 3, v[18:19]
	global_load_dwordx4 v[20:23], v[24:25], off offset:16
	global_load_dwordx4 v[32:35], v[24:25], off
	s_waitcnt vmcnt(1)
	v_mul_f32_e32 v0, v9, v23
	s_waitcnt vmcnt(0)
	v_mul_f32_e32 v24, v3, v33
	v_mul_f32_e32 v25, v3, v32
	v_fma_f32 v36, v8, v22, -v0
	v_fma_f32 v37, v9, v23, -v0
	v_fma_f32 v30, v2, v32, -v24
	v_fma_f32 v31, v2, v33, -v25
	v_fma_f32 v3, v2, v33, v25
	v_fma_f32 v2, v2, v32, v24
	v_mul_f32_e32 v24, v5, v35
	v_mul_f32_e32 v25, v5, v34
	v_mul_f32_e32 v0, v9, v22
	v_fma_f32 v32, v4, v34, -v24
	v_fma_f32 v33, v4, v35, -v25
	v_fma_f32 v5, v4, v35, v25
	v_fma_f32 v4, v4, v34, v24
	v_mul_f32_e32 v24, v7, v21
	v_mul_f32_e32 v25, v7, v20
	v_fma_f32 v8, v8, v23, v0
	v_fma_f32 v9, v9, v22, v0
	v_fma_f32 v34, v6, v20, -v24
	v_fma_f32 v35, v6, v21, -v25
	v_fma_f32 v7, v6, v21, v25
	v_fma_f32 v6, v6, v20, v24
	v_mov_b32_e32 v31, v3
	v_mov_b32_e32 v33, v5
	v_mov_b32_e32 v35, v7
	v_mov_b32_e32 v37, v8
	v_mov_b64_e32 v[2:3], v[30:31]
	v_mov_b64_e32 v[4:5], v[32:33]
	v_mov_b64_e32 v[6:7], v[34:35]
	v_mov_b64_e32 v[8:9], v[36:37]
.LBB0_457:
	s_or_b64 exec, exec, s[18:19]
	s_and_b64 vcc, exec, s[8:9]
	s_cbranch_vccnz .LBB0_459
	v_mul_f32_e32 v0, 0xbfb8aa3b, v2
	v_exp_f32_e32 v0, v0
	v_mul_f32_e32 v20, 0xbfb8aa3b, v3
	v_exp_f32_e32 v20, v20
	v_mul_f32_e32 v22, 0xbfb8aa3b, v5
	v_add_f32_e32 v0, 1.0, v0
	v_exp_f32_e32 v23, v22
	v_add_f32_e32 v21, 1.0, v20
	v_rcp_f32_e32 v20, v0
	v_mul_f32_e32 v0, 0xbfb8aa3b, v4
	v_exp_f32_e32 v0, v0
	v_mul_f32_e32 v22, 0xbfb8aa3b, v6
	v_exp_f32_e32 v24, v22
	v_mul_f32_e32 v25, 0xbfb8aa3b, v8
	v_add_f32_e32 v0, 1.0, v0
	v_rcp_f32_e32 v22, v0
	v_add_f32_e32 v0, 1.0, v23
	v_add_f32_e32 v23, 1.0, v24
	v_rcp_f32_e32 v24, v23
	v_mul_f32_e32 v23, 0xbfb8aa3b, v7
	v_exp_f32_e32 v25, v25
	v_mul_f32_e32 v29, 0xbfb8aa3b, v9
	v_exp_f32_e32 v23, v23
	v_exp_f32_e32 v29, v29
	v_add_f32_e32 v25, 1.0, v25
	v_rcp_f32_e32 v30, v25
	v_add_f32_e32 v23, 1.0, v23
	v_add_f32_e32 v25, 1.0, v29
	v_rcp_f32_e32 v31, v25
	v_rcp_f32_e32 v25, v23
	v_rcp_f32_e32 v23, v0
	v_rcp_f32_e32 v21, v21
	v_mul_f32_e32 v8, v8, v30
	v_mul_f32_e32 v9, v9, v31
	v_mul_f32_e32 v6, v6, v24
	v_mul_f32_e32 v7, v7, v25
	v_mul_f32_e32 v4, v4, v22
	v_mul_f32_e32 v5, v5, v23
	v_mul_f32_e32 v2, v2, v20
	v_mul_f32_e32 v3, v3, v21

; __device__ __forceinline__ float silu_f(float x) { return x * __builtin_amdgcn_rcpf(1.0f + __builtin_amdgcn_exp2f(-x * 1.4426950408889634f)); }
; __device__ __forceinline__ void rope8(float (&v)[8], const tab_t* tp) {
;     const f32x4 t0 = *(const f32x4*)tp, t1 = *(const f32x4*)(tp + 2);
;     const float c[4] = {t0[0], t0[2], t1[0], t1[2]}, s[4] = {t0[1], t0[3], t1[1], t1[3]};
; #pragma unroll
;     for (int j = 0; j < 4; ++j) { const float a = v[2 * j], b = v[2 * j + 1]; v[2 * j] = a * c[j] - b * s[j]; v[2 * j + 1] = b * c[j] + a * s[j]; }
; }
;     __device__ __forceinline__ void operator()(const f32x4 (&acc)[2][2][4][2], const Unit& u, int wr, int wc, int fr, int fq) const {
;     ...
;                 const int row = row0 + ai * HALF + m * 16;
;                 const float r = __builtin_amdgcn_rsqf(sum_parts<8>(ssq_h + (size_t)row * 32) * (1.0f / 2048.0f) + 1e-6f);
; #pragma unroll
;                 for (int bj = 0; bj < 2; ++bj) {
;                     float v[8];
; #pragma unroll
;                     for (int e = 0; e < 4; ++e) { v[e] = acc[ai][bj][m][0][e] * r; v[4 + e] = acc[ai][bj][m][1][e] * r; }
;                     if (tab[bj] >= 0) rope8(v, TAB + (size_t)row * NTAB + tab[bj]);
;                     if (act[bj]) {
; #pragma unroll
;                         for (int e = 0; e < 8; ++e) v[e] = silu_f(v[e]);
;                     }
; #pragma unroll
;                     for (int e = 0; e < 8; ++e) v[e] *= sc[bj];
;                     if (ssq[bj]) { float s = 0.f;
; #pragma unroll
;                         for (int e = 0; e < 8; ++e) s += v[e] * v[e];
;                         s += __shfl_xor(s, 16); s += __shfl_xor(s, 32);
;                         if (fq == 0) ssq[bj][(size_t)row * sld[bj]] = s; }
;                     store8(dst[bj] + (size_t)row * ld[bj], v);
;                     asm volatile("" ::: "memory");
;                 }
.LBB0_463:
	v_mul_lo_u32 v7, s91, v26
	v_mul_lo_u32 v22, s90, v27
	s_waitcnt lgkmcnt(0)
	v_mad_u64_u32 v[8:9], s[6:7], s90, v26, 0
	v_add3_u32 v9, v9, v22, v7
	v_lshl_add_u64 v[8:9], v[8:9], 1, v[148:149]
	v_cvt_pk_bf16_f32 v20, v20, v21
	v_cvt_pk_bf16_f32 v21, v3, v5
	v_cvt_pk_bf16_f32 v22, v2, v4
	v_cvt_pk_bf16_f32 v23, v0, v6
	global_store_dwordx4 v[8:9], v[20:23], off
	v_mov_b32_e32 v29, v28
	v_mul_f32_e32 v2, v14, v28
	v_mul_f32_e32 v3, v15, v29
	v_mul_f32_e32 v6, v10, v28
	v_mul_f32_e32 v7, v11, v29
	v_mul_f32_e32 v4, v16, v28
	v_mul_f32_e32 v5, v17, v29
	v_mul_f32_e32 v8, v12, v28
	v_mul_f32_e32 v9, v13, v29
	s_and_saveexec_b64 s[6:7], s[10:11]
	s_cbranch_execz .LBB0_465
	v_mov_b32_e32 v145, v1
	v_lshl_add_u64 v[10:11], v[144:145], 3, v[18:19]
	global_load_dwordx4 v[16:19], v[10:11], off offset:16
	global_load_dwordx4 v[12:15], v[10:11], off
	s_waitcnt vmcnt(1)
	v_mul_f32_e32 v0, v9, v19
	s_waitcnt vmcnt(0)
	v_mul_f32_e32 v20, v3, v13
	v_mul_f32_e32 v21, v3, v12
	s_nop 0
	v_fma_f32 v10, v2, v12, -v20
	v_fma_f32 v11, v2, v13, -v21
	v_fma_f32 v3, v2, v13, v21
	v_fma_f32 v2, v2, v12, v20
	v_mul_f32_e32 v20, v5, v15
	v_mul_f32_e32 v21, v5, v14
	v_mov_b32_e32 v11, v3
	v_fma_f32 v12, v4, v14, -v20
	v_fma_f32 v13, v4, v15, -v21
	v_fma_f32 v5, v4, v15, v21
	v_fma_f32 v4, v4, v14, v20
	v_mul_f32_e32 v20, v7, v17
	v_mul_f32_e32 v21, v7, v16
	v_mov_b32_e32 v13, v5
	v_fma_f32 v14, v6, v16, -v20
	v_fma_f32 v15, v6, v17, -v21
	v_fma_f32 v7, v6, v17, v21
	v_fma_f32 v6, v6, v16, v20
	v_fma_f32 v16, v8, v18, -v0
	v_fma_f32 v17, v9, v19, -v0
	v_mul_f32_e32 v0, v9, v18
	v_fma_f32 v8, v8, v19, v0
	v_fma_f32 v9, v9, v18, v0
	v_mov_b32_e32 v15, v7
	v_mov_b32_e32 v17, v8
	v_mov_b64_e32 v[2:3], v[10:11]
	v_mov_b64_e32 v[4:5], v[12:13]
	v_mov_b64_e32 v[6:7], v[14:15]
	v_mov_b64_e32 v[8:9], v[16:17]
.LBB0_465:
	s_or_b64 exec, exec, s[6:7]
	s_and_b64 vcc, exec, s[12:13]
	v_readlane_b32 s90, v254, 62
	v_readlane_b32 s91, v254, 63
	s_cbranch_vccnz .LBB0_467
	v_mul_f32_e32 v0, 0xbfb8aa3b, v2
	v_exp_f32_e32 v0, v0
	v_mul_f32_e32 v10, 0xbfb8aa3b, v3
	v_exp_f32_e32 v10, v10
	v_mul_f32_e32 v12, 0xbfb8aa3b, v5
	v_add_f32_e32 v0, 1.0, v0
	v_exp_f32_e32 v13, v12
	v_add_f32_e32 v11, 1.0, v10
	v_rcp_f32_e32 v10, v0
	v_mul_f32_e32 v0, 0xbfb8aa3b, v4
	v_exp_f32_e32 v0, v0
	v_mul_f32_e32 v12, 0xbfb8aa3b, v6
	v_exp_f32_e32 v14, v12
	v_mul_f32_e32 v15, 0xbfb8aa3b, v8
	v_add_f32_e32 v0, 1.0, v0
	v_rcp_f32_e32 v12, v0
	v_add_f32_e32 v0, 1.0, v13
	v_add_f32_e32 v13, 1.0, v14
	v_rcp_f32_e32 v14, v13
	v_mul_f32_e32 v13, 0xbfb8aa3b, v7
	v_exp_f32_e32 v15, v15
	v_mul_f32_e32 v16, 0xbfb8aa3b, v9
	v_exp_f32_e32 v13, v13
	v_exp_f32_e32 v17, v16
	v_add_f32_e32 v15, 1.0, v15
	v_rcp_f32_e32 v16, v15
	v_add_f32_e32 v13, 1.0, v13
	v_add_f32_e32 v15, 1.0, v17
	v_rcp_f32_e32 v17, v15
	v_rcp_f32_e32 v15, v13
	v_rcp_f32_e32 v13, v0
	v_rcp_f32_e32 v11, v11
	v_mul_f32_e32 v8, v8, v16
	v_mul_f32_e32 v9, v9, v17
	v_mul_f32_e32 v6, v6, v14
	v_mul_f32_e32 v7, v7, v15
	v_mul_f32_e32 v4, v4, v12
	v_mul_f32_e32 v5, v5, v13
	v_mul_f32_e32 v2, v2, v10
	v_mul_f32_e32 v3, v3, v11

;     ...
;                 for (int grp = bx * 8 + wave; grp < TOK / 16; grp += G * 8) {
;                     const bf16* pa = HB + (size_t)(grp * 16 + (lane & 15)) * DM + 8 * (lane >> 4);
;                     const bf16* pb = W8T + ((size_t)L * 16 + (lane & 15)) * DM + 8 * (lane >> 4);
;                     f32x4 acc = (f32x4){0.f, 0.f, 0.f, 0.f};
; #pragma unroll 16
;                     for (int s = 0; s < DM / 32; ++s) acc = __builtin_amdgcn_mfma_f32_16x16x32_bf16(*(const att::bf16x8*)(pa + 32 * s), *(const att::bf16x8*)(pb + 32 * s), acc, 0, 0, 0);
.LBB0_526:
	v_lshl_add_u64 v[16:17], v[14:15], 0, s[0:1]
	v_add_co_u32_e32 v16, vcc, 0xe510000, v16
	v_lshl_add_u64 v[18:19], v[12:13], 0, s[0:1]
	s_nop 0
	v_addc_co_u32_e32 v17, vcc, 0, v17, vcc
	global_load_dwordx4 v[22:25], v[16:17], off
	global_load_dwordx4 v[26:29], v[18:19], off offset:-512
	s_add_u32 s0, s0, 0x400
	s_addc_u32 s1, s1, 0
	s_cmpk_eq_i32 s0, 0x1000
	s_waitcnt vmcnt(0)
	v_mfma_f32_16x16x32_bf16 v[2:5], v[22:25], v[26:29], v[2:5]
	global_load_dwordx4 v[22:25], v[16:17], off offset:64
	global_load_dwordx4 v[26:29], v[18:19], off offset:-448
	s_waitcnt vmcnt(0)
	v_mfma_f32_16x16x32_bf16 v[2:5], v[22:25], v[26:29], v[2:5]
	global_load_dwordx4 v[22:25], v[16:17], off offset:128
	global_load_dwordx4 v[26:29], v[18:19], off offset:-384
	s_waitcnt vmcnt(0)
	v_mfma_f32_16x16x32_bf16 v[2:5], v[22:25], v[26:29], v[2:5]
	global_load_dwordx4 v[22:25], v[16:17], off offset:192
	global_load_dwordx4 v[26:29], v[18:19], off offset:-320
	s_waitcnt vmcnt(0)
	v_mfma_f32_16x16x32_bf16 v[2:5], v[22:25], v[26:29], v[2:5]
	global_load_dwordx4 v[22:25], v[16:17], off offset:256
	global_load_dwordx4 v[26:29], v[18:19], off offset:-256
	s_waitcnt vmcnt(0)
	v_mfma_f32_16x16x32_bf16 v[2:5], v[22:25], v[26:29], v[2:5]
	global_load_dwordx4 v[22:25], v[16:17], off offset:320
	global_load_dwordx4 v[26:29], v[18:19], off offset:-192
	s_waitcnt vmcnt(0)
	v_mfma_f32_16x16x32_bf16 v[2:5], v[22:25], v[26:29], v[2:5]
	global_load_dwordx4 v[22:25], v[16:17], off offset:384
	global_load_dwordx4 v[26:29], v[18:19], off offset:-128
	s_waitcnt vmcnt(0)
	v_mfma_f32_16x16x32_bf16 v[2:5], v[22:25], v[26:29], v[2:5]
	global_load_dwordx4 v[22:25], v[16:17], off offset:448
	global_load_dwordx4 v[26:29], v[18:19], off offset:-64
	s_waitcnt vmcnt(0)
	v_mfma_f32_16x16x32_bf16 v[2:5], v[22:25], v[26:29], v[2:5]
	global_load_dwordx4 v[22:25], v[16:17], off offset:512
	global_load_dwordx4 v[26:29], v[18:19], off
	s_waitcnt vmcnt(0)
	v_mfma_f32_16x16x32_bf16 v[2:5], v[22:25], v[26:29], v[2:5]
	global_load_dwordx4 v[22:25], v[16:17], off offset:576
	global_load_dwordx4 v[26:29], v[18:19], off offset:64
	s_waitcnt vmcnt(0)
	v_mfma_f32_16x16x32_bf16 v[2:5], v[22:25], v[26:29], v[2:5]
	global_load_dwordx4 v[22:25], v[16:17], off offset:640
	global_load_dwordx4 v[26:29], v[18:19], off offset:128
	s_waitcnt vmcnt(0)
	v_mfma_f32_16x16x32_bf16 v[2:5], v[22:25], v[26:29], v[2:5]
	global_load_dwordx4 v[22:25], v[16:17], off offset:704
	global_load_dwordx4 v[26:29], v[18:19], off offset:192
	s_waitcnt vmcnt(0)
	v_mfma_f32_16x16x32_bf16 v[2:5], v[22:25], v[26:29], v[2:5]
	global_load_dwordx4 v[22:25], v[16:17], off offset:768
	global_load_dwordx4 v[26:29], v[18:19], off offset:256
	s_waitcnt vmcnt(0)
	v_mfma_f32_16x16x32_bf16 v[2:5], v[22:25], v[26:29], v[2:5]
	global_load_dwordx4 v[22:25], v[16:17], off offset:832
	global_load_dwordx4 v[26:29], v[18:19], off offset:320
	s_waitcnt vmcnt(0)
	v_mfma_f32_16x16x32_bf16 v[2:5], v[22:25], v[26:29], v[2:5]
	global_load_dwordx4 v[22:25], v[16:17], off offset:896
	global_load_dwordx4 v[26:29], v[18:19], off offset:384
	s_waitcnt vmcnt(0)
	v_mfma_f32_16x16x32_bf16 v[2:5], v[22:25], v[26:29], v[2:5]
	global_load_dwordx4 v[22:25], v[16:17], off offset:960
	s_nop 0
	global_load_dwordx4 v[16:19], v[18:19], off offset:448
	s_waitcnt vmcnt(0)
	v_mfma_f32_16x16x32_bf16 v[2:5], v[22:25], v[16:19], v[2:5]
	s_cbranch_scc0 .LBB0_526
	s_and_saveexec_b64 s[0:1], s[2:3]
	s_cbranch_execz .LBB0_524
; template <int N4> __device__ __forceinline__ float sum_parts(const float* p) {
;     f32x4 a = *(const f32x4*)p;
; #pragma unroll
;     for (int i = 1; i < N4; ++i) a += *(const f32x4*)(p + 4 * i);
;     return (a[0] + a[1]) + (a[2] + a[3]);
; }
;     ...
;                     if ((lane & 15) < 8) {
; #pragma unroll
;                         for (int i = 0; i < 4; ++i) { const int row = grp * 16 + 4 * (lane >> 4) + i;
;                             const float r = __builtin_amdgcn_rsqf(pg8::sum_parts<8>(ssqh + (size_t)row * 32) * (1.0f / 2048.0f) + 1e-6f);
;                             WIDX[(size_t)row * 8 + (lane & 15)] = acc[i] * r; }
;                     }
	v_lshl_or_b32 v14, s4, 4, v20
	v_ashrrev_i32_e32 v15, 31, v14
	v_lshlrev_b64 v[16:17], 7, v[14:15]
	v_lshl_add_u64 v[34:35], s[22:23], 0, v[16:17]
	global_load_dwordx4 v[16:19], v[34:35], off offset:48
	global_load_dwordx4 v[22:25], v[34:35], off offset:32
	global_load_dwordx4 v[26:29], v[34:35], off
	global_load_dwordx4 v[30:33], v[34:35], off offset:16
	s_waitcnt vmcnt(0)
	v_add_f32_e32 v28, v28, v32
	v_add_f32_e32 v29, v29, v33
	v_add_f32_e32 v26, v26, v30
	v_add_f32_e32 v27, v27, v31
	v_add_f32_e32 v24, v28, v24
	v_add_f32_e32 v25, v29, v25
	v_add_f32_e32 v22, v26, v22
	v_add_f32_e32 v23, v27, v23
	v_add_f32_e32 v36, v24, v18
	v_add_f32_e32 v37, v25, v19
	v_add_f32_e32 v38, v22, v16
	v_add_f32_e32 v39, v23, v17
	global_load_dwordx4 v[16:19], v[34:35], off offset:112
	global_load_dwordx4 v[22:25], v[34:35], off offset:96
	global_load_dwordx4 v[26:29], v[34:35], off offset:80
	global_load_dwordx4 v[30:33], v[34:35], off offset:64
	v_or_b32_e32 v34, 1, v14
	v_ashrrev_i32_e32 v35, 31, v34
	s_waitcnt vmcnt(0)
	v_add_f32_e32 v32, v36, v32
	v_add_f32_e32 v33, v37, v33
	v_add_f32_e32 v30, v38, v30
	v_add_f32_e32 v31, v39, v31
	v_add_f32_e32 v28, v32, v28
	v_add_f32_e32 v29, v33, v29
	v_add_f32_e32 v26, v30, v26
	v_add_f32_e32 v27, v31, v27
	v_add_f32_e32 v24, v28, v24
	v_add_f32_e32 v25, v29, v25
	v_add_f32_e32 v22, v26, v22
	v_add_f32_e32 v23, v27, v23
	v_add_f32_e32 v18, v24, v18
	v_add_f32_e32 v19, v25, v19
	v_add_f32_e32 v16, v22, v16
	v_add_f32_e32 v17, v23, v17
	v_add_f32_e32 v11, v18, v19
	v_add_f32_e32 v0, v16, v17
	v_add_f32_e32 v0, v0, v11
	v_fmamk_f32 v0, v0, 0x3a000000, v204
	v_rsq_f32_e32 v0, v0
	v_lshlrev_b64 v[16:17], 5, v[14:15]
	v_lshl_add_u64 v[16:17], v[6:7], 0, v[16:17]
	v_mul_f32_e32 v0, v2, v0
	global_store_dword v[16:17], v0, off
	v_lshlrev_b64 v[16:17], 7, v[34:35]
	v_lshl_add_u64 v[36:37], s[22:23], 0, v[16:17]
	global_load_dwordx4 v[16:19], v[36:37], off offset:48
	global_load_dwordx4 v[22:25], v[36:37], off offset:32
	global_load_dwordx4 v[26:29], v[36:37], off
	global_load_dwordx4 v[30:33], v[36:37], off offset:16
	s_waitcnt vmcnt(0)
	v_add_f32_e32 v28, v28, v32
	v_add_f32_e32 v29, v29, v33
	v_add_f32_e32 v26, v26, v30
	v_add_f32_e32 v27, v27, v31
	v_add_f32_e32 v24, v28, v24
	v_add_f32_e32 v25, v29, v25
	v_add_f32_e32 v22, v26, v22
	v_add_f32_e32 v23, v27, v23
	v_add_f32_e32 v38, v24, v18
	v_add_f32_e32 v39, v25, v19
	v_add_f32_e32 v40, v22, v16
	v_add_f32_e32 v41, v23, v17
	global_load_dwordx4 v[16:19], v[36:37], off offset:112
	global_load_dwordx4 v[22:25], v[36:37], off offset:96
	global_load_dwordx4 v[26:29], v[36:37], off offset:80
	global_load_dwordx4 v[30:33], v[36:37], off offset:64
	s_waitcnt vmcnt(0)
	v_add_f32_e32 v32, v38, v32
	v_add_f32_e32 v33, v39, v33
	v_add_f32_e32 v30, v40, v30
	v_add_f32_e32 v31, v41, v31
	v_add_f32_e32 v28, v32, v28
	v_add_f32_e32 v29, v33, v29
	v_add_f32_e32 v26, v30, v26
	v_add_f32_e32 v27, v31, v27
	v_add_f32_e32 v24, v28, v24
	v_add_f32_e32 v25, v29, v25
	v_add_f32_e32 v22, v26, v22
	v_add_f32_e32 v23, v27, v23
	v_add_f32_e32 v18, v24, v18
	v_add_f32_e32 v19, v25, v19
	v_add_f32_e32 v16, v22, v16
	v_add_f32_e32 v17, v23, v17
	v_add_f32_e32 v2, v18, v19
	v_add_f32_e32 v0, v16, v17
	v_add_f32_e32 v0, v0, v2
	v_fmamk_f32 v0, v0, 0x3a000000, v204
	v_rsq_f32_e32 v0, v0
	s_nop 0
	v_mul_f32_e32 v0, v3, v0
	v_lshlrev_b64 v[2:3], 5, v[34:35]
	v_lshl_add_u64 v[2:3], v[6:7], 0, v[2:3]
	global_store_dword v[2:3], v0, off
	v_or_b32_e32 v2, 2, v14
	v_ashrrev_i32_e32 v3, 31, v2
	v_lshlrev_b64 v[16:17], 7, v[2:3]
	v_lshl_add_u64 v[34:35], s[22:23], 0, v[16:17]
	global_load_dwordx4 v[16:19], v[34:35], off offset:48
	global_load_dwordx4 v[22:25], v[34:35], off offset:32
	global_load_dwordx4 v[26:29], v[34:35], off
	global_load_dwordx4 v[30:33], v[34:35], off offset:16
	v_lshlrev_b64 v[2:3], 5, v[2:3]
	v_lshl_add_u64 v[2:3], v[6:7], 0, v[2:3]
	s_waitcnt vmcnt(0)
	v_add_f32_e32 v28, v28, v32
	v_add_f32_e32 v29, v29, v33
	v_add_f32_e32 v26, v26, v30
	v_add_f32_e32 v27, v27, v31
	v_add_f32_e32 v24, v28, v24
	v_add_f32_e32 v25, v29, v25
	v_add_f32_e32 v22, v26, v22
	v_add_f32_e32 v23, v27, v23
	v_add_f32_e32 v36, v24, v18
	v_add_f32_e32 v37, v25, v19
	v_add_f32_e32 v38, v22, v16
	v_add_f32_e32 v39, v23, v17
	global_load_dwordx4 v[16:19], v[34:35], off offset:112
	global_load_dwordx4 v[22:25], v[34:35], off offset:96
	global_load_dwordx4 v[26:29], v[34:35], off offset:80
	global_load_dwordx4 v[30:33], v[34:35], off offset:64
	s_waitcnt vmcnt(0)
	v_add_f32_e32 v32, v36, v32
	v_add_f32_e32 v33, v37, v33
	v_add_f32_e32 v30, v38, v30
	v_add_f32_e32 v31, v39, v31
	v_add_f32_e32 v28, v32, v28
	v_add_f32_e32 v29, v33, v29
	v_add_f32_e32 v26, v30, v26
	v_add_f32_e32 v27, v31, v27
	v_add_f32_e32 v24, v28, v24
	v_add_f32_e32 v25, v29, v25
	v_add_f32_e32 v22, v26, v22
	v_add_f32_e32 v23, v27, v23
	v_add_f32_e32 v18, v24, v18
	v_add_f32_e32 v19, v25, v19
	v_add_f32_e32 v16, v22, v16
	v_add_f32_e32 v17, v23, v17
	v_add_f32_e32 v11, v18, v19
	v_add_f32_e32 v0, v16, v17
	v_add_f32_e32 v0, v0, v11
	v_fmamk_f32 v0, v0, 0x3a000000, v204
	v_rsq_f32_e32 v0, v0
	s_nop 0
	v_mul_f32_e32 v0, v4, v0
	global_store_dword v[2:3], v0, off
	v_or_b32_e32 v2, 3, v14
	v_ashrrev_i32_e32 v3, 31, v2
	v_lshlrev_b64 v[14:15], 7, v[2:3]
	v_lshl_add_u64 v[18:19], s[22:23], 0, v[14:15]
	global_load_dwordx4 v[14:17], v[18:19], off offset:48
	global_load_dwordx4 v[22:25], v[18:19], off offset:32
	global_load_dwordx4 v[26:29], v[18:19], off
	global_load_dwordx4 v[30:33], v[18:19], off offset:16
	v_lshlrev_b64 v[2:3], 5, v[2:3]
	v_lshl_add_u64 v[2:3], v[6:7], 0, v[2:3]
	s_waitcnt vmcnt(0)
	v_add_f32_e32 v28, v28, v32
	v_add_f32_e32 v29, v29, v33
	v_add_f32_e32 v26, v26, v30
	v_add_f32_e32 v27, v27, v31
	v_add_f32_e32 v24, v28, v24
	v_add_f32_e32 v25, v29, v25
	v_add_f32_e32 v22, v26, v22
	v_add_f32_e32 v23, v27, v23
	v_add_f32_e32 v34, v24, v16
	v_add_f32_e32 v35, v25, v17
	v_add_f32_e32 v36, v22, v14
	v_add_f32_e32 v37, v23, v15
	global_load_dwordx4 v[14:17], v[18:19], off offset:112
	global_load_dwordx4 v[22:25], v[18:19], off offset:96
	global_load_dwordx4 v[26:29], v[18:19], off offset:80
	global_load_dwordx4 v[30:33], v[18:19], off offset:64
	s_waitcnt vmcnt(0)
	v_add_f32_e32 v18, v34, v32
	v_add_f32_e32 v19, v35, v33
	v_add_f32_e32 v30, v36, v30
	v_add_f32_e32 v31, v37, v31
	v_add_f32_e32 v18, v18, v28
	v_add_f32_e32 v19, v19, v29
	v_add_f32_e32 v26, v30, v26
	v_add_f32_e32 v27, v31, v27
	v_add_f32_e32 v18, v18, v24
	v_add_f32_e32 v19, v19, v25
	v_add_f32_e32 v22, v26, v22
	v_add_f32_e32 v23, v27, v23
	v_add_f32_e32 v16, v18, v16
	v_add_f32_e32 v17, v19, v17
	v_add_f32_e32 v14, v22, v14
	v_add_f32_e32 v15, v23, v15
	v_add_f32_e32 v4, v16, v17
	v_add_f32_e32 v0, v14, v15
	v_add_f32_e32 v0, v0, v4
	v_fmamk_f32 v0, v0, 0x3a000000, v204
	v_rsq_f32_e32 v0, v0
	s_nop 0
	v_mul_f32_e32 v0, v5, v0
	global_store_dword v[2:3], v0, off
	s_branch .LBB0_524

; template <int N4> __device__ __forceinline__ float sum_parts(const float* p) {
;     f32x4 a = *(const f32x4*)p;
; #pragma unroll
;     for (int i = 1; i < N4; ++i) a += *(const f32x4*)(p + 4 * i);
;     return (a[0] + a[1]) + (a[2] + a[3]);
; }
;     __device__ __forceinline__ void operator()(const f32x4 (&acc)[2][2][4][2], const Unit& u, int wr, int wc, int fr, int fq) const {
;         { const int t_ = opaque_tid(), w_ = __builtin_amdgcn_readfirstlane(t_ >> 6), l_ = t_ & 63; wr = w_ >> 2; wc = w_ & 3; fr = l_ & 15; fq = l_ >> 4; }
;         const int row0 = u.pm * BM + wr * 64 + fr;
; #pragma unroll
;         for (int bj = 0; bj < 2; ++bj) { const int n = u.pn * BM + bj * HALF + wc * 32 + fq * 8;
;             if (n < NUQ) {
; #pragma unroll
;             for (int ai = 0; ai < 2; ++ai)
; #pragma unroll
;                 for (int m = 0; m < 4; ++m) { const int row = row0 + ai * HALF + m * 16;
;                     const float r = __builtin_amdgcn_rsqf(sum_parts<3>(ssq + (size_t)row * 12) * (1.0f / 384.0f) + 1e-6f) * SC_A; float v[8];
.LBB0_595:
	s_getreg_b32 s22, hwreg(HW_REG_HW_ID, 0, 6)
	s_lshl_b32 s22, s22, 2
	s_and_b32 s22, s22, 0xfc
	s_add_i32 s22, s22, 0x20040
	v_mov_b32_e32 v136, s22
	ds_read_b32 v136, v136
	v_mov_b32_e32 v137, 0
	s_waitcnt lgkmcnt(0)
	v_readfirstlane_b32 s22, v136
	v_mbcnt_lo_u32_b32 v137, -1, v137
	v_mbcnt_hi_u32_b32 v137, -1, v137
	v_lshl_or_b32 v136, s22, 6, v137
	s_nop 0
	v_readfirstlane_b32 s22, v136
	s_ashr_i32 s23, s22, 2
	s_lshr_b32 s22, s22, 1
	s_andn2_b32 s23, s23, 63
	s_and_b32 s22, s22, 0x60
	v_lshrrev_b32_e32 v136, 1, v137
	v_and_or_b32 v136, v136, 24, s22
	v_and_or_b32 v137, v137, 15, s23
	v_lshl_add_u32 v147, s50, 8, v137
	v_lshl_or_b32 v136, s33, 8, v136
	s_movk_i32 s22, 0x480
	v_cmp_gt_i32_e32 vcc, s22, v136
	v_ashrrev_i32_e32 v137, 31, v136
	v_or_b32_e32 v146, 16, v147
	v_or_b32_e32 v145, 32, v147
	v_or_b32_e32 v144, 48, v147
	v_add_u32_e32 v143, 0x80, v147
	v_add_u32_e32 v142, 0x90, v147
	v_add_u32_e32 v141, 0xa0, v147
	v_add_u32_e32 v140, 0xb0, v147
	v_mad_i64_i32 v[218:219], s[24:25], v147, 48, s[6:7]
	global_load_dwordx4 v[168:171], v[218:219], off offset:32
	global_load_dwordx4 v[160:163], v[218:219], off
	global_load_dwordx4 v[164:167], v[218:219], off offset:16
	v_mad_i64_i32 v[220:221], s[24:25], v146, 48, s[6:7]
	global_load_dwordx4 v[180:183], v[220:221], off offset:32
	global_load_dwordx4 v[172:175], v[220:221], off
	global_load_dwordx4 v[176:179], v[220:221], off offset:16
	v_mad_i64_i32 v[222:223], s[24:25], v145, 48, s[6:7]
	global_load_dwordx4 v[192:195], v[222:223], off offset:32
	global_load_dwordx4 v[184:187], v[222:223], off
	global_load_dwordx4 v[188:191], v[222:223], off offset:16
	v_mad_i64_i32 v[224:225], s[24:25], v144, 48, s[6:7]
	global_load_dwordx4 v[238:241], v[224:225], off offset:32
	global_load_dwordx4 v[196:199], v[224:225], off
	global_load_dwordx4 v[234:237], v[224:225], off offset:16
	s_waitcnt vmcnt(0)
	v_add_f32_e32 v162, v162, v166
	v_add_f32_e32 v163, v163, v167
	v_add_f32_e32 v160, v160, v164
	v_add_f32_e32 v161, v161, v165
	v_add_f32_e32 v162, v162, v170
	v_add_f32_e32 v163, v163, v171
	v_add_f32_e32 v160, v160, v168
	v_add_f32_e32 v161, v161, v169
	v_add_f32_e32 v160, v161, v160
	v_add_f32_e32 v162, v162, v163
	v_add_f32_e32 v226, v160, v162
	v_fmamk_f32 v226, v226, 0x3b2aaaab, v204
	v_add_f32_e32 v174, v174, v178
	v_add_f32_e32 v175, v175, v179
	v_add_f32_e32 v172, v172, v176
	v_add_f32_e32 v173, v173, v177
	v_add_f32_e32 v174, v174, v182
	v_add_f32_e32 v175, v175, v183
	v_add_f32_e32 v172, v172, v180
	v_add_f32_e32 v173, v173, v181
	v_add_f32_e32 v172, v173, v172
	v_add_f32_e32 v174, v174, v175
	v_add_f32_e32 v227, v172, v174
	v_fmamk_f32 v227, v227, 0x3b2aaaab, v204
	v_add_f32_e32 v186, v186, v190
	v_add_f32_e32 v187, v187, v191
	v_add_f32_e32 v184, v184, v188
	v_add_f32_e32 v185, v185, v189
	v_add_f32_e32 v186, v186, v194
	v_add_f32_e32 v187, v187, v195
	v_add_f32_e32 v184, v184, v192
	v_add_f32_e32 v185, v185, v193
	v_add_f32_e32 v184, v185, v184
	v_add_f32_e32 v186, v186, v187
	v_add_f32_e32 v228, v184, v186
	v_fmamk_f32 v228, v228, 0x3b2aaaab, v204
	v_add_f32_e32 v198, v198, v236
	v_add_f32_e32 v199, v199, v237
	v_add_f32_e32 v196, v196, v234
	v_add_f32_e32 v197, v197, v235
	v_add_f32_e32 v198, v198, v240
	v_add_f32_e32 v199, v199, v241
	v_add_f32_e32 v196, v196, v238
	v_add_f32_e32 v197, v197, v239
	v_add_f32_e32 v196, v197, v196
	v_add_f32_e32 v198, v198, v199
	v_add_f32_e32 v229, v196, v198
	v_fmamk_f32 v229, v229, 0x3b2aaaab, v204
	v_rsq_f32_e32 v226, v226
	v_rsq_f32_e32 v227, v227
	v_rsq_f32_e32 v228, v228
	v_rsq_f32_e32 v229, v229
	s_nop 0
	v_mul_f32_e32 v226, 0x3dd53b94, v226
	v_mul_f32_e32 v227, 0x3dd53b94, v227
	v_mul_f32_e32 v228, 0x3dd53b94, v228
	v_mul_f32_e32 v229, 0x3dd53b94, v229
	v_mad_i64_i32 v[218:219], s[24:25], v143, 48, s[6:7]
	global_load_dwordx4 v[168:171], v[218:219], off offset:32
	global_load_dwordx4 v[160:163], v[218:219], off
	global_load_dwordx4 v[164:167], v[218:219], off offset:16
	v_mad_i64_i32 v[220:221], s[24:25], v142, 48, s[6:7]
	global_load_dwordx4 v[180:183], v[220:221], off offset:32
	global_load_dwordx4 v[172:175], v[220:221], off
	global_load_dwordx4 v[176:179], v[220:221], off offset:16
	v_mad_i64_i32 v[222:223], s[24:25], v141, 48, s[6:7]
	global_load_dwordx4 v[192:195], v[222:223], off offset:32
	global_load_dwordx4 v[184:187], v[222:223], off
	global_load_dwordx4 v[188:191], v[222:223], off offset:16
	v_mad_i64_i32 v[224:225], s[24:25], v140, 48, s[6:7]
	global_load_dwordx4 v[238:241], v[224:225], off offset:32
	global_load_dwordx4 v[196:199], v[224:225], off
	global_load_dwordx4 v[234:237], v[224:225], off offset:16
	s_waitcnt vmcnt(0)
	v_add_f32_e32 v162, v162, v166
	v_add_f32_e32 v163, v163, v167
	v_add_f32_e32 v160, v160, v164
	v_add_f32_e32 v161, v161, v165
	v_add_f32_e32 v162, v162, v170
	v_add_f32_e32 v163, v163, v171
	v_add_f32_e32 v160, v160, v168
	v_add_f32_e32 v161, v161, v169
	v_add_f32_e32 v160, v161, v160
	v_add_f32_e32 v162, v162, v163
	v_add_f32_e32 v230, v160, v162
	v_fmamk_f32 v230, v230, 0x3b2aaaab, v204
	v_add_f32_e32 v174, v174, v178
	v_add_f32_e32 v175, v175, v179
	v_add_f32_e32 v172, v172, v176
	v_add_f32_e32 v173, v173, v177
	v_add_f32_e32 v174, v174, v182
	v_add_f32_e32 v175, v175, v183
	v_add_f32_e32 v172, v172, v180
	v_add_f32_e32 v173, v173, v181
	v_add_f32_e32 v172, v173, v172
	v_add_f32_e32 v174, v174, v175
	v_add_f32_e32 v231, v172, v174
	v_fmamk_f32 v231, v231, 0x3b2aaaab, v204
	v_add_f32_e32 v186, v186, v190
	v_add_f32_e32 v187, v187, v191
	v_add_f32_e32 v184, v184, v188
	v_add_f32_e32 v185, v185, v189
	v_add_f32_e32 v186, v186, v194
	v_add_f32_e32 v187, v187, v195
	v_add_f32_e32 v184, v184, v192
	v_add_f32_e32 v185, v185, v193
	v_add_f32_e32 v184, v185, v184
	v_add_f32_e32 v186, v186, v187
	v_add_f32_e32 v232, v184, v186
	v_fmamk_f32 v232, v232, 0x3b2aaaab, v204
	v_add_f32_e32 v198, v198, v236
	v_add_f32_e32 v199, v199, v237
	v_add_f32_e32 v196, v196, v234
	v_add_f32_e32 v197, v197, v235
	v_add_f32_e32 v198, v198, v240
	v_add_f32_e32 v199, v199, v241
	v_add_f32_e32 v196, v196, v238
	v_add_f32_e32 v197, v197, v239
	v_add_f32_e32 v196, v197, v196
	v_add_f32_e32 v198, v198, v199
	v_add_f32_e32 v233, v196, v198
	v_fmamk_f32 v233, v233, 0x3b2aaaab, v204
	v_rsq_f32_e32 v230, v230
	v_rsq_f32_e32 v231, v231
	v_rsq_f32_e32 v232, v232
	v_rsq_f32_e32 v233, v233
	s_nop 0
	v_mul_f32_e32 v230, 0x3dd53b94, v230
	v_mul_f32_e32 v231, 0x3dd53b94, v231
	v_mul_f32_e32 v232, 0x3dd53b94, v232
	v_mul_f32_e32 v233, 0x3dd53b94, v233
	s_and_saveexec_b64 s[22:23], vcc
	s_cbranch_execz .LBB0_597
; __device__ __forceinline__ unsigned cvt_pk_bf16(float lo, float hi) { unsigned r; asm volatile("v_cvt_pk_bf16_f32 %0, %1, %2" : "=v"(r) : "v"(lo), "v"(hi)); return r; }
; __device__ __forceinline__ void store8(bf16_t* p, const float (&v)[8]) {
;     u32x4 w; w.x = cvt_pk_bf16(v[0], v[1]); w.y = cvt_pk_bf16(v[2], v[3]); w.z = cvt_pk_bf16(v[4], v[5]); w.w = cvt_pk_bf16(v[6], v[7]);
;     *(u32x4*)p = w;
; }
;     __device__ __forceinline__ void operator()(const f32x4 (&acc)[2][2][4][2], const Unit& u, int wr, int wc, int fr, int fq) const {
;     ...
;                 for (int m = 0; m < 4; ++m) { const int row = row0 + ai * HALF + m * 16;
;                     const float r = __builtin_amdgcn_rsqf(sum_parts<3>(ssq + (size_t)row * 12) * (1.0f / 384.0f) + 1e-6f) * SC_A; float v[8];
; #pragma unroll
;                     for (int e = 0; e < 4; ++e) { v[e] = acc[ai][bj][m][0][e] * r; v[4 + e] = acc[ai][bj][m][1][e] * r; }
;                     store8(Q + (size_t)row * NUQ + n, v); asm volatile("" ::: "memory"); } } }
	s_movk_i32 s33, 0x900
	s_nop 1
	v_mov_b32_e32 v148, v226
	v_mul_f32_e32 v150, v122, v148
	v_mul_f32_e32 v152, v123, v148
	v_mov_b64_e32 v[122:123], s[8:9]
	v_mul_f32_e32 v151, v126, v148
	v_mul_f32_e32 v153, v127, v148
	v_mul_f32_e32 v154, v124, v148
	v_mul_f32_e32 v155, v128, v148
	v_mul_f32_e32 v128, v125, v148
	v_mad_i64_i32 v[126:127], s[24:25], v147, s33, v[122:123]
	v_lshlrev_b64 v[124:125], 1, v[136:137]
	v_mul_f32_e32 v129, v129, v148
	v_lshl_add_u64 v[148:149], v[126:127], 0, v[124:125]
	v_cvt_pk_bf16_f32 v126, v150, v152
	v_cvt_pk_bf16_f32 v127, v154, v128
	v_cvt_pk_bf16_f32 v128, v151, v153
	v_cvt_pk_bf16_f32 v129, v155, v129
	global_store_dwordx4 v[148:149], v[126:129], off
	s_nop 1
	v_mov_b32_e32 v126, v227
	v_mul_f32_e32 v127, v114, v126
	v_mul_f32_e32 v129, v115, v126
	v_mad_i64_i32 v[114:115], s[24:25], v146, s33, v[122:123]
	v_mul_f32_e32 v128, v118, v126
	v_mul_f32_e32 v148, v119, v126
	v_mul_f32_e32 v116, v116, v126
	v_mul_f32_e32 v117, v117, v126
	v_lshl_add_u64 v[118:119], v[114:115], 0, v[124:125]
	v_mul_f32_e32 v120, v120, v126
	v_mul_f32_e32 v121, v121, v126
	v_cvt_pk_bf16_f32 v114, v127, v129
	v_cvt_pk_bf16_f32 v115, v116, v117
	v_cvt_pk_bf16_f32 v116, v128, v148
	v_cvt_pk_bf16_f32 v117, v120, v121
	global_store_dwordx4 v[118:119], v[114:117], off
	s_nop 1
	v_mov_b32_e32 v114, v228
	v_mul_f32_e32 v115, v106, v114
	v_mul_f32_e32 v117, v107, v114
	v_mad_i64_i32 v[106:107], s[24:25], v145, s33, v[122:123]
	v_mul_f32_e32 v116, v110, v114
	v_mul_f32_e32 v118, v111, v114
	v_mul_f32_e32 v108, v108, v114
	v_mul_f32_e32 v109, v109, v114
	v_lshl_add_u64 v[110:111], v[106:107], 0, v[124:125]
	v_mul_f32_e32 v112, v112, v114
	v_mul_f32_e32 v113, v113, v114
	v_cvt_pk_bf16_f32 v106, v115, v117
	v_cvt_pk_bf16_f32 v107, v108, v109
	v_cvt_pk_bf16_f32 v108, v116, v118
	v_cvt_pk_bf16_f32 v109, v112, v113
	global_store_dwordx4 v[110:111], v[106:109], off
	s_nop 1
	v_mov_b32_e32 v106, v229
	v_mul_f32_e32 v107, v98, v106
	v_mul_f32_e32 v109, v99, v106
	v_mad_i64_i32 v[98:99], s[24:25], v144, s33, v[122:123]
	v_mul_f32_e32 v108, v102, v106
	v_mul_f32_e32 v110, v103, v106
	v_mul_f32_e32 v100, v100, v106
	v_mul_f32_e32 v101, v101, v106
	v_lshl_add_u64 v[102:103], v[98:99], 0, v[124:125]
	v_mul_f32_e32 v104, v104, v106
	v_mul_f32_e32 v105, v105, v106
	v_cvt_pk_bf16_f32 v98, v107, v109
	v_cvt_pk_bf16_f32 v99, v100, v101
	v_cvt_pk_bf16_f32 v100, v108, v110
	v_cvt_pk_bf16_f32 v101, v104, v105
	global_store_dwordx4 v[102:103], v[98:101], off
	s_nop 1
	v_mov_b32_e32 v98, v230
	v_mul_f32_e32 v99, v90, v98
	v_mul_f32_e32 v101, v91, v98
	v_mad_i64_i32 v[90:91], s[24:25], v143, s33, v[122:123]
	v_mul_f32_e32 v100, v94, v98
	v_mul_f32_e32 v102, v95, v98
	v_mul_f32_e32 v92, v92, v98
	v_mul_f32_e32 v93, v93, v98
	v_lshl_add_u64 v[94:95], v[90:91], 0, v[124:125]
	v_mul_f32_e32 v96, v96, v98
	v_mul_f32_e32 v97, v97, v98
	v_cvt_pk_bf16_f32 v90, v99, v101
	v_cvt_pk_bf16_f32 v91, v92, v93
	v_cvt_pk_bf16_f32 v92, v100, v102
	v_cvt_pk_bf16_f32 v93, v96, v97
	global_store_dwordx4 v[94:95], v[90:93], off
	s_nop 1
	v_mov_b32_e32 v90, v231
	v_mul_f32_e32 v91, v82, v90
	v_mul_f32_e32 v93, v83, v90
	v_mad_i64_i32 v[82:83], s[24:25], v142, s33, v[122:123]
	v_mul_f32_e32 v92, v86, v90
	v_mul_f32_e32 v94, v87, v90
	v_mul_f32_e32 v84, v84, v90
	v_mul_f32_e32 v85, v85, v90
	v_lshl_add_u64 v[86:87], v[82:83], 0, v[124:125]
	v_mul_f32_e32 v88, v88, v90
	v_mul_f32_e32 v89, v89, v90
	v_cvt_pk_bf16_f32 v82, v91, v93
	v_cvt_pk_bf16_f32 v83, v84, v85
	v_cvt_pk_bf16_f32 v84, v92, v94
	v_cvt_pk_bf16_f32 v85, v88, v89
	global_store_dwordx4 v[86:87], v[82:85], off
	s_nop 1
	v_mov_b32_e32 v82, v232
	v_mul_f32_e32 v83, v74, v82
	v_mul_f32_e32 v85, v75, v82
	v_mad_i64_i32 v[74:75], s[24:25], v141, s33, v[122:123]
	v_mul_f32_e32 v84, v78, v82
	v_mul_f32_e32 v86, v79, v82
	v_mul_f32_e32 v76, v76, v82
	v_mul_f32_e32 v77, v77, v82
	v_lshl_add_u64 v[78:79], v[74:75], 0, v[124:125]
	v_mul_f32_e32 v80, v80, v82
	v_mul_f32_e32 v81, v81, v82
	v_cvt_pk_bf16_f32 v74, v83, v85
	v_cvt_pk_bf16_f32 v75, v76, v77
	v_cvt_pk_bf16_f32 v76, v84, v86
	v_cvt_pk_bf16_f32 v77, v80, v81
	global_store_dwordx4 v[78:79], v[74:77], off
	s_nop 1
	v_mov_b32_e32 v74, v233
	v_mul_f32_e32 v75, v66, v74
	v_mul_f32_e32 v77, v67, v74
	v_mad_i64_i32 v[66:67], s[24:25], v140, s33, v[122:123]
	v_mul_f32_e32 v76, v70, v74
	v_mul_f32_e32 v78, v71, v74
	v_mul_f32_e32 v68, v68, v74
	v_mul_f32_e32 v69, v69, v74
	v_lshl_add_u64 v[70:71], v[66:67], 0, v[124:125]
	v_mul_f32_e32 v72, v72, v74
	v_mul_f32_e32 v73, v73, v74
	v_cvt_pk_bf16_f32 v66, v75, v77
	v_cvt_pk_bf16_f32 v67, v68, v69
	v_cvt_pk_bf16_f32 v68, v76, v78
	v_cvt_pk_bf16_f32 v69, v72, v73
	global_store_dwordx4 v[70:71], v[66:69], off

; template <int N4> __device__ __forceinline__ float sum_parts(const float* p) {
;     f32x4 a = *(const f32x4*)p;
; #pragma unroll
;     for (int i = 1; i < N4; ++i) a += *(const f32x4*)(p + 4 * i);
;     return (a[0] + a[1]) + (a[2] + a[3]);
; }
;     __device__ __forceinline__ void operator()(const f32x4 (&acc)[2][2][4][2], const Unit& u, int wr, int wc, int fr, int fq) const {
;     ...
;             for (int m = 0; m < 4; ++m) { const int row = row0 + ai * HALF + m * 16;
;                 const float r = __builtin_amdgcn_rsqf(sum_parts<2>(ssq + (size_t)row * 8) * (1.0f / 256.0f) + 1e-6f);
; #pragma unroll
;                 for (int bj = 0; bj < 2; ++bj) { float v[8];
; #pragma unroll
;                     for (int e = 0; e < 4; ++e) { v[e] = acc[ai][bj][m][0][e] * r; v[4 + e] = acc[ai][bj][m][1][e] * r; }
;                     store8(dst[bj] + (size_t)row * 768, v); }
;                 asm volatile("" ::: "memory"); }
.LBB0_613:
	s_getreg_b32 s11, hwreg(HW_REG_HW_ID, 0, 6)
	s_lshl_b32 s11, s11, 2
	s_and_b32 s11, s11, 0xfc
	s_add_i32 s11, s11, 0x20040
	v_mov_b32_e32 v0, s11
	ds_read_b32 v0, v0
	s_lshl_b32 s24, s58, 7
	s_ashr_i32 s25, s24, 31
	s_lshl_b64 s[24:25], s[24:25], 1
	v_readlane_b32 s68, v255, 3
	s_waitcnt lgkmcnt(0)
	v_readfirstlane_b32 s11, v0
	v_mov_b32_e32 v0, 0
	v_readlane_b32 s69, v255, 4
	v_mbcnt_lo_u32_b32 v0, -1, v0
	v_mbcnt_hi_u32_b32 v142, -1, v0
	v_lshl_or_b32 v0, s11, 6, v142
	s_mov_b64 s[70:71], 0x100
	v_readfirstlane_b32 s11, v0
	s_ashr_i32 s13, s11, 2
	s_lshr_b32 s11, s11, 1
	s_and_b32 s11, s11, 0x60
	s_add_u32 s26, s54, s24
	v_lshrrev_b32_e32 v0, 1, v142
	s_addc_u32 s27, s55, s25
	v_and_or_b32 v0, v0, 24, s11
	s_add_u32 s24, s52, s24
	s_addc_u32 s25, s53, s25
	v_lshlrev_b32_e32 v0, 1, v0
	s_andn2_b32 s13, s13, 63
	v_lshl_add_u64 v[140:141], s[24:25], 0, v[0:1]
	v_lshl_add_u64 v[138:139], s[26:27], 0, v[0:1]
	v_and_or_b32 v0, v142, 15, s13
	v_lshl_add_u32 v142, s33, 8, v0
	v_ashrrev_i32_e32 v143, 31, v142
	v_lshlrev_b64 v[146:147], 5, v[142:143]
	v_lshl_add_u64 v[150:151], s[4:5], 0, v[146:147]
	global_load_dwordx4 v[146:149], v[150:151], off
	s_nop 0
	global_load_dwordx4 v[150:153], v[150:151], off offset:16
	s_andn2_b64 vcc, exec, s[2:3]
	s_waitcnt vmcnt(0)
	v_add_f32_e32 v148, v148, v152
	v_add_f32_e32 v149, v149, v153
	v_add_f32_e32 v146, v146, v150
	v_add_f32_e32 v147, v147, v151
	s_nop 0
	v_pk_mov_b32 v[150:151], v[146:147], v[148:149] op_sel:[1,0]
	v_mov_b32_e32 v147, v149
	v_add_f32_e32 v146, v150, v146
	v_add_f32_e32 v147, v151, v147
	s_nop 0
	v_add_f32_e32 v0, v146, v147
	v_fmamk_f32 v0, v0, 0x3b800000, v204
	v_rsq_f32_e32 v0, v0
	s_nop 0
	v_mul_f32_e32 v122, v122, v0
	v_mul_f32_e32 v143, v126, v0
	v_mul_f32_e32 v123, v123, v0
	v_mul_f32_e32 v146, v127, v0
	v_mul_f32_e32 v124, v124, v0
	v_mul_f32_e32 v125, v125, v0
	v_mad_i64_i32 v[126:127], s[24:25], v142, s20, v[140:141]
	v_cvt_pk_bf16_f32 v122, v122, v123
	v_mul_f32_e32 v128, v128, v0
	v_mul_f32_e32 v129, v129, v0
	v_cvt_pk_bf16_f32 v123, v124, v125
	v_cvt_pk_bf16_f32 v124, v143, v146
	v_cvt_pk_bf16_f32 v125, v128, v129
	global_store_dwordx4 v[126:127], v[122:125], off
	v_mul_f32_e32 v114, v114, v0
	v_mul_f32_e32 v115, v115, v0
	v_mul_f32_e32 v122, v118, v0
	v_mul_f32_e32 v116, v116, v0
	v_mul_f32_e32 v123, v119, v0
	v_mul_f32_e32 v117, v117, v0
	v_cvt_pk_bf16_f32 v114, v114, v115
	v_cvt_pk_bf16_f32 v115, v116, v117
	v_cvt_pk_bf16_f32 v116, v122, v123
	v_or_b32_e32 v122, 16, v142
	v_mad_i64_i32 v[118:119], s[24:25], v142, s20, v[138:139]
	v_ashrrev_i32_e32 v123, 31, v122
	v_mul_f32_e32 v120, v120, v0
	v_mul_f32_e32 v0, v121, v0
	v_cvt_pk_bf16_f32 v117, v120, v0
	global_store_dwordx4 v[118:119], v[114:117], off
	s_nop 1
	v_lshlrev_b64 v[114:115], 5, v[122:123]
	v_lshl_add_u64 v[118:119], s[4:5], 0, v[114:115]
	global_load_dwordx4 v[114:117], v[118:119], off
	s_nop 0
	global_load_dwordx4 v[118:121], v[118:119], off offset:16
	s_waitcnt vmcnt(0)
	v_add_f32_e32 v116, v116, v120
	v_add_f32_e32 v117, v117, v121
	v_add_f32_e32 v114, v114, v118
	v_add_f32_e32 v115, v115, v119
	s_nop 0
	v_pk_mov_b32 v[118:119], v[114:115], v[116:117] op_sel:[1,0]
	v_mov_b32_e32 v115, v117
	v_add_f32_e32 v114, v118, v114
	v_add_f32_e32 v115, v119, v115
	s_nop 0
	v_add_f32_e32 v0, v114, v115
	v_fmamk_f32 v0, v0, 0x3b800000, v204
	v_rsq_f32_e32 v0, v0
	s_nop 0
	v_mul_f32_e32 v98, v98, v0
	v_mul_f32_e32 v99, v99, v0
	v_mul_f32_e32 v114, v102, v0
	v_mul_f32_e32 v115, v103, v0
	v_mul_f32_e32 v100, v100, v0
	v_mul_f32_e32 v101, v101, v0
	v_mad_i64_i32 v[102:103], s[24:25], v122, s20, v[140:141]
	v_cvt_pk_bf16_f32 v98, v98, v99
	v_cvt_pk_bf16_f32 v99, v100, v101
	v_mul_f32_e32 v104, v104, v0
	v_mul_f32_e32 v105, v105, v0
	v_cvt_pk_bf16_f32 v100, v114, v115
	v_cvt_pk_bf16_f32 v101, v104, v105
	global_store_dwordx4 v[102:103], v[98:101], off
	v_mul_f32_e32 v104, v108, v0
	v_mad_i64_i32 v[102:103], s[24:25], v122, s20, v[138:139]
	v_mul_f32_e32 v98, v106, v0
	v_mul_f32_e32 v99, v107, v0
	v_mul_f32_e32 v106, v109, v0
	v_cvt_pk_bf16_f32 v98, v98, v99
	v_cvt_pk_bf16_f32 v99, v104, v106
	v_or_b32_e32 v106, 32, v142
	v_mul_f32_e32 v100, v110, v0
	v_mul_f32_e32 v101, v111, v0
	v_ashrrev_i32_e32 v107, 31, v106
	v_mul_f32_e32 v105, v112, v0
	v_mul_f32_e32 v0, v113, v0
	v_cvt_pk_bf16_f32 v100, v100, v101
	v_cvt_pk_bf16_f32 v101, v105, v0
	global_store_dwordx4 v[102:103], v[98:101], off
	s_nop 1
	v_lshlrev_b64 v[98:99], 5, v[106:107]
	v_lshl_add_u64 v[102:103], s[4:5], 0, v[98:99]
	global_load_dwordx4 v[98:101], v[102:103], off
	s_nop 0
	global_load_dwordx4 v[102:105], v[102:103], off offset:16
	s_waitcnt vmcnt(0)
	v_add_f32_e32 v100, v100, v104
	v_add_f32_e32 v101, v101, v105
	v_add_f32_e32 v98, v98, v102
	v_add_f32_e32 v99, v99, v103
	s_nop 0
	v_pk_mov_b32 v[102:103], v[98:99], v[100:101] op_sel:[1,0]
	v_mov_b32_e32 v99, v101
	v_add_f32_e32 v98, v102, v98
	v_add_f32_e32 v99, v103, v99
	s_nop 0
	v_add_f32_e32 v0, v98, v99
	v_fmamk_f32 v0, v0, 0x3b800000, v204
	v_rsq_f32_e32 v0, v0
	s_nop 0
	v_mul_f32_e32 v82, v82, v0
	v_mul_f32_e32 v83, v83, v0
	v_mul_f32_e32 v98, v86, v0
	v_mul_f32_e32 v99, v87, v0
	v_mul_f32_e32 v84, v84, v0
	v_mul_f32_e32 v85, v85, v0
	v_mad_i64_i32 v[86:87], s[24:25], v106, s20, v[140:141]
	v_cvt_pk_bf16_f32 v82, v82, v83
	v_cvt_pk_bf16_f32 v83, v84, v85
	v_mul_f32_e32 v88, v88, v0
	v_mul_f32_e32 v89, v89, v0
	v_cvt_pk_bf16_f32 v84, v98, v99
	v_cvt_pk_bf16_f32 v85, v88, v89
	global_store_dwordx4 v[86:87], v[82:85], off
	v_mul_f32_e32 v88, v92, v0
	v_mad_i64_i32 v[86:87], s[24:25], v106, s20, v[138:139]
	v_mul_f32_e32 v82, v90, v0
	v_mul_f32_e32 v83, v91, v0
	v_mul_f32_e32 v90, v93, v0
	v_cvt_pk_bf16_f32 v82, v82, v83
	v_cvt_pk_bf16_f32 v83, v88, v90
	v_or_b32_e32 v90, 48, v142
	v_mul_f32_e32 v84, v94, v0
	v_mul_f32_e32 v85, v95, v0
	v_ashrrev_i32_e32 v91, 31, v90
	v_mul_f32_e32 v89, v96, v0
	v_mul_f32_e32 v0, v97, v0
	v_cvt_pk_bf16_f32 v84, v84, v85
	v_cvt_pk_bf16_f32 v85, v89, v0
	global_store_dwordx4 v[86:87], v[82:85], off
	s_nop 1
	v_lshlrev_b64 v[82:83], 5, v[90:91]
	v_lshl_add_u64 v[86:87], s[4:5], 0, v[82:83]
	global_load_dwordx4 v[82:85], v[86:87], off
	s_nop 0
	global_load_dwordx4 v[86:89], v[86:87], off offset:16
	s_waitcnt vmcnt(0)
; template <int N4> __device__ __forceinline__ float sum_parts(const float* p) {
;     f32x4 a = *(const f32x4*)p;
; #pragma unroll
;     for (int i = 1; i < N4; ++i) a += *(const f32x4*)(p + 4 * i);
;     return (a[0] + a[1]) + (a[2] + a[3]);
; }
;     __device__ __forceinline__ void operator()(const f32x4 (&acc)[2][2][4][2], const Unit& u, int wr, int wc, int fr, int fq) const {
;     ...
;             for (int m = 0; m < 4; ++m) { const int row = row0 + ai * HALF + m * 16;
;                 const float r = __builtin_amdgcn_rsqf(sum_parts<2>(ssq + (size_t)row * 8) * (1.0f / 256.0f) + 1e-6f);
; #pragma unroll
;                 for (int bj = 0; bj < 2; ++bj) { float v[8];
; #pragma unroll
;                     for (int e = 0; e < 4; ++e) { v[e] = acc[ai][bj][m][0][e] * r; v[4 + e] = acc[ai][bj][m][1][e] * r; }
;                     store8(dst[bj] + (size_t)row * 768, v); }
;                 asm volatile("" ::: "memory"); }
	v_add_f32_e32 v84, v84, v88
	v_add_f32_e32 v85, v85, v89
	v_add_f32_e32 v82, v82, v86
	v_add_f32_e32 v83, v83, v87
	s_nop 0
	v_pk_mov_b32 v[86:87], v[82:83], v[84:85] op_sel:[1,0]
	v_mov_b32_e32 v83, v85
	v_add_f32_e32 v82, v86, v82
	v_add_f32_e32 v83, v87, v83
	s_nop 0
	v_add_f32_e32 v0, v82, v83
	v_fmamk_f32 v0, v0, 0x3b800000, v204
	v_rsq_f32_e32 v0, v0
	s_nop 0
	v_mul_f32_e32 v66, v66, v0
	v_mul_f32_e32 v67, v67, v0
	v_mul_f32_e32 v82, v70, v0
	v_mul_f32_e32 v83, v71, v0
	v_mul_f32_e32 v68, v68, v0
	v_mul_f32_e32 v69, v69, v0
	v_mad_i64_i32 v[70:71], s[24:25], v90, s20, v[140:141]
	v_cvt_pk_bf16_f32 v66, v66, v67
	v_cvt_pk_bf16_f32 v67, v68, v69
	v_mul_f32_e32 v72, v72, v0
	v_mul_f32_e32 v73, v73, v0
	v_cvt_pk_bf16_f32 v68, v82, v83
	v_cvt_pk_bf16_f32 v69, v72, v73
	global_store_dwordx4 v[70:71], v[66:69], off
	v_mul_f32_e32 v72, v76, v0
	v_mad_i64_i32 v[70:71], s[24:25], v90, s20, v[138:139]
	v_mul_f32_e32 v66, v74, v0
	v_mul_f32_e32 v67, v75, v0
	v_mul_f32_e32 v74, v77, v0
	v_cvt_pk_bf16_f32 v66, v66, v67
	v_cvt_pk_bf16_f32 v67, v72, v74
	v_add_u32_e32 v74, 0x80, v142
	v_mul_f32_e32 v68, v78, v0
	v_mul_f32_e32 v69, v79, v0
	v_ashrrev_i32_e32 v75, 31, v74
	v_mul_f32_e32 v73, v80, v0
	v_mul_f32_e32 v0, v81, v0
	v_cvt_pk_bf16_f32 v68, v68, v69
	v_cvt_pk_bf16_f32 v69, v73, v0
	global_store_dwordx4 v[70:71], v[66:69], off
	s_nop 1
	v_lshlrev_b64 v[66:67], 5, v[74:75]
	v_lshl_add_u64 v[70:71], s[4:5], 0, v[66:67]
	global_load_dwordx4 v[66:69], v[70:71], off
	s_nop 0
	global_load_dwordx4 v[70:73], v[70:71], off offset:16
	s_waitcnt vmcnt(0)
	v_add_f32_e32 v68, v68, v72
	v_add_f32_e32 v69, v69, v73
	v_add_f32_e32 v66, v66, v70
	v_add_f32_e32 v67, v67, v71
	s_nop 0
	v_pk_mov_b32 v[70:71], v[66:67], v[68:69] op_sel:[1,0]
	v_mov_b32_e32 v67, v69
	v_add_f32_e32 v66, v70, v66
	v_add_f32_e32 v67, v71, v67
	s_nop 0
	v_add_f32_e32 v0, v66, v67
	v_fmamk_f32 v0, v0, 0x3b800000, v204
	v_rsq_f32_e32 v0, v0
	s_nop 0
	v_mul_f32_e32 v50, v50, v0
	v_mul_f32_e32 v51, v51, v0
	v_mul_f32_e32 v66, v54, v0
	v_mul_f32_e32 v67, v55, v0
	v_mul_f32_e32 v52, v52, v0
	v_mul_f32_e32 v53, v53, v0
	v_mad_i64_i32 v[54:55], s[24:25], v74, s20, v[140:141]
	v_cvt_pk_bf16_f32 v50, v50, v51
	v_cvt_pk_bf16_f32 v51, v52, v53
	v_mul_f32_e32 v56, v56, v0
	v_mul_f32_e32 v57, v57, v0
	v_cvt_pk_bf16_f32 v52, v66, v67
	v_cvt_pk_bf16_f32 v53, v56, v57
	global_store_dwordx4 v[54:55], v[50:53], off
	v_mul_f32_e32 v56, v60, v0
	v_mad_i64_i32 v[54:55], s[24:25], v74, s20, v[138:139]
	v_mul_f32_e32 v50, v58, v0
	v_mul_f32_e32 v51, v59, v0
	v_mul_f32_e32 v58, v61, v0
	v_cvt_pk_bf16_f32 v50, v50, v51
	v_cvt_pk_bf16_f32 v51, v56, v58
	v_add_u32_e32 v58, 0x90, v142
	v_mul_f32_e32 v52, v62, v0
	v_mul_f32_e32 v53, v63, v0
	v_ashrrev_i32_e32 v59, 31, v58
	v_mul_f32_e32 v57, v64, v0
	v_mul_f32_e32 v0, v65, v0
	v_cvt_pk_bf16_f32 v52, v52, v53
	v_cvt_pk_bf16_f32 v53, v57, v0
	global_store_dwordx4 v[54:55], v[50:53], off
	s_nop 1
	v_lshlrev_b64 v[50:51], 5, v[58:59]
	v_lshl_add_u64 v[54:55], s[4:5], 0, v[50:51]
	global_load_dwordx4 v[50:53], v[54:55], off
	s_nop 0
	global_load_dwordx4 v[54:57], v[54:55], off offset:16
	s_waitcnt vmcnt(0)
; #define PG8_BAR __builtin_amdgcn_s_barrier()
;     __device__ __forceinline__ void operator()(const f32x4 (&acc)[2][2][4][2], const Unit& u, int wr, int wc, int fr, int fq) const {
;     ...
;             for (int m = 0; m < 4; ++m) { const int row = row0 + ai * HALF + m * 16;
;                 const float r = __builtin_amdgcn_rsqf(sum_parts<2>(ssq + (size_t)row * 8) * (1.0f / 256.0f) + 1e-6f);
; #pragma unroll
;                 for (int bj = 0; bj < 2; ++bj) { float v[8];
; #pragma unroll
;                     for (int e = 0; e < 4; ++e) { v[e] = acc[ai][bj][m][0][e] * r; v[4 + e] = acc[ai][bj][m][1][e] * r; }
;                     store8(dst[bj] + (size_t)row * 768, v); }
;                 asm volatile("" ::: "memory"); }
; template <class Epi, class Sched, bool ALIGN_EPI = false, bool SP2 = false>
; __device__ __forceinline__ void gemm_phase(PG8_LAS unsigned char* lds, const Gemm g, const Sched& S, const Epi& E) {
;     ...
;         if (!has_next) break;
; #pragma unroll
;         for (int a = 0; a < 2; ++a)
; #pragma unroll
;             for (int b = 0; b < 2; ++b)
; #pragma unroll
;                 for (int m = 0; m < 4; ++m)
; #pragma unroll
;                     for (int n = 0; n < 2; ++n) acc[a][b][m][n] = (f32x4){0.f, 0.f, 0.f, 0.f};
;         cur = nxt; cA = nA; cB = nB; ++ui;
;         if constexpr (ALIGN_EPI) { if (wr == 1) PG8_BAR; }
	v_add_f32_e32 v52, v52, v56
	v_add_f32_e32 v53, v53, v57
	v_add_f32_e32 v50, v50, v54
	v_add_f32_e32 v51, v51, v55
	s_nop 0
	v_pk_mov_b32 v[54:55], v[50:51], v[52:53] op_sel:[1,0]
	v_mov_b32_e32 v51, v53
	v_add_f32_e32 v50, v54, v50
	v_add_f32_e32 v51, v55, v51
	s_nop 0
	v_add_f32_e32 v0, v50, v51
	v_fmamk_f32 v0, v0, 0x3b800000, v204
	v_rsq_f32_e32 v0, v0
	s_nop 0
	v_mul_f32_e32 v34, v34, v0
	v_mul_f32_e32 v35, v35, v0
	v_mul_f32_e32 v50, v38, v0
	v_mul_f32_e32 v51, v39, v0
	v_mul_f32_e32 v36, v36, v0
	v_mul_f32_e32 v37, v37, v0
	v_mad_i64_i32 v[38:39], s[24:25], v58, s20, v[140:141]
	v_cvt_pk_bf16_f32 v34, v34, v35
	v_cvt_pk_bf16_f32 v35, v36, v37
	v_mul_f32_e32 v40, v40, v0
	v_mul_f32_e32 v41, v41, v0
	v_cvt_pk_bf16_f32 v36, v50, v51
	v_cvt_pk_bf16_f32 v37, v40, v41
	global_store_dwordx4 v[38:39], v[34:37], off
	v_mul_f32_e32 v40, v44, v0
	v_mad_i64_i32 v[38:39], s[24:25], v58, s20, v[138:139]
	v_mul_f32_e32 v34, v42, v0
	v_mul_f32_e32 v35, v43, v0
	v_mul_f32_e32 v42, v45, v0
	v_cvt_pk_bf16_f32 v34, v34, v35
	v_cvt_pk_bf16_f32 v35, v40, v42
	v_add_u32_e32 v42, 0xa0, v142
	v_mul_f32_e32 v36, v46, v0
	v_mul_f32_e32 v37, v47, v0
	v_ashrrev_i32_e32 v43, 31, v42
	v_mul_f32_e32 v41, v48, v0
	v_mul_f32_e32 v0, v49, v0
	v_cvt_pk_bf16_f32 v36, v36, v37
	v_cvt_pk_bf16_f32 v37, v41, v0
	global_store_dwordx4 v[38:39], v[34:37], off
	s_nop 1
	v_lshlrev_b64 v[34:35], 5, v[42:43]
	v_lshl_add_u64 v[38:39], s[4:5], 0, v[34:35]
	global_load_dwordx4 v[34:37], v[38:39], off
	s_nop 0
	global_load_dwordx4 v[38:41], v[38:39], off offset:16
	s_waitcnt vmcnt(0)
	v_add_f32_e32 v36, v36, v40
	v_add_f32_e32 v37, v37, v41
	v_add_f32_e32 v34, v34, v38
	v_add_f32_e32 v35, v35, v39
	s_nop 0
	v_pk_mov_b32 v[38:39], v[34:35], v[36:37] op_sel:[1,0]
	v_mov_b32_e32 v35, v37
	v_add_f32_e32 v34, v38, v34
	v_add_f32_e32 v35, v39, v35
	s_nop 0
	v_add_f32_e32 v0, v34, v35
	v_fmamk_f32 v0, v0, 0x3b800000, v204
	v_rsq_f32_e32 v0, v0
	s_nop 0
	v_mul_f32_e32 v18, v18, v0
	v_mul_f32_e32 v34, v22, v0
	v_mul_f32_e32 v19, v19, v0
	v_mul_f32_e32 v35, v23, v0
	v_mul_f32_e32 v20, v20, v0
	v_mul_f32_e32 v21, v21, v0
	v_mad_i64_i32 v[22:23], s[24:25], v42, s20, v[140:141]
	v_cvt_pk_bf16_f32 v18, v18, v19
	v_mul_f32_e32 v24, v24, v0
	v_mul_f32_e32 v25, v25, v0
	v_cvt_pk_bf16_f32 v19, v20, v21
	v_cvt_pk_bf16_f32 v20, v34, v35
	v_cvt_pk_bf16_f32 v21, v24, v25
	global_store_dwordx4 v[22:23], v[18:21], off
	v_mad_i64_i32 v[22:23], s[24:25], v42, s20, v[138:139]
	s_nop 0
	v_mul_f32_e32 v18, v26, v0
	v_mul_f32_e32 v20, v30, v0
	v_mul_f32_e32 v19, v27, v0
	v_mul_f32_e32 v21, v31, v0
	v_cvt_pk_bf16_f32 v18, v18, v19
	v_mul_f32_e32 v24, v28, v0
	v_mul_f32_e32 v25, v32, v0
	v_mul_f32_e32 v26, v29, v0
	v_mul_f32_e32 v0, v33, v0
	v_cvt_pk_bf16_f32 v19, v24, v26
	v_cvt_pk_bf16_f32 v20, v20, v21
	v_cvt_pk_bf16_f32 v21, v25, v0
	global_store_dwordx4 v[22:23], v[18:21], off
	s_nop 1
	v_add_u32_e32 v18, 0xb0, v142
	v_ashrrev_i32_e32 v19, 31, v18
	v_lshlrev_b64 v[20:21], 5, v[18:19]
	v_lshl_add_u64 v[24:25], s[4:5], 0, v[20:21]
	global_load_dwordx4 v[20:23], v[24:25], off
	s_nop 0
	global_load_dwordx4 v[24:27], v[24:25], off offset:16
	s_waitcnt vmcnt(0)
	v_add_f32_e32 v22, v22, v26
	v_add_f32_e32 v23, v23, v27
	v_add_f32_e32 v20, v20, v24
	v_add_f32_e32 v21, v21, v25
	s_nop 0
	v_pk_mov_b32 v[24:25], v[20:21], v[22:23] op_sel:[1,0]
	v_mov_b32_e32 v21, v23
	v_add_f32_e32 v20, v24, v20
	v_add_f32_e32 v21, v25, v21
	s_nop 0
	v_add_f32_e32 v0, v20, v21
	v_fmamk_f32 v0, v0, 0x3b800000, v204
	v_rsq_f32_e32 v0, v0
	s_nop 0
	v_mul_f32_e32 v10, v10, v0
	v_mul_f32_e32 v11, v11, v0
	v_mul_f32_e32 v19, v14, v0
	v_mul_f32_e32 v20, v15, v0
	v_mul_f32_e32 v12, v12, v0
	v_mul_f32_e32 v13, v13, v0
	v_mad_i64_i32 v[14:15], s[24:25], v18, s20, v[140:141]
	v_cvt_pk_bf16_f32 v10, v10, v11
	v_cvt_pk_bf16_f32 v11, v12, v13
	v_mul_f32_e32 v16, v16, v0
	v_mul_f32_e32 v17, v17, v0
	v_cvt_pk_bf16_f32 v12, v19, v20
	v_cvt_pk_bf16_f32 v13, v16, v17
	global_store_dwordx4 v[14:15], v[10:13], off
	v_mul_f32_e32 v2, v2, v0
	v_mul_f32_e32 v3, v3, v0
	v_mul_f32_e32 v10, v6, v0
	v_mul_f32_e32 v11, v7, v0
	v_mul_f32_e32 v4, v4, v0
	v_mul_f32_e32 v5, v5, v0
	v_mad_i64_i32 v[6:7], s[24:25], v18, s20, v[138:139]
	v_mul_f32_e32 v8, v8, v0
	v_mul_f32_e32 v0, v9, v0
	v_cvt_pk_bf16_f32 v2, v2, v3
	v_cvt_pk_bf16_f32 v3, v4, v5
	v_cvt_pk_bf16_f32 v4, v10, v11
	v_cvt_pk_bf16_f32 v5, v8, v0
	global_store_dwordx4 v[6:7], v[2:5], off
	s_mov_b64 s[24:25], -1
	s_cbranch_vccnz .LBB0_608
	s_andn2_b64 vcc, exec, s[0:1]
	s_cbranch_vccnz .LBB0_607
	s_barrier
	s_branch .LBB0_607

;     ...
;             float s1 = 0.f, s2 = 0.f;
;             for (int i = 0; i < 64; ++i) { s1 += ap->lam_q1[L * 64 + i] * ap->lam_k1[L * 64 + i]; s2 += ap->lam_q2[L * 64 + i] * ap->lam_k2[L * 64 + i]; }
;             const float lam_init = 0.8f - 0.6f * expf(-0.3f * (float)L); const float lam = expf(s1) - expf(s2) + lam_init;
.LBB0_618:
	s_add_u32 s10, s2, s0
	s_addc_u32 s11, s3, s1
	global_load_dwordx4 v[4:7], v1, s[10:11] offset:16
	global_load_dwordx4 v[8:11], v1, s[10:11]
	s_add_u32 s10, s4, s0
	s_addc_u32 s11, s5, s1
	global_load_dwordx4 v[12:15], v1, s[10:11] offset:16
	global_load_dwordx4 v[16:19], v1, s[10:11]
	s_add_u32 s10, s6, s0
	s_addc_u32 s11, s7, s1
	global_load_dwordx4 v[20:23], v1, s[10:11] offset:16
	global_load_dwordx4 v[24:27], v1, s[10:11]
	s_add_u32 s10, s8, s0
	s_addc_u32 s11, s9, s1
	global_load_dwordx4 v[28:31], v1, s[10:11] offset:16
	global_load_dwordx4 v[32:35], v1, s[10:11]
	s_add_u32 s0, s0, 32
	s_addc_u32 s1, s1, 0
	s_cmpk_eq_i32 s0, 0x100
	s_waitcnt vmcnt(0)
	v_mov_b32_e32 v36, v8
	v_mov_b32_e32 v8, v10
	v_mov_b32_e32 v10, v12
	v_mov_b32_e32 v38, v16
	v_mov_b32_e32 v16, v18
	v_mov_b32_e32 v37, v24
	v_mov_b32_e32 v24, v9
	v_mov_b32_e32 v9, v26
	v_mov_b32_e32 v39, v32
	v_fma_f32 v2, v36, v38, v2
	v_fma_f32 v3, v37, v39, v3
	v_mov_b32_e32 v32, v17
	v_fma_f32 v2, v24, v32, v2
	v_fma_f32 v3, v25, v33, v3
	v_mov_b32_e32 v17, v34
	v_fma_f32 v2, v8, v16, v2
	v_fma_f32 v3, v9, v17, v3
	v_mov_b32_e32 v26, v11
	v_mov_b32_e32 v34, v19
	v_fma_f32 v2, v26, v34, v2
	v_fma_f32 v3, v27, v35, v3
	v_mov_b32_e32 v8, v4
	v_mov_b32_e32 v9, v20
	v_mov_b32_e32 v11, v28
	v_fma_f32 v2, v8, v10, v2
	v_fma_f32 v3, v9, v11, v3
	v_mov_b32_e32 v20, v5
	v_mov_b32_e32 v28, v13
	v_fma_f32 v2, v20, v28, v2
	v_fma_f32 v3, v21, v29, v3
	v_mov_b32_e32 v4, v6
	v_mov_b32_e32 v5, v22
	v_mov_b32_e32 v8, v14
	v_mov_b32_e32 v9, v30
	v_fma_f32 v2, v4, v8, v2
	v_fma_f32 v3, v5, v9, v3
	v_mov_b32_e32 v22, v7
	v_mov_b32_e32 v30, v15
	v_fma_f32 v2, v22, v30, v2
	v_fma_f32 v3, v23, v31, v3
	s_cbranch_scc0 .LBB0_618
	v_cvt_f32_u32_e32 v0, s46
	s_mov_b32 s0, 0xc2ce8ed0
	s_mov_b32 s1, 0x42b17218
	s_lshl_b32 s68, s46, 5
	v_mul_f32_e32 v0, 0xbe99999a, v0
	v_cmp_ngt_f32_e64 s[6:7], s0, v2
	v_cmp_nlt_f32_e64 s[8:9], s1, v2
	v_cmp_ngt_f32_e64 s[10:11], s0, v0
	v_cmp_nlt_f32_e64 s[12:13], s1, v0
	v_cmp_ngt_f32_e64 s[2:3], s0, v3
	v_cmp_nlt_f32_e64 s[4:5], s1, v3
	s_lshl_b64 s[50:51], s[68:69], 2
	v_readlane_b32 s0, v254, 15
	s_add_u32 s58, s14, s50
	v_readlane_b32 s1, v254, 16
	s_addc_u32 s59, s15, s51
	s_and_b64 vcc, exec, s[0:1]
	s_barrier
	s_cbranch_vccz .LBB0_644
	v_mul_f32_e32 v4, 0x3fb8aa3b, v0
	s_mov_b32 s0, 0x3fb8aa3b
	v_fma_f32 v5, v0, s0, -v4
	v_fmac_f32_e32 v5, 0x32a5705f, v0
	v_rndne_f32_e32 v0, v4
	v_sub_f32_e32 v4, v4, v0
	v_add_f32_e32 v4, v4, v5
	v_exp_f32_e32 v4, v4
	v_cvt_i32_f32_e32 v0, v0
	v_mov_b32_e32 v7, 0x7f800000
	v_ldexp_f32 v0, v4, v0
	v_mul_f32_e32 v4, 0x3fb8aa3b, v2
	v_rndne_f32_e32 v5, v4
	v_sub_f32_e32 v6, v4, v5
	v_fma_f32 v4, v2, s0, -v4
	v_fmac_f32_e32 v4, 0x32a5705f, v2
	v_add_f32_e32 v2, v6, v4
	v_exp_f32_e32 v2, v2
	v_cvt_i32_f32_e32 v4, v5
	v_cndmask_b32_e64 v0, 0, v0, s[10:11]
	s_add_u32 s10, s14, 0x24d10000
	s_addc_u32 s11, s15, 0
	v_ldexp_f32 v2, v2, v4
	v_mul_f32_e32 v4, 0x3fb8aa3b, v3
	v_rndne_f32_e32 v5, v4
	v_sub_f32_e32 v6, v4, v5
	v_fma_f32 v4, v3, s0, -v4
	v_fmac_f32_e32 v4, 0x32a5705f, v3
	v_add_f32_e32 v3, v6, v4
	v_cndmask_b32_e64 v0, v7, v0, s[12:13]
	v_exp_f32_e32 v3, v3
	v_cvt_i32_f32_e32 v4, v5
	s_add_u32 s12, s14, 0x24d10500
	s_addc_u32 s13, s15, 0
	s_add_u32 s18, s14, 0x22510500
	s_load_dwordx2 s[0:1], s[16:17], 0x70
	s_addc_u32 s19, s15, 0
	v_ldexp_f32 v3, v3, v4
	s_add_u32 s21, s14, 0x1bd10b00
	v_cndmask_b32_e64 v2, 0, v2, s[6:7]
	v_cndmask_b32_e64 v3, 0, v3, s[2:3]
	s_addc_u32 s22, s15, 0
	s_lshl_b32 s68, s46, 7
	v_cndmask_b32_e64 v2, v7, v2, s[8:9]
	v_cndmask_b32_e64 v3, v7, v3, s[4:5]
	v_mov_b32_e32 v4, 0x3f4ccccd
	s_lshl_b64 s[2:3], s[68:69], 2
	v_fmamk_f32 v0, v0, 0xbf19999a, v4
	v_sub_f32_e32 v2, v2, v3
	s_waitcnt lgkmcnt(0)
	s_add_u32 s0, s0, s2
	v_add_f32_e32 v120, v0, v2
	v_sub_f32_e32 v121, 1.0, v0
	s_addc_u32 s1, s1, s3
	s_mov_b32 s2, s93
	s_branch .LBB0_623
